# GEMM K-loops: lgkmcnt(0) before each phase barrier dropped and the post-barrier wait replaced by a counted ladder (7/5/3/1/0) so MFMAs start as their fragments land
# baseline (speedup 1.0000x reference)
.Lgemm0_peel:
	s_add_u32 s10, s90, 0xfffc0080
	s_addc_u32 s33, s91, -1
	s_add_i32 s73, 0, 0x10000
	s_cmp_eq_u32 s72, 12
	s_cselect_b32 vcc_hi, s9, s33
	s_cselect_b32 vcc_lo, s34, s10
	v_add_u32_e32 v147, s73, v145
	s_cselect_b32 s47, s35, s71
	s_cselect_b32 s46, s41, s65
	s_add_i32 s10, 0, 0x14000
	ds_read_b128 v[140:143], v147
	ds_read_b128 v[148:151], v147 offset:1024
	ds_read_b128 v[152:155], v147 offset:2048
	ds_read_b128 v[156:159], v147 offset:3072
	v_add_u32_e32 v147, s10, v145
	ds_read_b128 v[160:163], v147
	ds_read_b128 v[164:167], v147 offset:1024
	ds_read_b128 v[168:171], v147 offset:2048
	ds_read_b128 v[172:175], v147 offset:3072
	v_lshl_add_u64 v[240:241], s[90:91], 0, v[136:137]
	s_add_i32 m0, s11, 0xc000
	ds_read_b128 v[176:179], v146
	ds_read_b128 v[180:183], v146 offset:1024
	ds_read_b128 v[184:187], v146 offset:2048
	ds_read_b128 v[208:211], v146 offset:3072
	ds_read_b128 v[212:215], v146 offset:4096
	ds_read_b128 v[228:231], v146 offset:5120
	ds_read_b128 v[232:235], v146 offset:6144
	ds_read_b128 v[236:239], v146 offset:7168
	global_load_lds_dwordx4 v[240:241], off
	v_lshl_add_u64 v[240:241], s[90:91], 0, v[138:139]
	s_add_i32 m0, s11, 0xe000
	s_nop 0
	global_load_lds_dwordx4 v[240:241], off
	s_waitcnt vmcnt(8)
	s_barrier
	s_setprio 1
	s_waitcnt lgkmcnt(7)
	v_mfma_f32_16x16x32_bf16 v[124:127], v[140:143], v[176:179], 0
	v_mfma_f32_16x16x32_bf16 v[120:123], v[152:155], v[176:179], 0
	s_waitcnt lgkmcnt(5)
	v_mfma_f32_16x16x32_bf16 v[108:111], v[140:143], v[184:187], 0
	v_mfma_f32_16x16x32_bf16 v[104:107], v[152:155], v[184:187], 0
	s_waitcnt lgkmcnt(3)
	v_mfma_f32_16x16x32_bf16 v[92:95], v[140:143], v[212:215], 0
	v_mfma_f32_16x16x32_bf16 v[88:91], v[152:155], v[212:215], 0
	s_waitcnt lgkmcnt(1)
	v_mfma_f32_16x16x32_bf16 v[76:79], v[140:143], v[232:235], 0
	v_mfma_f32_16x16x32_bf16 v[72:75], v[152:155], v[232:235], 0
	v_mfma_f32_16x16x32_bf16 v[124:127], v[148:151], v[180:183], v[124:127]
	v_mfma_f32_16x16x32_bf16 v[120:123], v[156:159], v[180:183], v[120:123]
	v_mfma_f32_16x16x32_bf16 v[108:111], v[148:151], v[208:211], v[108:111]
	v_mfma_f32_16x16x32_bf16 v[104:107], v[156:159], v[208:211], v[104:107]
	v_mfma_f32_16x16x32_bf16 v[92:95], v[148:151], v[228:231], v[92:95]
	v_mfma_f32_16x16x32_bf16 v[88:91], v[156:159], v[228:231], v[88:91]
	s_waitcnt lgkmcnt(0)
	v_mfma_f32_16x16x32_bf16 v[76:79], v[148:151], v[236:239], v[76:79]
	v_mfma_f32_16x16x32_bf16 v[72:75], v[156:159], v[236:239], v[72:75]
	s_setprio 0
	s_setprio 1
	v_mfma_f32_16x16x32_bf16 v[116:119], v[160:163], v[176:179], 0
	v_mfma_f32_16x16x32_bf16 v[112:115], v[168:171], v[176:179], 0
	v_mfma_f32_16x16x32_bf16 v[100:103], v[160:163], v[184:187], 0
	v_mfma_f32_16x16x32_bf16 v[96:99], v[168:171], v[184:187], 0
	v_mfma_f32_16x16x32_bf16 v[84:87], v[160:163], v[212:215], 0
	v_mfma_f32_16x16x32_bf16 v[80:83], v[168:171], v[212:215], 0
	v_mfma_f32_16x16x32_bf16 v[68:71], v[160:163], v[232:235], 0
	v_mfma_f32_16x16x32_bf16 v[64:67], v[168:171], v[232:235], 0
	v_mfma_f32_16x16x32_bf16 v[116:119], v[164:167], v[180:183], v[116:119]
	v_mfma_f32_16x16x32_bf16 v[112:115], v[172:175], v[180:183], v[112:115]
	v_mfma_f32_16x16x32_bf16 v[100:103], v[164:167], v[208:211], v[100:103]
	v_mfma_f32_16x16x32_bf16 v[96:99], v[172:175], v[208:211], v[96:99]
	v_mfma_f32_16x16x32_bf16 v[84:87], v[164:167], v[228:231], v[84:87]
	v_mfma_f32_16x16x32_bf16 v[80:83], v[172:175], v[228:231], v[80:83]
	v_mfma_f32_16x16x32_bf16 v[68:71], v[164:167], v[236:239], v[68:71]
	v_mfma_f32_16x16x32_bf16 v[64:67], v[172:175], v[236:239], v[64:67]
	s_setprio 0
	s_barrier
	s_add_i32 s33, s73, s3
	v_lshl_add_u64 v[240:241], s[46:47], 0, v[132:133]
	s_mov_b32 m0, s33
	ds_read_b128 v[176:179], v146 offset:16384
	ds_read_b128 v[180:183], v146 offset:17408
	ds_read_b128 v[184:187], v146 offset:18432
	ds_read_b128 v[208:211], v146 offset:19456
	ds_read_b128 v[212:215], v146 offset:20480
	ds_read_b128 v[228:231], v146 offset:21504
	ds_read_b128 v[232:235], v146 offset:22528
	ds_read_b128 v[236:239], v146 offset:23552
	global_load_lds_dwordx4 v[240:241], off
	s_add_i32 m0, s33, 0x2000
	s_add_u32 s78, s46, 0x40000
	v_lshl_add_u64 v[242:243], s[46:47], 0, v[128:129]
	s_addc_u32 s79, s47, 0
	s_add_i32 s10, s10, s3
	global_load_lds_dwordx4 v[242:243], off
	v_lshl_add_u64 v[244:245], s[78:79], 0, v[132:133]
	s_mov_b32 m0, s10
	v_lshl_add_u64 v[246:247], vcc, 0, v[130:131]
	global_load_lds_dwordx4 v[244:245], off
	v_lshl_add_u64 v[244:245], s[78:79], 0, v[128:129]
	s_add_i32 m0, s10, 0x2000
	s_nop 0
	global_load_lds_dwordx4 v[244:245], off
	v_lshl_add_u64 v[244:245], vcc, 0, v[134:135]
	s_mov_b32 m0, s11
	s_nop 0
	global_load_lds_dwordx4 v[244:245], off
	s_mov_b32 m0, s12
	s_nop 0
	global_load_lds_dwordx4 v[246:247], off
	s_waitcnt vmcnt(8)
	s_barrier
	s_setprio 1
	s_waitcnt lgkmcnt(7)
	v_mfma_f32_16x16x32_bf16 v[60:63], v[140:143], v[176:179], 0
	v_mfma_f32_16x16x32_bf16 v[56:59], v[152:155], v[176:179], 0
	s_waitcnt lgkmcnt(5)
	v_mfma_f32_16x16x32_bf16 v[44:47], v[140:143], v[184:187], 0
	v_mfma_f32_16x16x32_bf16 v[40:43], v[152:155], v[184:187], 0
	s_waitcnt lgkmcnt(3)
	v_mfma_f32_16x16x32_bf16 v[28:31], v[140:143], v[212:215], 0
	v_mfma_f32_16x16x32_bf16 v[24:27], v[152:155], v[212:215], 0
	s_waitcnt lgkmcnt(1)
	v_mfma_f32_16x16x32_bf16 v[12:15], v[140:143], v[232:235], 0
	v_mfma_f32_16x16x32_bf16 v[8:11], v[152:155], v[232:235], 0
	v_mfma_f32_16x16x32_bf16 v[60:63], v[148:151], v[180:183], v[60:63]
	v_mfma_f32_16x16x32_bf16 v[56:59], v[156:159], v[180:183], v[56:59]
	v_mfma_f32_16x16x32_bf16 v[44:47], v[148:151], v[208:211], v[44:47]
	v_mfma_f32_16x16x32_bf16 v[40:43], v[156:159], v[208:211], v[40:43]
	v_mfma_f32_16x16x32_bf16 v[28:31], v[148:151], v[228:231], v[28:31]
	v_mfma_f32_16x16x32_bf16 v[24:27], v[156:159], v[228:231], v[24:27]
	s_waitcnt lgkmcnt(0)
	v_mfma_f32_16x16x32_bf16 v[12:15], v[148:151], v[236:239], v[12:15]
	v_mfma_f32_16x16x32_bf16 v[8:11], v[156:159], v[236:239], v[8:11]
	s_setprio 0
	s_setprio 1
	v_mfma_f32_16x16x32_bf16 v[52:55], v[160:163], v[176:179], 0
	v_mfma_f32_16x16x32_bf16 v[48:51], v[168:171], v[176:179], 0
	v_mfma_f32_16x16x32_bf16 v[36:39], v[160:163], v[184:187], 0
	v_mfma_f32_16x16x32_bf16 v[32:35], v[168:171], v[184:187], 0
	v_mfma_f32_16x16x32_bf16 v[20:23], v[160:163], v[212:215], 0
	v_mfma_f32_16x16x32_bf16 v[16:19], v[168:171], v[212:215], 0
	v_mfma_f32_16x16x32_bf16 v[4:7], v[160:163], v[232:235], 0
	v_mfma_f32_16x16x32_bf16 v[0:3], v[168:171], v[232:235], 0
	v_mfma_f32_16x16x32_bf16 v[52:55], v[164:167], v[180:183], v[52:55]
	v_mfma_f32_16x16x32_bf16 v[48:51], v[172:175], v[180:183], v[48:51]
	v_mfma_f32_16x16x32_bf16 v[36:39], v[164:167], v[208:211], v[36:39]
	v_mfma_f32_16x16x32_bf16 v[32:35], v[172:175], v[208:211], v[32:35]
	v_mfma_f32_16x16x32_bf16 v[20:23], v[164:167], v[228:231], v[20:23]
	v_mfma_f32_16x16x32_bf16 v[16:19], v[172:175], v[228:231], v[16:19]
	v_mfma_f32_16x16x32_bf16 v[4:7], v[164:167], v[236:239], v[4:7]
	v_mfma_f32_16x16x32_bf16 v[0:3], v[172:175], v[236:239], v[0:3]
	s_setprio 0
	s_barrier
	s_add_i32 s10, 0, 0x18000
	v_add_u32_e32 v147, s10, v145
	s_add_i32 s33, 0, 0x1c000
	ds_read_b128 v[140:143], v147
	ds_read_b128 v[148:151], v147 offset:1024
	ds_read_b128 v[152:155], v147 offset:2048
	ds_read_b128 v[156:159], v147 offset:3072
	v_add_u32_e32 v147, s33, v145
	ds_read_b128 v[160:163], v147
	ds_read_b128 v[164:167], v147 offset:1024
	ds_read_b128 v[168:171], v147 offset:2048
	ds_read_b128 v[172:175], v147 offset:3072
	s_add_u32 s78, vcc_lo, 0x40000
	s_addc_u32 s79, vcc_hi, 0
	s_mov_b32 m0, s16
	v_lshl_add_u64 v[248:249], s[78:79], 0, v[134:135]
	ds_read_b128 v[176:179], v146 offset:32768
	ds_read_b128 v[180:183], v146 offset:33792
	ds_read_b128 v[184:187], v146 offset:34816
	ds_read_b128 v[208:211], v146 offset:35840
	ds_read_b128 v[212:215], v146 offset:36864
	ds_read_b128 v[228:231], v146 offset:37888
	ds_read_b128 v[232:235], v146 offset:38912
	ds_read_b128 v[236:239], v146 offset:39936
	global_load_lds_dwordx4 v[248:249], off
	v_lshl_add_u64 v[248:249], s[78:79], 0, v[130:131]
	s_mov_b32 m0, s17
	s_nop 0
	global_load_lds_dwordx4 v[248:249], off
	s_waitcnt vmcnt(8)
	s_barrier
	s_setprio 1
	s_waitcnt lgkmcnt(7)
	v_mfma_f32_16x16x32_bf16 v[124:127], v[140:143], v[176:179], v[124:127]
	v_mfma_f32_16x16x32_bf16 v[120:123], v[152:155], v[176:179], v[120:123]
	s_waitcnt lgkmcnt(5)
	v_mfma_f32_16x16x32_bf16 v[108:111], v[140:143], v[184:187], v[108:111]
	v_mfma_f32_16x16x32_bf16 v[104:107], v[152:155], v[184:187], v[104:107]
	s_waitcnt lgkmcnt(3)
	v_mfma_f32_16x16x32_bf16 v[92:95], v[140:143], v[212:215], v[92:95]
	v_mfma_f32_16x16x32_bf16 v[88:91], v[152:155], v[212:215], v[88:91]
	s_waitcnt lgkmcnt(1)
	v_mfma_f32_16x16x32_bf16 v[76:79], v[140:143], v[232:235], v[76:79]
	v_mfma_f32_16x16x32_bf16 v[72:75], v[152:155], v[232:235], v[72:75]
	v_mfma_f32_16x16x32_bf16 v[124:127], v[148:151], v[180:183], v[124:127]
	v_mfma_f32_16x16x32_bf16 v[120:123], v[156:159], v[180:183], v[120:123]
	v_mfma_f32_16x16x32_bf16 v[108:111], v[148:151], v[208:211], v[108:111]
	v_mfma_f32_16x16x32_bf16 v[104:107], v[156:159], v[208:211], v[104:107]
	v_mfma_f32_16x16x32_bf16 v[92:95], v[148:151], v[228:231], v[92:95]
	v_mfma_f32_16x16x32_bf16 v[88:91], v[156:159], v[228:231], v[88:91]
	s_waitcnt lgkmcnt(0)
	v_mfma_f32_16x16x32_bf16 v[76:79], v[148:151], v[236:239], v[76:79]
	v_mfma_f32_16x16x32_bf16 v[72:75], v[156:159], v[236:239], v[72:75]
	s_setprio 0
	s_setprio 1
	v_mfma_f32_16x16x32_bf16 v[116:119], v[160:163], v[176:179], v[116:119]
	v_mfma_f32_16x16x32_bf16 v[112:115], v[168:171], v[176:179], v[112:115]
	v_mfma_f32_16x16x32_bf16 v[100:103], v[160:163], v[184:187], v[100:103]
	v_mfma_f32_16x16x32_bf16 v[96:99], v[168:171], v[184:187], v[96:99]
	v_mfma_f32_16x16x32_bf16 v[84:87], v[160:163], v[212:215], v[84:87]
	v_mfma_f32_16x16x32_bf16 v[80:83], v[168:171], v[212:215], v[80:83]
	v_mfma_f32_16x16x32_bf16 v[68:71], v[160:163], v[232:235], v[68:71]
	v_mfma_f32_16x16x32_bf16 v[64:67], v[168:171], v[232:235], v[64:67]
	v_mfma_f32_16x16x32_bf16 v[116:119], v[164:167], v[180:183], v[116:119]
	v_mfma_f32_16x16x32_bf16 v[112:115], v[172:175], v[180:183], v[112:115]
	v_mfma_f32_16x16x32_bf16 v[100:103], v[164:167], v[208:211], v[100:103]
	v_mfma_f32_16x16x32_bf16 v[96:99], v[172:175], v[208:211], v[96:99]
	v_mfma_f32_16x16x32_bf16 v[84:87], v[164:167], v[228:231], v[84:87]
	v_mfma_f32_16x16x32_bf16 v[80:83], v[172:175], v[228:231], v[80:83]
	v_mfma_f32_16x16x32_bf16 v[68:71], v[164:167], v[236:239], v[68:71]
	v_mfma_f32_16x16x32_bf16 v[64:67], v[172:175], v[236:239], v[64:67]
	s_setprio 0
	s_barrier
	s_add_i32 s10, s10, s3
	v_lshl_add_u64 v[240:241], v[240:241], 0, s[48:49]
	s_mov_b32 m0, s10
	ds_read_b128 v[176:179], v146 offset:49152
	ds_read_b128 v[180:183], v146 offset:50176
	ds_read_b128 v[184:187], v146 offset:51200
	ds_read_b128 v[208:211], v146 offset:52224
	ds_read_b128 v[212:215], v146 offset:53248
	ds_read_b128 v[228:231], v146 offset:54272
	ds_read_b128 v[232:235], v146 offset:55296
	ds_read_b128 v[236:239], v146 offset:56320
	global_load_lds_dwordx4 v[240:241], off
	s_add_i32 m0, s10, 0x2000
	s_add_u32 s46, s46, 0x40080
	v_lshl_add_u64 v[240:241], v[242:243], 0, s[48:49]
	s_addc_u32 s47, s47, 0
	s_add_i32 s10, s33, s3
	global_load_lds_dwordx4 v[240:241], off
	v_lshl_add_u64 v[240:241], s[46:47], 0, v[132:133]
	s_mov_b32 m0, s10
	s_nop 0
	global_load_lds_dwordx4 v[240:241], off
	v_lshl_add_u64 v[240:241], s[46:47], 0, v[128:129]
	s_add_i32 m0, s10, 0x2000
	s_nop 0
	global_load_lds_dwordx4 v[240:241], off
	v_lshl_add_u64 v[240:241], v[244:245], 0, s[48:49]
	s_mov_b32 m0, s18
	s_nop 0
	global_load_lds_dwordx4 v[240:241], off
	v_lshl_add_u64 v[240:241], v[246:247], 0, s[48:49]
	s_mov_b32 m0, s45
	s_nop 0
	global_load_lds_dwordx4 v[240:241], off
	s_waitcnt vmcnt(8)
	s_barrier
	s_setprio 1
	s_waitcnt lgkmcnt(7)
	v_mfma_f32_16x16x32_bf16 v[60:63], v[140:143], v[176:179], v[60:63]
	v_mfma_f32_16x16x32_bf16 v[56:59], v[152:155], v[176:179], v[56:59]
	s_waitcnt lgkmcnt(5)
	v_mfma_f32_16x16x32_bf16 v[44:47], v[140:143], v[184:187], v[44:47]
	v_mfma_f32_16x16x32_bf16 v[40:43], v[152:155], v[184:187], v[40:43]
	s_waitcnt lgkmcnt(3)
	v_mfma_f32_16x16x32_bf16 v[28:31], v[140:143], v[212:215], v[28:31]
	v_mfma_f32_16x16x32_bf16 v[24:27], v[152:155], v[212:215], v[24:27]
	s_waitcnt lgkmcnt(1)
	v_mfma_f32_16x16x32_bf16 v[12:15], v[140:143], v[232:235], v[12:15]
	v_mfma_f32_16x16x32_bf16 v[8:11], v[152:155], v[232:235], v[8:11]
	v_mfma_f32_16x16x32_bf16 v[60:63], v[148:151], v[180:183], v[60:63]
	v_mfma_f32_16x16x32_bf16 v[56:59], v[156:159], v[180:183], v[56:59]
	v_mfma_f32_16x16x32_bf16 v[44:47], v[148:151], v[208:211], v[44:47]
	v_mfma_f32_16x16x32_bf16 v[40:43], v[156:159], v[208:211], v[40:43]
	v_mfma_f32_16x16x32_bf16 v[28:31], v[148:151], v[228:231], v[28:31]
	v_mfma_f32_16x16x32_bf16 v[24:27], v[156:159], v[228:231], v[24:27]
	s_waitcnt lgkmcnt(0)
	v_mfma_f32_16x16x32_bf16 v[12:15], v[148:151], v[236:239], v[12:15]
	v_mfma_f32_16x16x32_bf16 v[8:11], v[156:159], v[236:239], v[8:11]
	s_setprio 0
	s_setprio 1
	v_mfma_f32_16x16x32_bf16 v[52:55], v[160:163], v[176:179], v[52:55]
	v_mfma_f32_16x16x32_bf16 v[48:51], v[168:171], v[176:179], v[48:51]
	v_mfma_f32_16x16x32_bf16 v[36:39], v[160:163], v[184:187], v[36:39]
	v_mfma_f32_16x16x32_bf16 v[32:35], v[168:171], v[184:187], v[32:35]
	v_mfma_f32_16x16x32_bf16 v[20:23], v[160:163], v[212:215], v[20:23]
	v_mfma_f32_16x16x32_bf16 v[16:19], v[168:171], v[212:215], v[16:19]
	v_mfma_f32_16x16x32_bf16 v[4:7], v[160:163], v[232:235], v[4:7]
	v_mfma_f32_16x16x32_bf16 v[0:3], v[168:171], v[232:235], v[0:3]
	v_mfma_f32_16x16x32_bf16 v[52:55], v[164:167], v[180:183], v[52:55]
	v_mfma_f32_16x16x32_bf16 v[48:51], v[172:175], v[180:183], v[48:51]
	v_mfma_f32_16x16x32_bf16 v[36:39], v[164:167], v[208:211], v[36:39]
	v_mfma_f32_16x16x32_bf16 v[32:35], v[172:175], v[208:211], v[32:35]
	v_mfma_f32_16x16x32_bf16 v[20:23], v[164:167], v[228:231], v[20:23]
	v_mfma_f32_16x16x32_bf16 v[16:19], v[172:175], v[228:231], v[16:19]
	v_mfma_f32_16x16x32_bf16 v[4:7], v[164:167], v[236:239], v[4:7]
	v_mfma_f32_16x16x32_bf16 v[0:3], v[172:175], v[236:239], v[0:3]
	s_setprio 0
	s_barrier
	s_add_i32 s72, s72, 2
	s_add_u32 s90, s90, 0x100
	s_addc_u32 s91, s91, 0
	s_add_u32 s65, s65, 0x100
	s_addc_u32 s71, s71, 0
	s_cmp_gt_u32 s72, 13
	s_cbranch_scc0 .LBB0_216
	s_branch .Lgemm0_exit
.LBB0_216:
	s_add_u32 s10, s90, 0xfffc0080
	s_addc_u32 s33, s91, -1
	s_add_i32 s73, 0, 0x10000
	s_cmp_eq_u32 s72, 12
	s_cselect_b32 vcc_hi, s9, s33
	s_cselect_b32 vcc_lo, s34, s10
	v_add_u32_e32 v147, s73, v145
	s_cselect_b32 s47, s35, s71
	s_cselect_b32 s46, s41, s65
	s_add_i32 s10, 0, 0x14000
	ds_read_b128 v[140:143], v147
	ds_read_b128 v[148:151], v147 offset:1024
	ds_read_b128 v[152:155], v147 offset:2048
	ds_read_b128 v[156:159], v147 offset:3072
	v_add_u32_e32 v147, s10, v145
	ds_read_b128 v[160:163], v147
	ds_read_b128 v[164:167], v147 offset:1024
	ds_read_b128 v[168:171], v147 offset:2048
	ds_read_b128 v[172:175], v147 offset:3072
	v_lshl_add_u64 v[240:241], s[90:91], 0, v[136:137]
	s_add_i32 m0, s11, 0xc000
	ds_read_b128 v[176:179], v146
	ds_read_b128 v[180:183], v146 offset:1024
	ds_read_b128 v[184:187], v146 offset:2048
	ds_read_b128 v[208:211], v146 offset:3072
	ds_read_b128 v[212:215], v146 offset:4096
	ds_read_b128 v[228:231], v146 offset:5120
	ds_read_b128 v[232:235], v146 offset:6144
	ds_read_b128 v[236:239], v146 offset:7168
	global_load_lds_dwordx4 v[240:241], off
	v_lshl_add_u64 v[240:241], s[90:91], 0, v[138:139]
	s_add_i32 m0, s11, 0xe000
	s_nop 0
	global_load_lds_dwordx4 v[240:241], off
	s_waitcnt vmcnt(8)
	s_barrier
	s_setprio 1
	s_waitcnt lgkmcnt(7)
	v_mfma_f32_16x16x32_bf16 v[124:127], v[140:143], v[176:179], v[124:127]
	v_mfma_f32_16x16x32_bf16 v[120:123], v[152:155], v[176:179], v[120:123]
	s_waitcnt lgkmcnt(5)
	v_mfma_f32_16x16x32_bf16 v[108:111], v[140:143], v[184:187], v[108:111]
	v_mfma_f32_16x16x32_bf16 v[104:107], v[152:155], v[184:187], v[104:107]
	s_waitcnt lgkmcnt(3)
	v_mfma_f32_16x16x32_bf16 v[92:95], v[140:143], v[212:215], v[92:95]
	v_mfma_f32_16x16x32_bf16 v[88:91], v[152:155], v[212:215], v[88:91]
	s_waitcnt lgkmcnt(1)
	v_mfma_f32_16x16x32_bf16 v[76:79], v[140:143], v[232:235], v[76:79]
	v_mfma_f32_16x16x32_bf16 v[72:75], v[152:155], v[232:235], v[72:75]
	v_mfma_f32_16x16x32_bf16 v[124:127], v[148:151], v[180:183], v[124:127]
	v_mfma_f32_16x16x32_bf16 v[120:123], v[156:159], v[180:183], v[120:123]
	v_mfma_f32_16x16x32_bf16 v[108:111], v[148:151], v[208:211], v[108:111]
	v_mfma_f32_16x16x32_bf16 v[104:107], v[156:159], v[208:211], v[104:107]
	v_mfma_f32_16x16x32_bf16 v[92:95], v[148:151], v[228:231], v[92:95]
	v_mfma_f32_16x16x32_bf16 v[88:91], v[156:159], v[228:231], v[88:91]
	s_waitcnt lgkmcnt(0)
	v_mfma_f32_16x16x32_bf16 v[76:79], v[148:151], v[236:239], v[76:79]
	v_mfma_f32_16x16x32_bf16 v[72:75], v[156:159], v[236:239], v[72:75]
	s_setprio 0
	s_setprio 1
	v_mfma_f32_16x16x32_bf16 v[116:119], v[160:163], v[176:179], v[116:119]
	v_mfma_f32_16x16x32_bf16 v[112:115], v[168:171], v[176:179], v[112:115]
	v_mfma_f32_16x16x32_bf16 v[100:103], v[160:163], v[184:187], v[100:103]
	v_mfma_f32_16x16x32_bf16 v[96:99], v[168:171], v[184:187], v[96:99]
	v_mfma_f32_16x16x32_bf16 v[84:87], v[160:163], v[212:215], v[84:87]
	v_mfma_f32_16x16x32_bf16 v[80:83], v[168:171], v[212:215], v[80:83]
	v_mfma_f32_16x16x32_bf16 v[68:71], v[160:163], v[232:235], v[68:71]
	v_mfma_f32_16x16x32_bf16 v[64:67], v[168:171], v[232:235], v[64:67]
	v_mfma_f32_16x16x32_bf16 v[116:119], v[164:167], v[180:183], v[116:119]
	v_mfma_f32_16x16x32_bf16 v[112:115], v[172:175], v[180:183], v[112:115]
	v_mfma_f32_16x16x32_bf16 v[100:103], v[164:167], v[208:211], v[100:103]
	v_mfma_f32_16x16x32_bf16 v[96:99], v[172:175], v[208:211], v[96:99]
	v_mfma_f32_16x16x32_bf16 v[84:87], v[164:167], v[228:231], v[84:87]
	v_mfma_f32_16x16x32_bf16 v[80:83], v[172:175], v[228:231], v[80:83]
	v_mfma_f32_16x16x32_bf16 v[68:71], v[164:167], v[236:239], v[68:71]
	v_mfma_f32_16x16x32_bf16 v[64:67], v[172:175], v[236:239], v[64:67]
	s_setprio 0
	s_barrier
	s_add_i32 s33, s73, s3
	v_lshl_add_u64 v[240:241], s[46:47], 0, v[132:133]
	s_mov_b32 m0, s33
	ds_read_b128 v[176:179], v146 offset:16384
	ds_read_b128 v[180:183], v146 offset:17408
	ds_read_b128 v[184:187], v146 offset:18432
	ds_read_b128 v[208:211], v146 offset:19456
	ds_read_b128 v[212:215], v146 offset:20480
	ds_read_b128 v[228:231], v146 offset:21504
	ds_read_b128 v[232:235], v146 offset:22528
	ds_read_b128 v[236:239], v146 offset:23552
	global_load_lds_dwordx4 v[240:241], off
	s_add_i32 m0, s33, 0x2000
	s_add_u32 s78, s46, 0x40000
	v_lshl_add_u64 v[242:243], s[46:47], 0, v[128:129]
	s_addc_u32 s79, s47, 0
	s_add_i32 s10, s10, s3
	global_load_lds_dwordx4 v[242:243], off
	v_lshl_add_u64 v[244:245], s[78:79], 0, v[132:133]
	s_mov_b32 m0, s10
	v_lshl_add_u64 v[246:247], vcc, 0, v[130:131]
	global_load_lds_dwordx4 v[244:245], off
	v_lshl_add_u64 v[244:245], s[78:79], 0, v[128:129]
	s_add_i32 m0, s10, 0x2000
	s_nop 0
	global_load_lds_dwordx4 v[244:245], off
	v_lshl_add_u64 v[244:245], vcc, 0, v[134:135]
	s_mov_b32 m0, s11
	s_nop 0
	global_load_lds_dwordx4 v[244:245], off
	s_mov_b32 m0, s12
	s_nop 0
	global_load_lds_dwordx4 v[246:247], off
	s_waitcnt vmcnt(8)
	s_barrier
	s_setprio 1
	s_waitcnt lgkmcnt(7)
	v_mfma_f32_16x16x32_bf16 v[60:63], v[140:143], v[176:179], v[60:63]
	v_mfma_f32_16x16x32_bf16 v[56:59], v[152:155], v[176:179], v[56:59]
	s_waitcnt lgkmcnt(5)
	v_mfma_f32_16x16x32_bf16 v[44:47], v[140:143], v[184:187], v[44:47]
	v_mfma_f32_16x16x32_bf16 v[40:43], v[152:155], v[184:187], v[40:43]
	s_waitcnt lgkmcnt(3)
	v_mfma_f32_16x16x32_bf16 v[28:31], v[140:143], v[212:215], v[28:31]
	v_mfma_f32_16x16x32_bf16 v[24:27], v[152:155], v[212:215], v[24:27]
	s_waitcnt lgkmcnt(1)
	v_mfma_f32_16x16x32_bf16 v[12:15], v[140:143], v[232:235], v[12:15]
	v_mfma_f32_16x16x32_bf16 v[8:11], v[152:155], v[232:235], v[8:11]
	v_mfma_f32_16x16x32_bf16 v[60:63], v[148:151], v[180:183], v[60:63]
	v_mfma_f32_16x16x32_bf16 v[56:59], v[156:159], v[180:183], v[56:59]
	v_mfma_f32_16x16x32_bf16 v[44:47], v[148:151], v[208:211], v[44:47]
	v_mfma_f32_16x16x32_bf16 v[40:43], v[156:159], v[208:211], v[40:43]
	v_mfma_f32_16x16x32_bf16 v[28:31], v[148:151], v[228:231], v[28:31]
	v_mfma_f32_16x16x32_bf16 v[24:27], v[156:159], v[228:231], v[24:27]
	s_waitcnt lgkmcnt(0)
	v_mfma_f32_16x16x32_bf16 v[12:15], v[148:151], v[236:239], v[12:15]
	v_mfma_f32_16x16x32_bf16 v[8:11], v[156:159], v[236:239], v[8:11]
	s_setprio 0
	s_setprio 1
	v_mfma_f32_16x16x32_bf16 v[52:55], v[160:163], v[176:179], v[52:55]
	v_mfma_f32_16x16x32_bf16 v[48:51], v[168:171], v[176:179], v[48:51]
	v_mfma_f32_16x16x32_bf16 v[36:39], v[160:163], v[184:187], v[36:39]
	v_mfma_f32_16x16x32_bf16 v[32:35], v[168:171], v[184:187], v[32:35]
	v_mfma_f32_16x16x32_bf16 v[20:23], v[160:163], v[212:215], v[20:23]
	v_mfma_f32_16x16x32_bf16 v[16:19], v[168:171], v[212:215], v[16:19]
	v_mfma_f32_16x16x32_bf16 v[4:7], v[160:163], v[232:235], v[4:7]
	v_mfma_f32_16x16x32_bf16 v[0:3], v[168:171], v[232:235], v[0:3]
	v_mfma_f32_16x16x32_bf16 v[52:55], v[164:167], v[180:183], v[52:55]
	v_mfma_f32_16x16x32_bf16 v[48:51], v[172:175], v[180:183], v[48:51]
	v_mfma_f32_16x16x32_bf16 v[36:39], v[164:167], v[208:211], v[36:39]
	v_mfma_f32_16x16x32_bf16 v[32:35], v[172:175], v[208:211], v[32:35]
	v_mfma_f32_16x16x32_bf16 v[20:23], v[164:167], v[228:231], v[20:23]
	v_mfma_f32_16x16x32_bf16 v[16:19], v[172:175], v[228:231], v[16:19]
	v_mfma_f32_16x16x32_bf16 v[4:7], v[164:167], v[236:239], v[4:7]
	v_mfma_f32_16x16x32_bf16 v[0:3], v[172:175], v[236:239], v[0:3]
	s_setprio 0
	s_barrier
	s_add_i32 s10, 0, 0x18000
	v_add_u32_e32 v147, s10, v145
	s_add_i32 s33, 0, 0x1c000
	ds_read_b128 v[140:143], v147
	ds_read_b128 v[148:151], v147 offset:1024
	ds_read_b128 v[152:155], v147 offset:2048
	ds_read_b128 v[156:159], v147 offset:3072
	v_add_u32_e32 v147, s33, v145
	ds_read_b128 v[160:163], v147
	ds_read_b128 v[164:167], v147 offset:1024
	ds_read_b128 v[168:171], v147 offset:2048
	ds_read_b128 v[172:175], v147 offset:3072
	s_add_u32 s78, vcc_lo, 0x40000
	s_addc_u32 s79, vcc_hi, 0
	s_mov_b32 m0, s16
	v_lshl_add_u64 v[248:249], s[78:79], 0, v[134:135]
	ds_read_b128 v[176:179], v146 offset:32768
	ds_read_b128 v[180:183], v146 offset:33792
	ds_read_b128 v[184:187], v146 offset:34816
	ds_read_b128 v[208:211], v146 offset:35840
	ds_read_b128 v[212:215], v146 offset:36864
	ds_read_b128 v[228:231], v146 offset:37888
	ds_read_b128 v[232:235], v146 offset:38912
	ds_read_b128 v[236:239], v146 offset:39936
	global_load_lds_dwordx4 v[248:249], off
	v_lshl_add_u64 v[248:249], s[78:79], 0, v[130:131]
	s_mov_b32 m0, s17
	s_nop 0
	global_load_lds_dwordx4 v[248:249], off
	s_waitcnt vmcnt(8)
	s_barrier
	s_setprio 1
	s_waitcnt lgkmcnt(7)
	v_mfma_f32_16x16x32_bf16 v[124:127], v[140:143], v[176:179], v[124:127]
	v_mfma_f32_16x16x32_bf16 v[120:123], v[152:155], v[176:179], v[120:123]
	s_waitcnt lgkmcnt(5)
	v_mfma_f32_16x16x32_bf16 v[108:111], v[140:143], v[184:187], v[108:111]
	v_mfma_f32_16x16x32_bf16 v[104:107], v[152:155], v[184:187], v[104:107]
	s_waitcnt lgkmcnt(3)
	v_mfma_f32_16x16x32_bf16 v[92:95], v[140:143], v[212:215], v[92:95]
	v_mfma_f32_16x16x32_bf16 v[88:91], v[152:155], v[212:215], v[88:91]
	s_waitcnt lgkmcnt(1)
	v_mfma_f32_16x16x32_bf16 v[76:79], v[140:143], v[232:235], v[76:79]
	v_mfma_f32_16x16x32_bf16 v[72:75], v[152:155], v[232:235], v[72:75]
	v_mfma_f32_16x16x32_bf16 v[124:127], v[148:151], v[180:183], v[124:127]
	v_mfma_f32_16x16x32_bf16 v[120:123], v[156:159], v[180:183], v[120:123]
	v_mfma_f32_16x16x32_bf16 v[108:111], v[148:151], v[208:211], v[108:111]
	v_mfma_f32_16x16x32_bf16 v[104:107], v[156:159], v[208:211], v[104:107]
	v_mfma_f32_16x16x32_bf16 v[92:95], v[148:151], v[228:231], v[92:95]
	v_mfma_f32_16x16x32_bf16 v[88:91], v[156:159], v[228:231], v[88:91]
	s_waitcnt lgkmcnt(0)
	v_mfma_f32_16x16x32_bf16 v[76:79], v[148:151], v[236:239], v[76:79]
	v_mfma_f32_16x16x32_bf16 v[72:75], v[156:159], v[236:239], v[72:75]
	s_setprio 0
	s_setprio 1
	v_mfma_f32_16x16x32_bf16 v[116:119], v[160:163], v[176:179], v[116:119]
	v_mfma_f32_16x16x32_bf16 v[112:115], v[168:171], v[176:179], v[112:115]
	v_mfma_f32_16x16x32_bf16 v[100:103], v[160:163], v[184:187], v[100:103]
	v_mfma_f32_16x16x32_bf16 v[96:99], v[168:171], v[184:187], v[96:99]
	v_mfma_f32_16x16x32_bf16 v[84:87], v[160:163], v[212:215], v[84:87]
	v_mfma_f32_16x16x32_bf16 v[80:83], v[168:171], v[212:215], v[80:83]
	v_mfma_f32_16x16x32_bf16 v[68:71], v[160:163], v[232:235], v[68:71]
	v_mfma_f32_16x16x32_bf16 v[64:67], v[168:171], v[232:235], v[64:67]
	v_mfma_f32_16x16x32_bf16 v[116:119], v[164:167], v[180:183], v[116:119]
	v_mfma_f32_16x16x32_bf16 v[112:115], v[172:175], v[180:183], v[112:115]
	v_mfma_f32_16x16x32_bf16 v[100:103], v[164:167], v[208:211], v[100:103]
	v_mfma_f32_16x16x32_bf16 v[96:99], v[172:175], v[208:211], v[96:99]
	v_mfma_f32_16x16x32_bf16 v[84:87], v[164:167], v[228:231], v[84:87]
	v_mfma_f32_16x16x32_bf16 v[80:83], v[172:175], v[228:231], v[80:83]
	v_mfma_f32_16x16x32_bf16 v[68:71], v[164:167], v[236:239], v[68:71]
	v_mfma_f32_16x16x32_bf16 v[64:67], v[172:175], v[236:239], v[64:67]
	s_setprio 0
	s_barrier
	s_add_i32 s10, s10, s3
	v_lshl_add_u64 v[240:241], v[240:241], 0, s[48:49]
	s_mov_b32 m0, s10
	ds_read_b128 v[176:179], v146 offset:49152
	ds_read_b128 v[180:183], v146 offset:50176
	ds_read_b128 v[184:187], v146 offset:51200
	ds_read_b128 v[208:211], v146 offset:52224
	ds_read_b128 v[212:215], v146 offset:53248
	ds_read_b128 v[228:231], v146 offset:54272
	ds_read_b128 v[232:235], v146 offset:55296
	ds_read_b128 v[236:239], v146 offset:56320
	global_load_lds_dwordx4 v[240:241], off
	s_add_i32 m0, s10, 0x2000
	s_add_u32 s46, s46, 0x40080
	v_lshl_add_u64 v[240:241], v[242:243], 0, s[48:49]
	s_addc_u32 s47, s47, 0
	s_add_i32 s10, s33, s3
	global_load_lds_dwordx4 v[240:241], off
	v_lshl_add_u64 v[240:241], s[46:47], 0, v[132:133]
	s_mov_b32 m0, s10
	s_nop 0
	global_load_lds_dwordx4 v[240:241], off
	v_lshl_add_u64 v[240:241], s[46:47], 0, v[128:129]
	s_add_i32 m0, s10, 0x2000
	s_nop 0
	global_load_lds_dwordx4 v[240:241], off
	v_lshl_add_u64 v[240:241], v[244:245], 0, s[48:49]
	s_mov_b32 m0, s18
	s_nop 0
	global_load_lds_dwordx4 v[240:241], off
	v_lshl_add_u64 v[240:241], v[246:247], 0, s[48:49]
	s_mov_b32 m0, s45
	s_nop 0
	global_load_lds_dwordx4 v[240:241], off
	s_waitcnt vmcnt(8)
	s_barrier
	s_setprio 1
	s_waitcnt lgkmcnt(7)
	v_mfma_f32_16x16x32_bf16 v[60:63], v[140:143], v[176:179], v[60:63]
	v_mfma_f32_16x16x32_bf16 v[56:59], v[152:155], v[176:179], v[56:59]
	s_waitcnt lgkmcnt(5)
	v_mfma_f32_16x16x32_bf16 v[44:47], v[140:143], v[184:187], v[44:47]
	v_mfma_f32_16x16x32_bf16 v[40:43], v[152:155], v[184:187], v[40:43]
	s_waitcnt lgkmcnt(3)
	v_mfma_f32_16x16x32_bf16 v[28:31], v[140:143], v[212:215], v[28:31]
	v_mfma_f32_16x16x32_bf16 v[24:27], v[152:155], v[212:215], v[24:27]
	s_waitcnt lgkmcnt(1)
	v_mfma_f32_16x16x32_bf16 v[12:15], v[140:143], v[232:235], v[12:15]
	v_mfma_f32_16x16x32_bf16 v[8:11], v[152:155], v[232:235], v[8:11]
	v_mfma_f32_16x16x32_bf16 v[60:63], v[148:151], v[180:183], v[60:63]
	v_mfma_f32_16x16x32_bf16 v[56:59], v[156:159], v[180:183], v[56:59]
	v_mfma_f32_16x16x32_bf16 v[44:47], v[148:151], v[208:211], v[44:47]
	v_mfma_f32_16x16x32_bf16 v[40:43], v[156:159], v[208:211], v[40:43]
	v_mfma_f32_16x16x32_bf16 v[28:31], v[148:151], v[228:231], v[28:31]
	v_mfma_f32_16x16x32_bf16 v[24:27], v[156:159], v[228:231], v[24:27]
	s_waitcnt lgkmcnt(0)
	v_mfma_f32_16x16x32_bf16 v[12:15], v[148:151], v[236:239], v[12:15]
	v_mfma_f32_16x16x32_bf16 v[8:11], v[156:159], v[236:239], v[8:11]
	s_setprio 0
	s_setprio 1
	v_mfma_f32_16x16x32_bf16 v[52:55], v[160:163], v[176:179], v[52:55]
	v_mfma_f32_16x16x32_bf16 v[48:51], v[168:171], v[176:179], v[48:51]
	v_mfma_f32_16x16x32_bf16 v[36:39], v[160:163], v[184:187], v[36:39]
	v_mfma_f32_16x16x32_bf16 v[32:35], v[168:171], v[184:187], v[32:35]
	v_mfma_f32_16x16x32_bf16 v[20:23], v[160:163], v[212:215], v[20:23]
	v_mfma_f32_16x16x32_bf16 v[16:19], v[168:171], v[212:215], v[16:19]
	v_mfma_f32_16x16x32_bf16 v[4:7], v[160:163], v[232:235], v[4:7]
	v_mfma_f32_16x16x32_bf16 v[0:3], v[168:171], v[232:235], v[0:3]
	v_mfma_f32_16x16x32_bf16 v[52:55], v[164:167], v[180:183], v[52:55]
	v_mfma_f32_16x16x32_bf16 v[48:51], v[172:175], v[180:183], v[48:51]
	v_mfma_f32_16x16x32_bf16 v[36:39], v[164:167], v[208:211], v[36:39]
	v_mfma_f32_16x16x32_bf16 v[32:35], v[172:175], v[208:211], v[32:35]
	v_mfma_f32_16x16x32_bf16 v[20:23], v[164:167], v[228:231], v[20:23]
	v_mfma_f32_16x16x32_bf16 v[16:19], v[172:175], v[228:231], v[16:19]
	v_mfma_f32_16x16x32_bf16 v[4:7], v[164:167], v[236:239], v[4:7]
	v_mfma_f32_16x16x32_bf16 v[0:3], v[172:175], v[236:239], v[0:3]
	s_setprio 0
	s_barrier
	s_add_i32 s72, s72, 2
	s_add_u32 s90, s90, 0x100
	s_addc_u32 s91, s91, 0
	s_add_u32 s65, s65, 0x100
	s_addc_u32 s71, s71, 0
	s_cmp_gt_u32 s72, 13
	s_cbranch_scc0 .LBB0_216

.Lgemm1_peel:
	s_add_u32 s10, s0, 0xfffc0080
	s_addc_u32 s33, s1, -1
	s_add_i32 s75, 0, 0x10000
	s_cmp_eq_u32 s73, 12
	s_cselect_b32 vcc_hi, s9, s33
	s_cselect_b32 vcc_lo, s34, s10
	v_add_u32_e32 v157, s75, v154
	s_cselect_b32 s47, s35, s72
	s_cselect_b32 s46, s45, s60
	s_add_i32 s10, 0, 0x14000
	ds_read_b128 v[140:143], v157
	ds_read_b128 v[144:147], v157 offset:1024
	ds_read_b128 v[148:151], v157 offset:2048
	ds_read_b128 v[158:161], v157 offset:3072
	v_add_u32_e32 v157, s10, v154
	ds_read_b128 v[162:165], v157
	ds_read_b128 v[166:169], v157 offset:1024
	ds_read_b128 v[170:173], v157 offset:2048
	ds_read_b128 v[174:177], v157 offset:3072
	v_lshl_add_u64 v[186:187], s[0:1], 0, v[136:137]
	s_add_i32 m0, s11, 0xc000
	ds_read_b128 v[178:181], v156
	ds_read_b128 v[182:185], v156 offset:1024
	ds_read_b128 v[208:211], v156 offset:2048
	ds_read_b128 v[212:215], v156 offset:3072
	ds_read_b128 v[228:231], v156 offset:4096
	ds_read_b128 v[232:235], v156 offset:5120
	ds_read_b128 v[236:239], v156 offset:6144
	ds_read_b128 v[240:243], v156 offset:7168
	global_load_lds_dwordx4 v[186:187], off
	v_lshl_add_u64 v[186:187], s[0:1], 0, v[138:139]
	s_add_i32 m0, s11, 0xe000
	s_nop 0
	global_load_lds_dwordx4 v[186:187], off
	s_waitcnt vmcnt(8)
	s_barrier
	s_setprio 1
	s_waitcnt lgkmcnt(7)
	v_mfma_f32_16x16x32_bf16 v[124:127], v[140:143], v[178:181], 0
	v_mfma_f32_16x16x32_bf16 v[120:123], v[148:151], v[178:181], 0
	s_waitcnt lgkmcnt(5)
	v_mfma_f32_16x16x32_bf16 v[116:119], v[140:143], v[208:211], 0
	v_mfma_f32_16x16x32_bf16 v[112:115], v[148:151], v[208:211], 0
	s_waitcnt lgkmcnt(3)
	v_mfma_f32_16x16x32_bf16 v[108:111], v[140:143], v[228:231], 0
	v_mfma_f32_16x16x32_bf16 v[104:107], v[148:151], v[228:231], 0
	s_waitcnt lgkmcnt(1)
	v_mfma_f32_16x16x32_bf16 v[100:103], v[140:143], v[236:239], 0
	v_mfma_f32_16x16x32_bf16 v[96:99], v[148:151], v[236:239], 0
	v_mfma_f32_16x16x32_bf16 v[124:127], v[144:147], v[182:185], v[124:127]
	v_mfma_f32_16x16x32_bf16 v[120:123], v[158:161], v[182:185], v[120:123]
	v_mfma_f32_16x16x32_bf16 v[116:119], v[144:147], v[212:215], v[116:119]
	v_mfma_f32_16x16x32_bf16 v[112:115], v[158:161], v[212:215], v[112:115]
	v_mfma_f32_16x16x32_bf16 v[108:111], v[144:147], v[232:235], v[108:111]
	v_mfma_f32_16x16x32_bf16 v[104:107], v[158:161], v[232:235], v[104:107]
	s_waitcnt lgkmcnt(0)
	v_mfma_f32_16x16x32_bf16 v[100:103], v[144:147], v[240:243], v[100:103]
	v_mfma_f32_16x16x32_bf16 v[96:99], v[158:161], v[240:243], v[96:99]
	s_setprio 0
	s_setprio 1
	v_mfma_f32_16x16x32_bf16 v[60:63], v[162:165], v[178:181], 0
	v_mfma_f32_16x16x32_bf16 v[56:59], v[170:173], v[178:181], 0
	v_mfma_f32_16x16x32_bf16 v[52:55], v[162:165], v[208:211], 0
	v_mfma_f32_16x16x32_bf16 v[48:51], v[170:173], v[208:211], 0
	v_mfma_f32_16x16x32_bf16 v[44:47], v[162:165], v[228:231], 0
	v_mfma_f32_16x16x32_bf16 v[40:43], v[170:173], v[228:231], 0
	v_mfma_f32_16x16x32_bf16 v[36:39], v[162:165], v[236:239], 0
	v_mfma_f32_16x16x32_bf16 v[32:35], v[170:173], v[236:239], 0
	v_mfma_f32_16x16x32_bf16 v[60:63], v[166:169], v[182:185], v[60:63]
	v_mfma_f32_16x16x32_bf16 v[56:59], v[174:177], v[182:185], v[56:59]
	v_mfma_f32_16x16x32_bf16 v[52:55], v[166:169], v[212:215], v[52:55]
	v_mfma_f32_16x16x32_bf16 v[48:51], v[174:177], v[212:215], v[48:51]
	v_mfma_f32_16x16x32_bf16 v[44:47], v[166:169], v[232:235], v[44:47]
	v_mfma_f32_16x16x32_bf16 v[40:43], v[174:177], v[232:235], v[40:43]
	v_mfma_f32_16x16x32_bf16 v[36:39], v[166:169], v[240:243], v[36:39]
	v_mfma_f32_16x16x32_bf16 v[32:35], v[174:177], v[240:243], v[32:35]
	s_setprio 0
	s_barrier
	s_add_i32 s33, s75, s3
	v_lshl_add_u64 v[186:187], s[46:47], 0, v[132:133]
	s_mov_b32 m0, s33
	ds_read_b128 v[178:181], v156 offset:16384
	ds_read_b128 v[182:185], v156 offset:17408
	ds_read_b128 v[208:211], v156 offset:18432
	ds_read_b128 v[212:215], v156 offset:19456
	ds_read_b128 v[228:231], v156 offset:20480
	ds_read_b128 v[232:235], v156 offset:21504
	ds_read_b128 v[236:239], v156 offset:22528
	ds_read_b128 v[240:243], v156 offset:23552
	global_load_lds_dwordx4 v[186:187], off
	s_add_i32 m0, s33, 0x2000
	s_add_u32 s78, s46, 0x40000
	v_lshl_add_u64 v[244:245], s[46:47], 0, v[128:129]
	s_addc_u32 s79, s47, 0
	s_add_i32 s10, s10, s3
	global_load_lds_dwordx4 v[244:245], off
	v_lshl_add_u64 v[246:247], s[78:79], 0, v[132:133]
	s_mov_b32 m0, s10
	v_lshl_add_u64 v[248:249], vcc, 0, v[130:131]
	global_load_lds_dwordx4 v[246:247], off
	v_lshl_add_u64 v[246:247], s[78:79], 0, v[128:129]
	s_add_i32 m0, s10, 0x2000
	s_nop 0
	global_load_lds_dwordx4 v[246:247], off
	v_lshl_add_u64 v[246:247], vcc, 0, v[134:135]
	s_mov_b32 m0, s11
	s_nop 0
	global_load_lds_dwordx4 v[246:247], off
	s_mov_b32 m0, s12
	s_nop 0
	global_load_lds_dwordx4 v[248:249], off
	s_waitcnt vmcnt(8)
	s_barrier
	s_setprio 1
	s_waitcnt lgkmcnt(7)
	v_mfma_f32_16x16x32_bf16 v[92:95], v[140:143], v[178:181], 0
	v_mfma_f32_16x16x32_bf16 v[88:91], v[148:151], v[178:181], 0
	s_waitcnt lgkmcnt(5)
	v_mfma_f32_16x16x32_bf16 v[84:87], v[140:143], v[208:211], 0
	v_mfma_f32_16x16x32_bf16 v[80:83], v[148:151], v[208:211], 0
	s_waitcnt lgkmcnt(3)
	v_mfma_f32_16x16x32_bf16 v[76:79], v[140:143], v[228:231], 0
	v_mfma_f32_16x16x32_bf16 v[72:75], v[148:151], v[228:231], 0
	s_waitcnt lgkmcnt(1)
	v_mfma_f32_16x16x32_bf16 v[68:71], v[140:143], v[236:239], 0
	v_mfma_f32_16x16x32_bf16 v[64:67], v[148:151], v[236:239], 0
	v_mfma_f32_16x16x32_bf16 v[92:95], v[144:147], v[182:185], v[92:95]
	v_mfma_f32_16x16x32_bf16 v[88:91], v[158:161], v[182:185], v[88:91]
	v_mfma_f32_16x16x32_bf16 v[84:87], v[144:147], v[212:215], v[84:87]
	v_mfma_f32_16x16x32_bf16 v[80:83], v[158:161], v[212:215], v[80:83]
	v_mfma_f32_16x16x32_bf16 v[76:79], v[144:147], v[232:235], v[76:79]
	v_mfma_f32_16x16x32_bf16 v[72:75], v[158:161], v[232:235], v[72:75]
	s_waitcnt lgkmcnt(0)
	v_mfma_f32_16x16x32_bf16 v[68:71], v[144:147], v[240:243], v[68:71]
	v_mfma_f32_16x16x32_bf16 v[64:67], v[158:161], v[240:243], v[64:67]
	s_setprio 0
	s_setprio 1
	v_mfma_f32_16x16x32_bf16 v[28:31], v[162:165], v[178:181], 0
	v_mfma_f32_16x16x32_bf16 v[24:27], v[170:173], v[178:181], 0
	v_mfma_f32_16x16x32_bf16 v[20:23], v[162:165], v[208:211], 0
	v_mfma_f32_16x16x32_bf16 v[16:19], v[170:173], v[208:211], 0
	v_mfma_f32_16x16x32_bf16 v[12:15], v[162:165], v[228:231], 0
	v_mfma_f32_16x16x32_bf16 v[8:11], v[170:173], v[228:231], 0
	v_mfma_f32_16x16x32_bf16 v[4:7], v[162:165], v[236:239], 0
	v_mfma_f32_16x16x32_bf16 v[0:3], v[170:173], v[236:239], 0
	v_mfma_f32_16x16x32_bf16 v[28:31], v[166:169], v[182:185], v[28:31]
	v_mfma_f32_16x16x32_bf16 v[24:27], v[174:177], v[182:185], v[24:27]
	v_mfma_f32_16x16x32_bf16 v[20:23], v[166:169], v[212:215], v[20:23]
	v_mfma_f32_16x16x32_bf16 v[16:19], v[174:177], v[212:215], v[16:19]
	v_mfma_f32_16x16x32_bf16 v[12:15], v[166:169], v[232:235], v[12:15]
	v_mfma_f32_16x16x32_bf16 v[8:11], v[174:177], v[232:235], v[8:11]
	v_mfma_f32_16x16x32_bf16 v[4:7], v[166:169], v[240:243], v[4:7]
	v_mfma_f32_16x16x32_bf16 v[0:3], v[174:177], v[240:243], v[0:3]
	s_setprio 0
	s_barrier
	s_add_i32 s10, 0, 0x18000
	v_add_u32_e32 v157, s10, v154
	s_add_i32 s33, 0, 0x1c000
	ds_read_b128 v[140:143], v157
	ds_read_b128 v[144:147], v157 offset:1024
	ds_read_b128 v[148:151], v157 offset:2048
	ds_read_b128 v[158:161], v157 offset:3072
	v_add_u32_e32 v157, s33, v154
	ds_read_b128 v[162:165], v157
	ds_read_b128 v[166:169], v157 offset:1024
	ds_read_b128 v[170:173], v157 offset:2048
	ds_read_b128 v[174:177], v157 offset:3072
	s_add_u32 s78, vcc_lo, 0x40000
	s_addc_u32 s79, vcc_hi, 0
	s_mov_b32 m0, s16
	v_lshl_add_u64 v[250:251], s[78:79], 0, v[134:135]
	ds_read_b128 v[178:181], v156 offset:32768
	ds_read_b128 v[182:185], v156 offset:33792
	ds_read_b128 v[208:211], v156 offset:34816
	ds_read_b128 v[212:215], v156 offset:35840
	ds_read_b128 v[228:231], v156 offset:36864
	ds_read_b128 v[232:235], v156 offset:37888
	ds_read_b128 v[236:239], v156 offset:38912
	ds_read_b128 v[240:243], v156 offset:39936
	global_load_lds_dwordx4 v[250:251], off
	v_lshl_add_u64 v[250:251], s[78:79], 0, v[130:131]
	s_mov_b32 m0, s17
	s_nop 0
	global_load_lds_dwordx4 v[250:251], off
	s_waitcnt vmcnt(8)
	s_barrier
	s_setprio 1
	s_waitcnt lgkmcnt(7)
	v_mfma_f32_16x16x32_bf16 v[124:127], v[140:143], v[178:181], v[124:127]
	v_mfma_f32_16x16x32_bf16 v[120:123], v[148:151], v[178:181], v[120:123]
	s_waitcnt lgkmcnt(5)
	v_mfma_f32_16x16x32_bf16 v[116:119], v[140:143], v[208:211], v[116:119]
	v_mfma_f32_16x16x32_bf16 v[112:115], v[148:151], v[208:211], v[112:115]
	s_waitcnt lgkmcnt(3)
	v_mfma_f32_16x16x32_bf16 v[108:111], v[140:143], v[228:231], v[108:111]
	v_mfma_f32_16x16x32_bf16 v[104:107], v[148:151], v[228:231], v[104:107]
	s_waitcnt lgkmcnt(1)
	v_mfma_f32_16x16x32_bf16 v[100:103], v[140:143], v[236:239], v[100:103]
	v_mfma_f32_16x16x32_bf16 v[96:99], v[148:151], v[236:239], v[96:99]
	v_mfma_f32_16x16x32_bf16 v[124:127], v[144:147], v[182:185], v[124:127]
	v_mfma_f32_16x16x32_bf16 v[120:123], v[158:161], v[182:185], v[120:123]
	v_mfma_f32_16x16x32_bf16 v[116:119], v[144:147], v[212:215], v[116:119]
	v_mfma_f32_16x16x32_bf16 v[112:115], v[158:161], v[212:215], v[112:115]
	v_mfma_f32_16x16x32_bf16 v[108:111], v[144:147], v[232:235], v[108:111]
	v_mfma_f32_16x16x32_bf16 v[104:107], v[158:161], v[232:235], v[104:107]
	s_waitcnt lgkmcnt(0)
	v_mfma_f32_16x16x32_bf16 v[100:103], v[144:147], v[240:243], v[100:103]
	v_mfma_f32_16x16x32_bf16 v[96:99], v[158:161], v[240:243], v[96:99]
	s_setprio 0
	s_setprio 1
	v_mfma_f32_16x16x32_bf16 v[60:63], v[162:165], v[178:181], v[60:63]
	v_mfma_f32_16x16x32_bf16 v[56:59], v[170:173], v[178:181], v[56:59]
	v_mfma_f32_16x16x32_bf16 v[52:55], v[162:165], v[208:211], v[52:55]
	v_mfma_f32_16x16x32_bf16 v[48:51], v[170:173], v[208:211], v[48:51]
	v_mfma_f32_16x16x32_bf16 v[44:47], v[162:165], v[228:231], v[44:47]
	v_mfma_f32_16x16x32_bf16 v[40:43], v[170:173], v[228:231], v[40:43]
	v_mfma_f32_16x16x32_bf16 v[36:39], v[162:165], v[236:239], v[36:39]
	v_mfma_f32_16x16x32_bf16 v[32:35], v[170:173], v[236:239], v[32:35]
	v_mfma_f32_16x16x32_bf16 v[60:63], v[166:169], v[182:185], v[60:63]
	v_mfma_f32_16x16x32_bf16 v[56:59], v[174:177], v[182:185], v[56:59]
	v_mfma_f32_16x16x32_bf16 v[52:55], v[166:169], v[212:215], v[52:55]
	v_mfma_f32_16x16x32_bf16 v[48:51], v[174:177], v[212:215], v[48:51]
	v_mfma_f32_16x16x32_bf16 v[44:47], v[166:169], v[232:235], v[44:47]
	v_mfma_f32_16x16x32_bf16 v[40:43], v[174:177], v[232:235], v[40:43]
	v_mfma_f32_16x16x32_bf16 v[36:39], v[166:169], v[240:243], v[36:39]
	v_mfma_f32_16x16x32_bf16 v[32:35], v[174:177], v[240:243], v[32:35]
	s_setprio 0
	s_barrier
	s_add_i32 s10, s10, s3
	v_lshl_add_u64 v[186:187], v[186:187], 0, s[48:49]
	s_mov_b32 m0, s10
	ds_read_b128 v[178:181], v156 offset:49152
	ds_read_b128 v[182:185], v156 offset:50176
	ds_read_b128 v[208:211], v156 offset:51200
	ds_read_b128 v[212:215], v156 offset:52224
	ds_read_b128 v[228:231], v156 offset:53248
	ds_read_b128 v[232:235], v156 offset:54272
	ds_read_b128 v[236:239], v156 offset:55296
	ds_read_b128 v[240:243], v156 offset:56320
	global_load_lds_dwordx4 v[186:187], off
	s_add_i32 m0, s10, 0x2000
	s_add_u32 s46, s46, 0x40080
	v_lshl_add_u64 v[186:187], v[244:245], 0, s[48:49]
	s_addc_u32 s47, s47, 0
	s_add_i32 s10, s33, s3
	global_load_lds_dwordx4 v[186:187], off
	v_lshl_add_u64 v[186:187], s[46:47], 0, v[132:133]
	s_mov_b32 m0, s10
	s_nop 0
	global_load_lds_dwordx4 v[186:187], off
	v_lshl_add_u64 v[186:187], s[46:47], 0, v[128:129]
	s_add_i32 m0, s10, 0x2000
	s_nop 0
	global_load_lds_dwordx4 v[186:187], off
	v_lshl_add_u64 v[186:187], v[246:247], 0, s[48:49]
	s_mov_b32 m0, s71
	s_nop 0
	global_load_lds_dwordx4 v[186:187], off
	v_lshl_add_u64 v[186:187], v[248:249], 0, s[48:49]
	s_mov_b32 m0, s92
	s_nop 0
	global_load_lds_dwordx4 v[186:187], off
	s_waitcnt vmcnt(8)
	s_barrier
	s_setprio 1
	s_waitcnt lgkmcnt(7)
	v_mfma_f32_16x16x32_bf16 v[92:95], v[140:143], v[178:181], v[92:95]
	v_mfma_f32_16x16x32_bf16 v[88:91], v[148:151], v[178:181], v[88:91]
	s_waitcnt lgkmcnt(5)
	v_mfma_f32_16x16x32_bf16 v[84:87], v[140:143], v[208:211], v[84:87]
	v_mfma_f32_16x16x32_bf16 v[80:83], v[148:151], v[208:211], v[80:83]
	s_waitcnt lgkmcnt(3)
	v_mfma_f32_16x16x32_bf16 v[76:79], v[140:143], v[228:231], v[76:79]
	v_mfma_f32_16x16x32_bf16 v[72:75], v[148:151], v[228:231], v[72:75]
	s_waitcnt lgkmcnt(1)
	v_mfma_f32_16x16x32_bf16 v[68:71], v[140:143], v[236:239], v[68:71]
	v_mfma_f32_16x16x32_bf16 v[64:67], v[148:151], v[236:239], v[64:67]
	v_mfma_f32_16x16x32_bf16 v[92:95], v[144:147], v[182:185], v[92:95]
	v_mfma_f32_16x16x32_bf16 v[88:91], v[158:161], v[182:185], v[88:91]
	v_mfma_f32_16x16x32_bf16 v[84:87], v[144:147], v[212:215], v[84:87]
	v_mfma_f32_16x16x32_bf16 v[80:83], v[158:161], v[212:215], v[80:83]
	v_mfma_f32_16x16x32_bf16 v[76:79], v[144:147], v[232:235], v[76:79]
	v_mfma_f32_16x16x32_bf16 v[72:75], v[158:161], v[232:235], v[72:75]
	s_waitcnt lgkmcnt(0)
	v_mfma_f32_16x16x32_bf16 v[68:71], v[144:147], v[240:243], v[68:71]
	v_mfma_f32_16x16x32_bf16 v[64:67], v[158:161], v[240:243], v[64:67]
	s_setprio 0
	s_setprio 1
	v_mfma_f32_16x16x32_bf16 v[28:31], v[162:165], v[178:181], v[28:31]
	v_mfma_f32_16x16x32_bf16 v[24:27], v[170:173], v[178:181], v[24:27]
	v_mfma_f32_16x16x32_bf16 v[20:23], v[162:165], v[208:211], v[20:23]
	v_mfma_f32_16x16x32_bf16 v[16:19], v[170:173], v[208:211], v[16:19]
	v_mfma_f32_16x16x32_bf16 v[12:15], v[162:165], v[228:231], v[12:15]
	v_mfma_f32_16x16x32_bf16 v[8:11], v[170:173], v[228:231], v[8:11]
	v_mfma_f32_16x16x32_bf16 v[4:7], v[162:165], v[236:239], v[4:7]
	v_mfma_f32_16x16x32_bf16 v[0:3], v[170:173], v[236:239], v[0:3]
	v_mfma_f32_16x16x32_bf16 v[28:31], v[166:169], v[182:185], v[28:31]
	v_mfma_f32_16x16x32_bf16 v[24:27], v[174:177], v[182:185], v[24:27]
	v_mfma_f32_16x16x32_bf16 v[20:23], v[166:169], v[212:215], v[20:23]
	v_mfma_f32_16x16x32_bf16 v[16:19], v[174:177], v[212:215], v[16:19]
	v_mfma_f32_16x16x32_bf16 v[12:15], v[166:169], v[232:235], v[12:15]
	v_mfma_f32_16x16x32_bf16 v[8:11], v[174:177], v[232:235], v[8:11]
	v_mfma_f32_16x16x32_bf16 v[4:7], v[166:169], v[240:243], v[4:7]
	v_mfma_f32_16x16x32_bf16 v[0:3], v[174:177], v[240:243], v[0:3]
	s_setprio 0
	s_barrier
	s_add_i32 s73, s73, 2
	s_add_u32 s0, s0, 0x100
	s_addc_u32 s1, s1, 0
	s_add_u32 s60, s60, 0x100
	s_addc_u32 s72, s72, 0
	s_cmp_gt_u32 s73, 13
	s_cbranch_scc0 .LBB0_236
	s_branch .Lgemm1_exit
.LBB0_236:
	s_add_u32 s10, s0, 0xfffc0080
	s_addc_u32 s33, s1, -1
	s_add_i32 s75, 0, 0x10000
	s_cmp_eq_u32 s73, 12
	s_cselect_b32 vcc_hi, s9, s33
	s_cselect_b32 vcc_lo, s34, s10
	v_add_u32_e32 v157, s75, v154
	s_cselect_b32 s47, s35, s72
	s_cselect_b32 s46, s45, s60
	s_add_i32 s10, 0, 0x14000
	ds_read_b128 v[140:143], v157
	ds_read_b128 v[144:147], v157 offset:1024
	ds_read_b128 v[148:151], v157 offset:2048
	ds_read_b128 v[158:161], v157 offset:3072
	v_add_u32_e32 v157, s10, v154
	ds_read_b128 v[162:165], v157
	ds_read_b128 v[166:169], v157 offset:1024
	ds_read_b128 v[170:173], v157 offset:2048
	ds_read_b128 v[174:177], v157 offset:3072
	v_lshl_add_u64 v[186:187], s[0:1], 0, v[136:137]
	s_add_i32 m0, s11, 0xc000
	ds_read_b128 v[178:181], v156
	ds_read_b128 v[182:185], v156 offset:1024
	ds_read_b128 v[208:211], v156 offset:2048
	ds_read_b128 v[212:215], v156 offset:3072
	ds_read_b128 v[228:231], v156 offset:4096
	ds_read_b128 v[232:235], v156 offset:5120
	ds_read_b128 v[236:239], v156 offset:6144
	ds_read_b128 v[240:243], v156 offset:7168
	global_load_lds_dwordx4 v[186:187], off
	v_lshl_add_u64 v[186:187], s[0:1], 0, v[138:139]
	s_add_i32 m0, s11, 0xe000
	s_nop 0
	global_load_lds_dwordx4 v[186:187], off
	s_waitcnt vmcnt(8)
	s_barrier
	s_setprio 1
	s_waitcnt lgkmcnt(7)
	v_mfma_f32_16x16x32_bf16 v[124:127], v[140:143], v[178:181], v[124:127]
	v_mfma_f32_16x16x32_bf16 v[120:123], v[148:151], v[178:181], v[120:123]
	s_waitcnt lgkmcnt(5)
	v_mfma_f32_16x16x32_bf16 v[116:119], v[140:143], v[208:211], v[116:119]
	v_mfma_f32_16x16x32_bf16 v[112:115], v[148:151], v[208:211], v[112:115]
	s_waitcnt lgkmcnt(3)
	v_mfma_f32_16x16x32_bf16 v[108:111], v[140:143], v[228:231], v[108:111]
	v_mfma_f32_16x16x32_bf16 v[104:107], v[148:151], v[228:231], v[104:107]
	s_waitcnt lgkmcnt(1)
	v_mfma_f32_16x16x32_bf16 v[100:103], v[140:143], v[236:239], v[100:103]
	v_mfma_f32_16x16x32_bf16 v[96:99], v[148:151], v[236:239], v[96:99]
	v_mfma_f32_16x16x32_bf16 v[124:127], v[144:147], v[182:185], v[124:127]
	v_mfma_f32_16x16x32_bf16 v[120:123], v[158:161], v[182:185], v[120:123]
	v_mfma_f32_16x16x32_bf16 v[116:119], v[144:147], v[212:215], v[116:119]
	v_mfma_f32_16x16x32_bf16 v[112:115], v[158:161], v[212:215], v[112:115]
	v_mfma_f32_16x16x32_bf16 v[108:111], v[144:147], v[232:235], v[108:111]
	v_mfma_f32_16x16x32_bf16 v[104:107], v[158:161], v[232:235], v[104:107]
	s_waitcnt lgkmcnt(0)
	v_mfma_f32_16x16x32_bf16 v[100:103], v[144:147], v[240:243], v[100:103]
	v_mfma_f32_16x16x32_bf16 v[96:99], v[158:161], v[240:243], v[96:99]
	s_setprio 0
	s_setprio 1
	v_mfma_f32_16x16x32_bf16 v[60:63], v[162:165], v[178:181], v[60:63]
	v_mfma_f32_16x16x32_bf16 v[56:59], v[170:173], v[178:181], v[56:59]
	v_mfma_f32_16x16x32_bf16 v[52:55], v[162:165], v[208:211], v[52:55]
	v_mfma_f32_16x16x32_bf16 v[48:51], v[170:173], v[208:211], v[48:51]
	v_mfma_f32_16x16x32_bf16 v[44:47], v[162:165], v[228:231], v[44:47]
	v_mfma_f32_16x16x32_bf16 v[40:43], v[170:173], v[228:231], v[40:43]
	v_mfma_f32_16x16x32_bf16 v[36:39], v[162:165], v[236:239], v[36:39]
	v_mfma_f32_16x16x32_bf16 v[32:35], v[170:173], v[236:239], v[32:35]
	v_mfma_f32_16x16x32_bf16 v[60:63], v[166:169], v[182:185], v[60:63]
	v_mfma_f32_16x16x32_bf16 v[56:59], v[174:177], v[182:185], v[56:59]
	v_mfma_f32_16x16x32_bf16 v[52:55], v[166:169], v[212:215], v[52:55]
	v_mfma_f32_16x16x32_bf16 v[48:51], v[174:177], v[212:215], v[48:51]
	v_mfma_f32_16x16x32_bf16 v[44:47], v[166:169], v[232:235], v[44:47]
	v_mfma_f32_16x16x32_bf16 v[40:43], v[174:177], v[232:235], v[40:43]
	v_mfma_f32_16x16x32_bf16 v[36:39], v[166:169], v[240:243], v[36:39]
	v_mfma_f32_16x16x32_bf16 v[32:35], v[174:177], v[240:243], v[32:35]
	s_setprio 0
	s_barrier
	s_add_i32 s33, s75, s3
	v_lshl_add_u64 v[186:187], s[46:47], 0, v[132:133]
	s_mov_b32 m0, s33
	ds_read_b128 v[178:181], v156 offset:16384
	ds_read_b128 v[182:185], v156 offset:17408
	ds_read_b128 v[208:211], v156 offset:18432
	ds_read_b128 v[212:215], v156 offset:19456
	ds_read_b128 v[228:231], v156 offset:20480
	ds_read_b128 v[232:235], v156 offset:21504
	ds_read_b128 v[236:239], v156 offset:22528
	ds_read_b128 v[240:243], v156 offset:23552
	global_load_lds_dwordx4 v[186:187], off
	s_add_i32 m0, s33, 0x2000
	s_add_u32 s78, s46, 0x40000
	v_lshl_add_u64 v[244:245], s[46:47], 0, v[128:129]
	s_addc_u32 s79, s47, 0
	s_add_i32 s10, s10, s3
	global_load_lds_dwordx4 v[244:245], off
	v_lshl_add_u64 v[246:247], s[78:79], 0, v[132:133]
	s_mov_b32 m0, s10
	v_lshl_add_u64 v[248:249], vcc, 0, v[130:131]
	global_load_lds_dwordx4 v[246:247], off
	v_lshl_add_u64 v[246:247], s[78:79], 0, v[128:129]
	s_add_i32 m0, s10, 0x2000
	s_nop 0
	global_load_lds_dwordx4 v[246:247], off
	v_lshl_add_u64 v[246:247], vcc, 0, v[134:135]
	s_mov_b32 m0, s11
	s_nop 0
	global_load_lds_dwordx4 v[246:247], off
	s_mov_b32 m0, s12
	s_nop 0
	global_load_lds_dwordx4 v[248:249], off
	s_waitcnt vmcnt(8)
	s_barrier
	s_setprio 1
	s_waitcnt lgkmcnt(7)
	v_mfma_f32_16x16x32_bf16 v[92:95], v[140:143], v[178:181], v[92:95]
	v_mfma_f32_16x16x32_bf16 v[88:91], v[148:151], v[178:181], v[88:91]
	s_waitcnt lgkmcnt(5)
	v_mfma_f32_16x16x32_bf16 v[84:87], v[140:143], v[208:211], v[84:87]
	v_mfma_f32_16x16x32_bf16 v[80:83], v[148:151], v[208:211], v[80:83]
	s_waitcnt lgkmcnt(3)
	v_mfma_f32_16x16x32_bf16 v[76:79], v[140:143], v[228:231], v[76:79]
	v_mfma_f32_16x16x32_bf16 v[72:75], v[148:151], v[228:231], v[72:75]
	s_waitcnt lgkmcnt(1)
	v_mfma_f32_16x16x32_bf16 v[68:71], v[140:143], v[236:239], v[68:71]
	v_mfma_f32_16x16x32_bf16 v[64:67], v[148:151], v[236:239], v[64:67]
	v_mfma_f32_16x16x32_bf16 v[92:95], v[144:147], v[182:185], v[92:95]
	v_mfma_f32_16x16x32_bf16 v[88:91], v[158:161], v[182:185], v[88:91]
	v_mfma_f32_16x16x32_bf16 v[84:87], v[144:147], v[212:215], v[84:87]
	v_mfma_f32_16x16x32_bf16 v[80:83], v[158:161], v[212:215], v[80:83]
	v_mfma_f32_16x16x32_bf16 v[76:79], v[144:147], v[232:235], v[76:79]
	v_mfma_f32_16x16x32_bf16 v[72:75], v[158:161], v[232:235], v[72:75]
	s_waitcnt lgkmcnt(0)
	v_mfma_f32_16x16x32_bf16 v[68:71], v[144:147], v[240:243], v[68:71]
	v_mfma_f32_16x16x32_bf16 v[64:67], v[158:161], v[240:243], v[64:67]
	s_setprio 0
	s_setprio 1
	v_mfma_f32_16x16x32_bf16 v[28:31], v[162:165], v[178:181], v[28:31]
	v_mfma_f32_16x16x32_bf16 v[24:27], v[170:173], v[178:181], v[24:27]
	v_mfma_f32_16x16x32_bf16 v[20:23], v[162:165], v[208:211], v[20:23]
	v_mfma_f32_16x16x32_bf16 v[16:19], v[170:173], v[208:211], v[16:19]
	v_mfma_f32_16x16x32_bf16 v[12:15], v[162:165], v[228:231], v[12:15]
	v_mfma_f32_16x16x32_bf16 v[8:11], v[170:173], v[228:231], v[8:11]
	v_mfma_f32_16x16x32_bf16 v[4:7], v[162:165], v[236:239], v[4:7]
	v_mfma_f32_16x16x32_bf16 v[0:3], v[170:173], v[236:239], v[0:3]
	v_mfma_f32_16x16x32_bf16 v[28:31], v[166:169], v[182:185], v[28:31]
	v_mfma_f32_16x16x32_bf16 v[24:27], v[174:177], v[182:185], v[24:27]
	v_mfma_f32_16x16x32_bf16 v[20:23], v[166:169], v[212:215], v[20:23]
	v_mfma_f32_16x16x32_bf16 v[16:19], v[174:177], v[212:215], v[16:19]
	v_mfma_f32_16x16x32_bf16 v[12:15], v[166:169], v[232:235], v[12:15]
	v_mfma_f32_16x16x32_bf16 v[8:11], v[174:177], v[232:235], v[8:11]
	v_mfma_f32_16x16x32_bf16 v[4:7], v[166:169], v[240:243], v[4:7]
	v_mfma_f32_16x16x32_bf16 v[0:3], v[174:177], v[240:243], v[0:3]
	s_setprio 0
	s_barrier
	s_add_i32 s10, 0, 0x18000
	v_add_u32_e32 v157, s10, v154
	s_add_i32 s33, 0, 0x1c000
	ds_read_b128 v[140:143], v157
	ds_read_b128 v[144:147], v157 offset:1024
	ds_read_b128 v[148:151], v157 offset:2048
	ds_read_b128 v[158:161], v157 offset:3072
	v_add_u32_e32 v157, s33, v154
	ds_read_b128 v[162:165], v157
	ds_read_b128 v[166:169], v157 offset:1024
	ds_read_b128 v[170:173], v157 offset:2048
	ds_read_b128 v[174:177], v157 offset:3072
	s_add_u32 s78, vcc_lo, 0x40000
	s_addc_u32 s79, vcc_hi, 0
	s_mov_b32 m0, s16
	v_lshl_add_u64 v[250:251], s[78:79], 0, v[134:135]
	ds_read_b128 v[178:181], v156 offset:32768
	ds_read_b128 v[182:185], v156 offset:33792
	ds_read_b128 v[208:211], v156 offset:34816
	ds_read_b128 v[212:215], v156 offset:35840
	ds_read_b128 v[228:231], v156 offset:36864
	ds_read_b128 v[232:235], v156 offset:37888
	ds_read_b128 v[236:239], v156 offset:38912
	ds_read_b128 v[240:243], v156 offset:39936
	global_load_lds_dwordx4 v[250:251], off
	v_lshl_add_u64 v[250:251], s[78:79], 0, v[130:131]
	s_mov_b32 m0, s17
	s_nop 0
	global_load_lds_dwordx4 v[250:251], off
	s_waitcnt vmcnt(8)
	s_barrier
	s_setprio 1
	s_waitcnt lgkmcnt(7)
	v_mfma_f32_16x16x32_bf16 v[124:127], v[140:143], v[178:181], v[124:127]
	v_mfma_f32_16x16x32_bf16 v[120:123], v[148:151], v[178:181], v[120:123]
	s_waitcnt lgkmcnt(5)
	v_mfma_f32_16x16x32_bf16 v[116:119], v[140:143], v[208:211], v[116:119]
	v_mfma_f32_16x16x32_bf16 v[112:115], v[148:151], v[208:211], v[112:115]
	s_waitcnt lgkmcnt(3)
	v_mfma_f32_16x16x32_bf16 v[108:111], v[140:143], v[228:231], v[108:111]
	v_mfma_f32_16x16x32_bf16 v[104:107], v[148:151], v[228:231], v[104:107]
	s_waitcnt lgkmcnt(1)
	v_mfma_f32_16x16x32_bf16 v[100:103], v[140:143], v[236:239], v[100:103]
	v_mfma_f32_16x16x32_bf16 v[96:99], v[148:151], v[236:239], v[96:99]
	v_mfma_f32_16x16x32_bf16 v[124:127], v[144:147], v[182:185], v[124:127]
	v_mfma_f32_16x16x32_bf16 v[120:123], v[158:161], v[182:185], v[120:123]
	v_mfma_f32_16x16x32_bf16 v[116:119], v[144:147], v[212:215], v[116:119]
	v_mfma_f32_16x16x32_bf16 v[112:115], v[158:161], v[212:215], v[112:115]
	v_mfma_f32_16x16x32_bf16 v[108:111], v[144:147], v[232:235], v[108:111]
	v_mfma_f32_16x16x32_bf16 v[104:107], v[158:161], v[232:235], v[104:107]
	s_waitcnt lgkmcnt(0)
	v_mfma_f32_16x16x32_bf16 v[100:103], v[144:147], v[240:243], v[100:103]
	v_mfma_f32_16x16x32_bf16 v[96:99], v[158:161], v[240:243], v[96:99]
	s_setprio 0
	s_setprio 1
	v_mfma_f32_16x16x32_bf16 v[60:63], v[162:165], v[178:181], v[60:63]
	v_mfma_f32_16x16x32_bf16 v[56:59], v[170:173], v[178:181], v[56:59]
	v_mfma_f32_16x16x32_bf16 v[52:55], v[162:165], v[208:211], v[52:55]
	v_mfma_f32_16x16x32_bf16 v[48:51], v[170:173], v[208:211], v[48:51]
	v_mfma_f32_16x16x32_bf16 v[44:47], v[162:165], v[228:231], v[44:47]
	v_mfma_f32_16x16x32_bf16 v[40:43], v[170:173], v[228:231], v[40:43]
	v_mfma_f32_16x16x32_bf16 v[36:39], v[162:165], v[236:239], v[36:39]
	v_mfma_f32_16x16x32_bf16 v[32:35], v[170:173], v[236:239], v[32:35]
	v_mfma_f32_16x16x32_bf16 v[60:63], v[166:169], v[182:185], v[60:63]
	v_mfma_f32_16x16x32_bf16 v[56:59], v[174:177], v[182:185], v[56:59]
	v_mfma_f32_16x16x32_bf16 v[52:55], v[166:169], v[212:215], v[52:55]
	v_mfma_f32_16x16x32_bf16 v[48:51], v[174:177], v[212:215], v[48:51]
	v_mfma_f32_16x16x32_bf16 v[44:47], v[166:169], v[232:235], v[44:47]
	v_mfma_f32_16x16x32_bf16 v[40:43], v[174:177], v[232:235], v[40:43]
	v_mfma_f32_16x16x32_bf16 v[36:39], v[166:169], v[240:243], v[36:39]
	v_mfma_f32_16x16x32_bf16 v[32:35], v[174:177], v[240:243], v[32:35]
	s_setprio 0
	s_barrier
	s_add_i32 s10, s10, s3
	v_lshl_add_u64 v[186:187], v[186:187], 0, s[48:49]
	s_mov_b32 m0, s10
	ds_read_b128 v[178:181], v156 offset:49152
	ds_read_b128 v[182:185], v156 offset:50176
	ds_read_b128 v[208:211], v156 offset:51200
	ds_read_b128 v[212:215], v156 offset:52224
	ds_read_b128 v[228:231], v156 offset:53248
	ds_read_b128 v[232:235], v156 offset:54272
	ds_read_b128 v[236:239], v156 offset:55296
	ds_read_b128 v[240:243], v156 offset:56320
	global_load_lds_dwordx4 v[186:187], off
	s_add_i32 m0, s10, 0x2000
	s_add_u32 s46, s46, 0x40080
	v_lshl_add_u64 v[186:187], v[244:245], 0, s[48:49]
	s_addc_u32 s47, s47, 0
	s_add_i32 s10, s33, s3
	global_load_lds_dwordx4 v[186:187], off
	v_lshl_add_u64 v[186:187], s[46:47], 0, v[132:133]
	s_mov_b32 m0, s10
	s_nop 0
	global_load_lds_dwordx4 v[186:187], off
	v_lshl_add_u64 v[186:187], s[46:47], 0, v[128:129]
	s_add_i32 m0, s10, 0x2000
	s_nop 0
	global_load_lds_dwordx4 v[186:187], off
	v_lshl_add_u64 v[186:187], v[246:247], 0, s[48:49]
	s_mov_b32 m0, s71
	s_nop 0
	global_load_lds_dwordx4 v[186:187], off
	v_lshl_add_u64 v[186:187], v[248:249], 0, s[48:49]
	s_mov_b32 m0, s92
	s_nop 0
	global_load_lds_dwordx4 v[186:187], off
	s_waitcnt vmcnt(8)
	s_barrier
	s_setprio 1
	s_waitcnt lgkmcnt(7)
	v_mfma_f32_16x16x32_bf16 v[92:95], v[140:143], v[178:181], v[92:95]
	v_mfma_f32_16x16x32_bf16 v[88:91], v[148:151], v[178:181], v[88:91]
	s_waitcnt lgkmcnt(5)
	v_mfma_f32_16x16x32_bf16 v[84:87], v[140:143], v[208:211], v[84:87]
	v_mfma_f32_16x16x32_bf16 v[80:83], v[148:151], v[208:211], v[80:83]
	s_waitcnt lgkmcnt(3)
	v_mfma_f32_16x16x32_bf16 v[76:79], v[140:143], v[228:231], v[76:79]
	v_mfma_f32_16x16x32_bf16 v[72:75], v[148:151], v[228:231], v[72:75]
	s_waitcnt lgkmcnt(1)
	v_mfma_f32_16x16x32_bf16 v[68:71], v[140:143], v[236:239], v[68:71]
	v_mfma_f32_16x16x32_bf16 v[64:67], v[148:151], v[236:239], v[64:67]
	v_mfma_f32_16x16x32_bf16 v[92:95], v[144:147], v[182:185], v[92:95]
	v_mfma_f32_16x16x32_bf16 v[88:91], v[158:161], v[182:185], v[88:91]
	v_mfma_f32_16x16x32_bf16 v[84:87], v[144:147], v[212:215], v[84:87]
	v_mfma_f32_16x16x32_bf16 v[80:83], v[158:161], v[212:215], v[80:83]
	v_mfma_f32_16x16x32_bf16 v[76:79], v[144:147], v[232:235], v[76:79]
	v_mfma_f32_16x16x32_bf16 v[72:75], v[158:161], v[232:235], v[72:75]
	s_waitcnt lgkmcnt(0)
	v_mfma_f32_16x16x32_bf16 v[68:71], v[144:147], v[240:243], v[68:71]
	v_mfma_f32_16x16x32_bf16 v[64:67], v[158:161], v[240:243], v[64:67]
	s_setprio 0
	s_setprio 1
	v_mfma_f32_16x16x32_bf16 v[28:31], v[162:165], v[178:181], v[28:31]
	v_mfma_f32_16x16x32_bf16 v[24:27], v[170:173], v[178:181], v[24:27]
	v_mfma_f32_16x16x32_bf16 v[20:23], v[162:165], v[208:211], v[20:23]
	v_mfma_f32_16x16x32_bf16 v[16:19], v[170:173], v[208:211], v[16:19]
	v_mfma_f32_16x16x32_bf16 v[12:15], v[162:165], v[228:231], v[12:15]
	v_mfma_f32_16x16x32_bf16 v[8:11], v[170:173], v[228:231], v[8:11]
	v_mfma_f32_16x16x32_bf16 v[4:7], v[162:165], v[236:239], v[4:7]
	v_mfma_f32_16x16x32_bf16 v[0:3], v[170:173], v[236:239], v[0:3]
	v_mfma_f32_16x16x32_bf16 v[28:31], v[166:169], v[182:185], v[28:31]
	v_mfma_f32_16x16x32_bf16 v[24:27], v[174:177], v[182:185], v[24:27]
	v_mfma_f32_16x16x32_bf16 v[20:23], v[166:169], v[212:215], v[20:23]
	v_mfma_f32_16x16x32_bf16 v[16:19], v[174:177], v[212:215], v[16:19]
	v_mfma_f32_16x16x32_bf16 v[12:15], v[166:169], v[232:235], v[12:15]
	v_mfma_f32_16x16x32_bf16 v[8:11], v[174:177], v[232:235], v[8:11]
	v_mfma_f32_16x16x32_bf16 v[4:7], v[166:169], v[240:243], v[4:7]
	v_mfma_f32_16x16x32_bf16 v[0:3], v[174:177], v[240:243], v[0:3]
	s_setprio 0
	s_barrier
	s_add_i32 s73, s73, 2
	s_add_u32 s0, s0, 0x100
	s_addc_u32 s1, s1, 0
	s_add_u32 s60, s60, 0x100
	s_addc_u32 s72, s72, 0
	s_cmp_gt_u32 s73, 13
	s_cbranch_scc0 .LBB0_236

.Lgemm2_peel:
	s_add_u32 s0, s64, 0x100
	s_addc_u32 s1, s65, 0
	s_add_i32 s10, 0, 0x10000
	s_cmp_eq_u32 s45, 4
	s_cselect_b32 vcc_hi, s77, s1
	s_cselect_b32 vcc_lo, s76, s0
	s_cselect_b32 s91, s9, s41
	s_cselect_b32 s90, s34, s35
	s_add_i32 s33, 0, 0x14000
	v_add_u32_e32 v154, s10, v151
	v_add_u32_e32 v170, s33, v151
	ds_read_b128 v[128:131], v154
	ds_read_b128 v[142:145], v154 offset:1024
	ds_read_b128 v[146:149], v154 offset:2048
	ds_read_b128 v[154:157], v154 offset:3072
	ds_read_b128 v[158:161], v170
	ds_read_b128 v[162:165], v170 offset:1024
	ds_read_b128 v[166:169], v170 offset:2048
	ds_read_b128 v[170:173], v170 offset:3072
	v_lshl_add_u64 v[186:187], s[64:65], 0, v[138:139]
	s_add_i32 m0, s12, 0xc000
	ds_read_b128 v[174:177], v153
	ds_read_b128 v[178:181], v153 offset:1024
	ds_read_b128 v[182:185], v153 offset:2048
	ds_read_b128 v[208:211], v153 offset:3072
	ds_read_b128 v[212:215], v153 offset:4096
	ds_read_b128 v[228:231], v153 offset:5120
	ds_read_b128 v[232:235], v153 offset:6144
	ds_read_b128 v[236:239], v153 offset:7168
	global_load_lds_dwordx4 v[186:187], off
	v_lshl_add_u64 v[186:187], s[64:65], 0, v[140:141]
	s_add_i32 m0, s12, 0xe000
	s_nop 0
	global_load_lds_dwordx4 v[186:187], off
	s_waitcnt vmcnt(8)
	s_barrier
	s_setprio 1
	s_waitcnt lgkmcnt(7)
	v_mfma_f32_16x16x32_bf16 v[124:127], v[128:131], v[174:177], 0
	v_mfma_f32_16x16x32_bf16 v[120:123], v[146:149], v[174:177], 0
	s_waitcnt lgkmcnt(5)
	v_mfma_f32_16x16x32_bf16 v[108:111], v[128:131], v[182:185], 0
	v_mfma_f32_16x16x32_bf16 v[104:107], v[146:149], v[182:185], 0
	s_waitcnt lgkmcnt(3)
	v_mfma_f32_16x16x32_bf16 v[92:95], v[128:131], v[212:215], 0
	v_mfma_f32_16x16x32_bf16 v[88:91], v[146:149], v[212:215], 0
	s_waitcnt lgkmcnt(1)
	v_mfma_f32_16x16x32_bf16 v[76:79], v[128:131], v[232:235], 0
	v_mfma_f32_16x16x32_bf16 v[72:75], v[146:149], v[232:235], 0
	v_mfma_f32_16x16x32_bf16 v[124:127], v[142:145], v[178:181], v[124:127]
	v_mfma_f32_16x16x32_bf16 v[120:123], v[154:157], v[178:181], v[120:123]
	v_mfma_f32_16x16x32_bf16 v[108:111], v[142:145], v[208:211], v[108:111]
	v_mfma_f32_16x16x32_bf16 v[104:107], v[154:157], v[208:211], v[104:107]
	v_mfma_f32_16x16x32_bf16 v[92:95], v[142:145], v[228:231], v[92:95]
	v_mfma_f32_16x16x32_bf16 v[88:91], v[154:157], v[228:231], v[88:91]
	s_waitcnt lgkmcnt(0)
	v_mfma_f32_16x16x32_bf16 v[76:79], v[142:145], v[236:239], v[76:79]
	v_mfma_f32_16x16x32_bf16 v[72:75], v[154:157], v[236:239], v[72:75]
	s_setprio 0
	s_setprio 1
	v_mfma_f32_16x16x32_bf16 v[116:119], v[158:161], v[174:177], 0
	v_mfma_f32_16x16x32_bf16 v[112:115], v[166:169], v[174:177], 0
	v_mfma_f32_16x16x32_bf16 v[100:103], v[158:161], v[182:185], 0
	v_mfma_f32_16x16x32_bf16 v[96:99], v[166:169], v[182:185], 0
	v_mfma_f32_16x16x32_bf16 v[84:87], v[158:161], v[212:215], 0
	v_mfma_f32_16x16x32_bf16 v[80:83], v[166:169], v[212:215], 0
	v_mfma_f32_16x16x32_bf16 v[68:71], v[158:161], v[232:235], 0
	v_mfma_f32_16x16x32_bf16 v[64:67], v[166:169], v[232:235], 0
	v_mfma_f32_16x16x32_bf16 v[116:119], v[162:165], v[178:181], v[116:119]
	v_mfma_f32_16x16x32_bf16 v[112:115], v[170:173], v[178:181], v[112:115]
	v_mfma_f32_16x16x32_bf16 v[100:103], v[162:165], v[208:211], v[100:103]
	v_mfma_f32_16x16x32_bf16 v[96:99], v[170:173], v[208:211], v[96:99]
	v_mfma_f32_16x16x32_bf16 v[84:87], v[162:165], v[228:231], v[84:87]
	v_mfma_f32_16x16x32_bf16 v[80:83], v[170:173], v[228:231], v[80:83]
	v_mfma_f32_16x16x32_bf16 v[68:71], v[162:165], v[236:239], v[68:71]
	v_mfma_f32_16x16x32_bf16 v[64:67], v[170:173], v[236:239], v[64:67]
	s_setprio 0
	s_barrier
	s_add_i32 s10, s10, s11
	v_lshl_add_u64 v[186:187], s[90:91], 0, v[194:195]
	s_mov_b32 m0, s10
	ds_read_b128 v[174:177], v153 offset:16384
	ds_read_b128 v[178:181], v153 offset:17408
	ds_read_b128 v[182:185], v153 offset:18432
	ds_read_b128 v[208:211], v153 offset:19456
	ds_read_b128 v[212:215], v153 offset:20480
	ds_read_b128 v[228:231], v153 offset:21504
	ds_read_b128 v[232:235], v153 offset:22528
	ds_read_b128 v[236:239], v153 offset:23552
	global_load_lds_dwordx4 v[186:187], off
	s_add_i32 m0, s10, 0x2000
	s_add_u32 s64, s90, 0x20000
	v_lshl_add_u64 v[240:241], s[90:91], 0, v[132:133]
	s_addc_u32 s65, s91, 0
	s_add_i32 s10, s33, s11
	global_load_lds_dwordx4 v[240:241], off
	v_lshl_add_u64 v[242:243], s[64:65], 0, v[194:195]
	s_mov_b32 m0, s10
	v_lshl_add_u64 v[244:245], vcc, 0, v[134:135]
	global_load_lds_dwordx4 v[242:243], off
	v_lshl_add_u64 v[242:243], s[64:65], 0, v[132:133]
	s_add_i32 m0, s10, 0x2000
	s_nop 0
	global_load_lds_dwordx4 v[242:243], off
	v_lshl_add_u64 v[242:243], vcc, 0, v[136:137]
	s_mov_b32 m0, s12
	s_nop 0
	global_load_lds_dwordx4 v[242:243], off
	s_mov_b32 m0, s16
	s_nop 0
	global_load_lds_dwordx4 v[244:245], off
	s_waitcnt vmcnt(8)
	s_barrier
	s_setprio 1
	s_waitcnt lgkmcnt(7)
	v_mfma_f32_16x16x32_bf16 v[60:63], v[128:131], v[174:177], 0
	v_mfma_f32_16x16x32_bf16 v[56:59], v[146:149], v[174:177], 0
	s_waitcnt lgkmcnt(5)
	v_mfma_f32_16x16x32_bf16 v[44:47], v[128:131], v[182:185], 0
	v_mfma_f32_16x16x32_bf16 v[40:43], v[146:149], v[182:185], 0
	s_waitcnt lgkmcnt(3)
	v_mfma_f32_16x16x32_bf16 v[28:31], v[128:131], v[212:215], 0
	v_mfma_f32_16x16x32_bf16 v[24:27], v[146:149], v[212:215], 0
	s_waitcnt lgkmcnt(1)
	v_mfma_f32_16x16x32_bf16 v[12:15], v[128:131], v[232:235], 0
	v_mfma_f32_16x16x32_bf16 v[8:11], v[146:149], v[232:235], 0
	v_mfma_f32_16x16x32_bf16 v[60:63], v[142:145], v[178:181], v[60:63]
	v_mfma_f32_16x16x32_bf16 v[56:59], v[154:157], v[178:181], v[56:59]
	v_mfma_f32_16x16x32_bf16 v[44:47], v[142:145], v[208:211], v[44:47]
	v_mfma_f32_16x16x32_bf16 v[40:43], v[154:157], v[208:211], v[40:43]
	v_mfma_f32_16x16x32_bf16 v[28:31], v[142:145], v[228:231], v[28:31]
	v_mfma_f32_16x16x32_bf16 v[24:27], v[154:157], v[228:231], v[24:27]
	s_waitcnt lgkmcnt(0)
	v_mfma_f32_16x16x32_bf16 v[12:15], v[142:145], v[236:239], v[12:15]
	v_mfma_f32_16x16x32_bf16 v[8:11], v[154:157], v[236:239], v[8:11]
	s_setprio 0
	s_setprio 1
	v_mfma_f32_16x16x32_bf16 v[52:55], v[158:161], v[174:177], 0
	v_mfma_f32_16x16x32_bf16 v[48:51], v[166:169], v[174:177], 0
	v_mfma_f32_16x16x32_bf16 v[36:39], v[158:161], v[182:185], 0
	v_mfma_f32_16x16x32_bf16 v[32:35], v[166:169], v[182:185], 0
	v_mfma_f32_16x16x32_bf16 v[20:23], v[158:161], v[212:215], 0
	v_mfma_f32_16x16x32_bf16 v[16:19], v[166:169], v[212:215], 0
	v_mfma_f32_16x16x32_bf16 v[4:7], v[158:161], v[232:235], 0
	v_mfma_f32_16x16x32_bf16 v[0:3], v[166:169], v[232:235], 0
	v_mfma_f32_16x16x32_bf16 v[52:55], v[162:165], v[178:181], v[52:55]
	v_mfma_f32_16x16x32_bf16 v[48:51], v[170:173], v[178:181], v[48:51]
	v_mfma_f32_16x16x32_bf16 v[36:39], v[162:165], v[208:211], v[36:39]
	v_mfma_f32_16x16x32_bf16 v[32:35], v[170:173], v[208:211], v[32:35]
	v_mfma_f32_16x16x32_bf16 v[20:23], v[162:165], v[228:231], v[20:23]
	v_mfma_f32_16x16x32_bf16 v[16:19], v[170:173], v[228:231], v[16:19]
	v_mfma_f32_16x16x32_bf16 v[4:7], v[162:165], v[236:239], v[4:7]
	v_mfma_f32_16x16x32_bf16 v[0:3], v[170:173], v[236:239], v[0:3]
	s_setprio 0
	s_barrier
	s_add_i32 s10, 0, 0x18000
	s_add_i32 s33, 0, 0x1c000
	v_add_u32_e32 v154, s10, v151
	v_add_u32_e32 v170, s33, v151
	ds_read_b128 v[128:131], v154
	ds_read_b128 v[142:145], v154 offset:1024
	ds_read_b128 v[146:149], v154 offset:2048
	ds_read_b128 v[154:157], v154 offset:3072
	ds_read_b128 v[158:161], v170
	ds_read_b128 v[162:165], v170 offset:1024
	ds_read_b128 v[166:169], v170 offset:2048
	ds_read_b128 v[170:173], v170 offset:3072
	s_add_u32 s64, vcc_lo, 0x160000
	s_addc_u32 s65, vcc_hi, 0
	s_mov_b32 m0, s17
	v_lshl_add_u64 v[246:247], s[64:65], 0, v[136:137]
	ds_read_b128 v[174:177], v153 offset:32768
	ds_read_b128 v[178:181], v153 offset:33792
	ds_read_b128 v[182:185], v153 offset:34816
	ds_read_b128 v[208:211], v153 offset:35840
	ds_read_b128 v[212:215], v153 offset:36864
	ds_read_b128 v[228:231], v153 offset:37888
	ds_read_b128 v[232:235], v153 offset:38912
	ds_read_b128 v[236:239], v153 offset:39936
	global_load_lds_dwordx4 v[246:247], off
	v_lshl_add_u64 v[246:247], s[64:65], 0, v[134:135]
	s_mov_b32 m0, s18
	s_nop 0
	global_load_lds_dwordx4 v[246:247], off
	s_waitcnt vmcnt(8)
	s_barrier
	s_setprio 1
	s_waitcnt lgkmcnt(7)
	v_mfma_f32_16x16x32_bf16 v[124:127], v[128:131], v[174:177], v[124:127]
	v_mfma_f32_16x16x32_bf16 v[120:123], v[146:149], v[174:177], v[120:123]
	s_waitcnt lgkmcnt(5)
	v_mfma_f32_16x16x32_bf16 v[108:111], v[128:131], v[182:185], v[108:111]
	v_mfma_f32_16x16x32_bf16 v[104:107], v[146:149], v[182:185], v[104:107]
	s_waitcnt lgkmcnt(3)
	v_mfma_f32_16x16x32_bf16 v[92:95], v[128:131], v[212:215], v[92:95]
	v_mfma_f32_16x16x32_bf16 v[88:91], v[146:149], v[212:215], v[88:91]
	s_waitcnt lgkmcnt(1)
	v_mfma_f32_16x16x32_bf16 v[76:79], v[128:131], v[232:235], v[76:79]
	v_mfma_f32_16x16x32_bf16 v[72:75], v[146:149], v[232:235], v[72:75]
	v_mfma_f32_16x16x32_bf16 v[124:127], v[142:145], v[178:181], v[124:127]
	v_mfma_f32_16x16x32_bf16 v[120:123], v[154:157], v[178:181], v[120:123]
	v_mfma_f32_16x16x32_bf16 v[108:111], v[142:145], v[208:211], v[108:111]
	v_mfma_f32_16x16x32_bf16 v[104:107], v[154:157], v[208:211], v[104:107]
	v_mfma_f32_16x16x32_bf16 v[92:95], v[142:145], v[228:231], v[92:95]
	v_mfma_f32_16x16x32_bf16 v[88:91], v[154:157], v[228:231], v[88:91]
	s_waitcnt lgkmcnt(0)
	v_mfma_f32_16x16x32_bf16 v[76:79], v[142:145], v[236:239], v[76:79]
	v_mfma_f32_16x16x32_bf16 v[72:75], v[154:157], v[236:239], v[72:75]
	s_setprio 0
	s_setprio 1
	v_mfma_f32_16x16x32_bf16 v[116:119], v[158:161], v[174:177], v[116:119]
	v_mfma_f32_16x16x32_bf16 v[112:115], v[166:169], v[174:177], v[112:115]
	v_mfma_f32_16x16x32_bf16 v[100:103], v[158:161], v[182:185], v[100:103]
	v_mfma_f32_16x16x32_bf16 v[96:99], v[166:169], v[182:185], v[96:99]
	v_mfma_f32_16x16x32_bf16 v[84:87], v[158:161], v[212:215], v[84:87]
	v_mfma_f32_16x16x32_bf16 v[80:83], v[166:169], v[212:215], v[80:83]
	v_mfma_f32_16x16x32_bf16 v[68:71], v[158:161], v[232:235], v[68:71]
	v_mfma_f32_16x16x32_bf16 v[64:67], v[166:169], v[232:235], v[64:67]
	v_mfma_f32_16x16x32_bf16 v[116:119], v[162:165], v[178:181], v[116:119]
	v_mfma_f32_16x16x32_bf16 v[112:115], v[170:173], v[178:181], v[112:115]
	v_mfma_f32_16x16x32_bf16 v[100:103], v[162:165], v[208:211], v[100:103]
	v_mfma_f32_16x16x32_bf16 v[96:99], v[170:173], v[208:211], v[96:99]
	v_mfma_f32_16x16x32_bf16 v[84:87], v[162:165], v[228:231], v[84:87]
	v_mfma_f32_16x16x32_bf16 v[80:83], v[170:173], v[228:231], v[80:83]
	v_mfma_f32_16x16x32_bf16 v[68:71], v[162:165], v[236:239], v[68:71]
	v_mfma_f32_16x16x32_bf16 v[64:67], v[170:173], v[236:239], v[64:67]
	s_setprio 0
	s_barrier
	s_add_i32 s10, s10, s11
	v_lshl_add_u64 v[186:187], v[186:187], 0, s[48:49]
	s_mov_b32 m0, s10
	ds_read_b128 v[174:177], v153 offset:49152
	ds_read_b128 v[178:181], v153 offset:50176
	ds_read_b128 v[182:185], v153 offset:51200
	ds_read_b128 v[208:211], v153 offset:52224
	ds_read_b128 v[212:215], v153 offset:53248
	ds_read_b128 v[228:231], v153 offset:54272
	ds_read_b128 v[232:235], v153 offset:55296
	ds_read_b128 v[236:239], v153 offset:56320
	global_load_lds_dwordx4 v[186:187], off
	s_add_i32 m0, s10, 0x2000
	s_add_u32 s64, s90, 0x20080
	v_lshl_add_u64 v[186:187], v[240:241], 0, s[48:49]
	s_addc_u32 s65, s91, 0
	s_add_i32 s10, s33, s11
	global_load_lds_dwordx4 v[186:187], off
	v_lshl_add_u64 v[186:187], s[64:65], 0, v[194:195]
	s_mov_b32 m0, s10
	s_nop 0
	global_load_lds_dwordx4 v[186:187], off
	v_lshl_add_u64 v[186:187], s[64:65], 0, v[132:133]
	s_add_i32 m0, s10, 0x2000
	s_nop 0
	global_load_lds_dwordx4 v[186:187], off
	v_lshl_add_u64 v[186:187], v[242:243], 0, s[48:49]
	s_mov_b32 m0, s92
	s_nop 0
	global_load_lds_dwordx4 v[186:187], off
	v_lshl_add_u64 v[186:187], v[244:245], 0, s[48:49]
	s_mov_b32 m0, s94
	s_nop 0
	global_load_lds_dwordx4 v[186:187], off
	s_waitcnt vmcnt(8)
	s_barrier
	s_setprio 1
	s_waitcnt lgkmcnt(7)
	v_mfma_f32_16x16x32_bf16 v[60:63], v[128:131], v[174:177], v[60:63]
	v_mfma_f32_16x16x32_bf16 v[56:59], v[146:149], v[174:177], v[56:59]
	s_waitcnt lgkmcnt(5)
	v_mfma_f32_16x16x32_bf16 v[44:47], v[128:131], v[182:185], v[44:47]
	v_mfma_f32_16x16x32_bf16 v[40:43], v[146:149], v[182:185], v[40:43]
	s_waitcnt lgkmcnt(3)
	v_mfma_f32_16x16x32_bf16 v[28:31], v[128:131], v[212:215], v[28:31]
	v_mfma_f32_16x16x32_bf16 v[24:27], v[146:149], v[212:215], v[24:27]
	s_waitcnt lgkmcnt(1)
	v_mfma_f32_16x16x32_bf16 v[12:15], v[128:131], v[232:235], v[12:15]
	v_mfma_f32_16x16x32_bf16 v[8:11], v[146:149], v[232:235], v[8:11]
	v_mfma_f32_16x16x32_bf16 v[60:63], v[142:145], v[178:181], v[60:63]
	v_mfma_f32_16x16x32_bf16 v[56:59], v[154:157], v[178:181], v[56:59]
	v_mfma_f32_16x16x32_bf16 v[44:47], v[142:145], v[208:211], v[44:47]
	v_mfma_f32_16x16x32_bf16 v[40:43], v[154:157], v[208:211], v[40:43]
	v_mfma_f32_16x16x32_bf16 v[28:31], v[142:145], v[228:231], v[28:31]
	v_mfma_f32_16x16x32_bf16 v[24:27], v[154:157], v[228:231], v[24:27]
	s_waitcnt lgkmcnt(0)
	v_mfma_f32_16x16x32_bf16 v[12:15], v[142:145], v[236:239], v[12:15]
	v_mfma_f32_16x16x32_bf16 v[8:11], v[154:157], v[236:239], v[8:11]
	s_setprio 0
	s_setprio 1
	v_mfma_f32_16x16x32_bf16 v[52:55], v[158:161], v[174:177], v[52:55]
	v_mfma_f32_16x16x32_bf16 v[48:51], v[166:169], v[174:177], v[48:51]
	v_mfma_f32_16x16x32_bf16 v[36:39], v[158:161], v[182:185], v[36:39]
	v_mfma_f32_16x16x32_bf16 v[32:35], v[166:169], v[182:185], v[32:35]
	v_mfma_f32_16x16x32_bf16 v[20:23], v[158:161], v[212:215], v[20:23]
	v_mfma_f32_16x16x32_bf16 v[16:19], v[166:169], v[212:215], v[16:19]
	v_mfma_f32_16x16x32_bf16 v[4:7], v[158:161], v[232:235], v[4:7]
	v_mfma_f32_16x16x32_bf16 v[0:3], v[166:169], v[232:235], v[0:3]
	v_mfma_f32_16x16x32_bf16 v[52:55], v[162:165], v[178:181], v[52:55]
	v_mfma_f32_16x16x32_bf16 v[48:51], v[170:173], v[178:181], v[48:51]
	v_mfma_f32_16x16x32_bf16 v[36:39], v[162:165], v[208:211], v[36:39]
	v_mfma_f32_16x16x32_bf16 v[32:35], v[170:173], v[208:211], v[32:35]
	v_mfma_f32_16x16x32_bf16 v[20:23], v[162:165], v[228:231], v[20:23]
	v_mfma_f32_16x16x32_bf16 v[16:19], v[170:173], v[228:231], v[16:19]
	v_mfma_f32_16x16x32_bf16 v[4:7], v[162:165], v[236:239], v[4:7]
	v_mfma_f32_16x16x32_bf16 v[0:3], v[170:173], v[236:239], v[0:3]
	s_setprio 0
	s_barrier
	s_add_i32 s45, s45, 2
	s_add_u32 s35, s35, 0x100
	s_addc_u32 s41, s41, 0
	s_cmp_gt_u32 s45, 5
	s_mov_b64 s[64:65], s[0:1]
	s_cbranch_scc0 .LBB0_913
	s_branch .Lgemm2_exit
.LBB0_913:
	s_add_u32 s0, s64, 0x100
	s_addc_u32 s1, s65, 0
	s_add_i32 s10, 0, 0x10000
	s_cmp_eq_u32 s45, 4
	s_cselect_b32 vcc_hi, s77, s1
	s_cselect_b32 vcc_lo, s76, s0
	s_cselect_b32 s91, s9, s41
	s_cselect_b32 s90, s34, s35
	s_add_i32 s33, 0, 0x14000
	v_add_u32_e32 v154, s10, v151
	v_add_u32_e32 v170, s33, v151
	ds_read_b128 v[128:131], v154
	ds_read_b128 v[142:145], v154 offset:1024
	ds_read_b128 v[146:149], v154 offset:2048
	ds_read_b128 v[154:157], v154 offset:3072
	ds_read_b128 v[158:161], v170
	ds_read_b128 v[162:165], v170 offset:1024
	ds_read_b128 v[166:169], v170 offset:2048
	ds_read_b128 v[170:173], v170 offset:3072
	v_lshl_add_u64 v[186:187], s[64:65], 0, v[138:139]
	s_add_i32 m0, s12, 0xc000
	ds_read_b128 v[174:177], v153
	ds_read_b128 v[178:181], v153 offset:1024
	ds_read_b128 v[182:185], v153 offset:2048
	ds_read_b128 v[208:211], v153 offset:3072
	ds_read_b128 v[212:215], v153 offset:4096
	ds_read_b128 v[228:231], v153 offset:5120
	ds_read_b128 v[232:235], v153 offset:6144
	ds_read_b128 v[236:239], v153 offset:7168
	global_load_lds_dwordx4 v[186:187], off
	v_lshl_add_u64 v[186:187], s[64:65], 0, v[140:141]
	s_add_i32 m0, s12, 0xe000
	s_nop 0
	global_load_lds_dwordx4 v[186:187], off
	s_waitcnt vmcnt(8)
	s_barrier
	s_setprio 1
	s_waitcnt lgkmcnt(7)
	v_mfma_f32_16x16x32_bf16 v[124:127], v[128:131], v[174:177], v[124:127]
	v_mfma_f32_16x16x32_bf16 v[120:123], v[146:149], v[174:177], v[120:123]
	s_waitcnt lgkmcnt(5)
	v_mfma_f32_16x16x32_bf16 v[108:111], v[128:131], v[182:185], v[108:111]
	v_mfma_f32_16x16x32_bf16 v[104:107], v[146:149], v[182:185], v[104:107]
	s_waitcnt lgkmcnt(3)
	v_mfma_f32_16x16x32_bf16 v[92:95], v[128:131], v[212:215], v[92:95]
	v_mfma_f32_16x16x32_bf16 v[88:91], v[146:149], v[212:215], v[88:91]
	s_waitcnt lgkmcnt(1)
	v_mfma_f32_16x16x32_bf16 v[76:79], v[128:131], v[232:235], v[76:79]
	v_mfma_f32_16x16x32_bf16 v[72:75], v[146:149], v[232:235], v[72:75]
	v_mfma_f32_16x16x32_bf16 v[124:127], v[142:145], v[178:181], v[124:127]
	v_mfma_f32_16x16x32_bf16 v[120:123], v[154:157], v[178:181], v[120:123]
	v_mfma_f32_16x16x32_bf16 v[108:111], v[142:145], v[208:211], v[108:111]
	v_mfma_f32_16x16x32_bf16 v[104:107], v[154:157], v[208:211], v[104:107]
	v_mfma_f32_16x16x32_bf16 v[92:95], v[142:145], v[228:231], v[92:95]
	v_mfma_f32_16x16x32_bf16 v[88:91], v[154:157], v[228:231], v[88:91]
	s_waitcnt lgkmcnt(0)
	v_mfma_f32_16x16x32_bf16 v[76:79], v[142:145], v[236:239], v[76:79]
	v_mfma_f32_16x16x32_bf16 v[72:75], v[154:157], v[236:239], v[72:75]
	s_setprio 0
	s_setprio 1
	v_mfma_f32_16x16x32_bf16 v[116:119], v[158:161], v[174:177], v[116:119]
	v_mfma_f32_16x16x32_bf16 v[112:115], v[166:169], v[174:177], v[112:115]
	v_mfma_f32_16x16x32_bf16 v[100:103], v[158:161], v[182:185], v[100:103]
	v_mfma_f32_16x16x32_bf16 v[96:99], v[166:169], v[182:185], v[96:99]
	v_mfma_f32_16x16x32_bf16 v[84:87], v[158:161], v[212:215], v[84:87]
	v_mfma_f32_16x16x32_bf16 v[80:83], v[166:169], v[212:215], v[80:83]
	v_mfma_f32_16x16x32_bf16 v[68:71], v[158:161], v[232:235], v[68:71]
	v_mfma_f32_16x16x32_bf16 v[64:67], v[166:169], v[232:235], v[64:67]
	v_mfma_f32_16x16x32_bf16 v[116:119], v[162:165], v[178:181], v[116:119]
	v_mfma_f32_16x16x32_bf16 v[112:115], v[170:173], v[178:181], v[112:115]
	v_mfma_f32_16x16x32_bf16 v[100:103], v[162:165], v[208:211], v[100:103]
	v_mfma_f32_16x16x32_bf16 v[96:99], v[170:173], v[208:211], v[96:99]
	v_mfma_f32_16x16x32_bf16 v[84:87], v[162:165], v[228:231], v[84:87]
	v_mfma_f32_16x16x32_bf16 v[80:83], v[170:173], v[228:231], v[80:83]
	v_mfma_f32_16x16x32_bf16 v[68:71], v[162:165], v[236:239], v[68:71]
	v_mfma_f32_16x16x32_bf16 v[64:67], v[170:173], v[236:239], v[64:67]
	s_setprio 0
	s_barrier
	s_add_i32 s10, s10, s11
	v_lshl_add_u64 v[186:187], s[90:91], 0, v[194:195]
	s_mov_b32 m0, s10
	ds_read_b128 v[174:177], v153 offset:16384
	ds_read_b128 v[178:181], v153 offset:17408
	ds_read_b128 v[182:185], v153 offset:18432
	ds_read_b128 v[208:211], v153 offset:19456
	ds_read_b128 v[212:215], v153 offset:20480
	ds_read_b128 v[228:231], v153 offset:21504
	ds_read_b128 v[232:235], v153 offset:22528
	ds_read_b128 v[236:239], v153 offset:23552
	global_load_lds_dwordx4 v[186:187], off
	s_add_i32 m0, s10, 0x2000
	s_add_u32 s64, s90, 0x20000
	v_lshl_add_u64 v[240:241], s[90:91], 0, v[132:133]
	s_addc_u32 s65, s91, 0
	s_add_i32 s10, s33, s11
	global_load_lds_dwordx4 v[240:241], off
	v_lshl_add_u64 v[242:243], s[64:65], 0, v[194:195]
	s_mov_b32 m0, s10
	v_lshl_add_u64 v[244:245], vcc, 0, v[134:135]
	global_load_lds_dwordx4 v[242:243], off
	v_lshl_add_u64 v[242:243], s[64:65], 0, v[132:133]
	s_add_i32 m0, s10, 0x2000
	s_nop 0
	global_load_lds_dwordx4 v[242:243], off
	v_lshl_add_u64 v[242:243], vcc, 0, v[136:137]
	s_mov_b32 m0, s12
	s_nop 0
	global_load_lds_dwordx4 v[242:243], off
	s_mov_b32 m0, s16
	s_nop 0
	global_load_lds_dwordx4 v[244:245], off
	s_waitcnt vmcnt(8)
	s_barrier
	s_setprio 1
	s_waitcnt lgkmcnt(7)
	v_mfma_f32_16x16x32_bf16 v[60:63], v[128:131], v[174:177], v[60:63]
	v_mfma_f32_16x16x32_bf16 v[56:59], v[146:149], v[174:177], v[56:59]
	s_waitcnt lgkmcnt(5)
	v_mfma_f32_16x16x32_bf16 v[44:47], v[128:131], v[182:185], v[44:47]
	v_mfma_f32_16x16x32_bf16 v[40:43], v[146:149], v[182:185], v[40:43]
	s_waitcnt lgkmcnt(3)
	v_mfma_f32_16x16x32_bf16 v[28:31], v[128:131], v[212:215], v[28:31]
	v_mfma_f32_16x16x32_bf16 v[24:27], v[146:149], v[212:215], v[24:27]
	s_waitcnt lgkmcnt(1)
	v_mfma_f32_16x16x32_bf16 v[12:15], v[128:131], v[232:235], v[12:15]
	v_mfma_f32_16x16x32_bf16 v[8:11], v[146:149], v[232:235], v[8:11]
	v_mfma_f32_16x16x32_bf16 v[60:63], v[142:145], v[178:181], v[60:63]
	v_mfma_f32_16x16x32_bf16 v[56:59], v[154:157], v[178:181], v[56:59]
	v_mfma_f32_16x16x32_bf16 v[44:47], v[142:145], v[208:211], v[44:47]
	v_mfma_f32_16x16x32_bf16 v[40:43], v[154:157], v[208:211], v[40:43]
	v_mfma_f32_16x16x32_bf16 v[28:31], v[142:145], v[228:231], v[28:31]
	v_mfma_f32_16x16x32_bf16 v[24:27], v[154:157], v[228:231], v[24:27]
	s_waitcnt lgkmcnt(0)
	v_mfma_f32_16x16x32_bf16 v[12:15], v[142:145], v[236:239], v[12:15]
	v_mfma_f32_16x16x32_bf16 v[8:11], v[154:157], v[236:239], v[8:11]
	s_setprio 0
	s_setprio 1
	v_mfma_f32_16x16x32_bf16 v[52:55], v[158:161], v[174:177], v[52:55]
	v_mfma_f32_16x16x32_bf16 v[48:51], v[166:169], v[174:177], v[48:51]
	v_mfma_f32_16x16x32_bf16 v[36:39], v[158:161], v[182:185], v[36:39]
	v_mfma_f32_16x16x32_bf16 v[32:35], v[166:169], v[182:185], v[32:35]
	v_mfma_f32_16x16x32_bf16 v[20:23], v[158:161], v[212:215], v[20:23]
	v_mfma_f32_16x16x32_bf16 v[16:19], v[166:169], v[212:215], v[16:19]
	v_mfma_f32_16x16x32_bf16 v[4:7], v[158:161], v[232:235], v[4:7]
	v_mfma_f32_16x16x32_bf16 v[0:3], v[166:169], v[232:235], v[0:3]
	v_mfma_f32_16x16x32_bf16 v[52:55], v[162:165], v[178:181], v[52:55]
	v_mfma_f32_16x16x32_bf16 v[48:51], v[170:173], v[178:181], v[48:51]
	v_mfma_f32_16x16x32_bf16 v[36:39], v[162:165], v[208:211], v[36:39]
	v_mfma_f32_16x16x32_bf16 v[32:35], v[170:173], v[208:211], v[32:35]
	v_mfma_f32_16x16x32_bf16 v[20:23], v[162:165], v[228:231], v[20:23]
	v_mfma_f32_16x16x32_bf16 v[16:19], v[170:173], v[228:231], v[16:19]
	v_mfma_f32_16x16x32_bf16 v[4:7], v[162:165], v[236:239], v[4:7]
	v_mfma_f32_16x16x32_bf16 v[0:3], v[170:173], v[236:239], v[0:3]
	s_setprio 0
	s_barrier
	s_add_i32 s10, 0, 0x18000
	s_add_i32 s33, 0, 0x1c000
	v_add_u32_e32 v154, s10, v151
	v_add_u32_e32 v170, s33, v151
	ds_read_b128 v[128:131], v154
	ds_read_b128 v[142:145], v154 offset:1024
	ds_read_b128 v[146:149], v154 offset:2048
	ds_read_b128 v[154:157], v154 offset:3072
	ds_read_b128 v[158:161], v170
	ds_read_b128 v[162:165], v170 offset:1024
	ds_read_b128 v[166:169], v170 offset:2048
	ds_read_b128 v[170:173], v170 offset:3072
	s_add_u32 s64, vcc_lo, 0x160000
	s_addc_u32 s65, vcc_hi, 0
	s_mov_b32 m0, s17
	v_lshl_add_u64 v[246:247], s[64:65], 0, v[136:137]
	ds_read_b128 v[174:177], v153 offset:32768
	ds_read_b128 v[178:181], v153 offset:33792
	ds_read_b128 v[182:185], v153 offset:34816
	ds_read_b128 v[208:211], v153 offset:35840
	ds_read_b128 v[212:215], v153 offset:36864
	ds_read_b128 v[228:231], v153 offset:37888
	ds_read_b128 v[232:235], v153 offset:38912
	ds_read_b128 v[236:239], v153 offset:39936
	global_load_lds_dwordx4 v[246:247], off
	v_lshl_add_u64 v[246:247], s[64:65], 0, v[134:135]
	s_mov_b32 m0, s18
	s_nop 0
	global_load_lds_dwordx4 v[246:247], off
	s_waitcnt vmcnt(8)
	s_barrier
	s_setprio 1
	s_waitcnt lgkmcnt(7)
	v_mfma_f32_16x16x32_bf16 v[124:127], v[128:131], v[174:177], v[124:127]
	v_mfma_f32_16x16x32_bf16 v[120:123], v[146:149], v[174:177], v[120:123]
	s_waitcnt lgkmcnt(5)
	v_mfma_f32_16x16x32_bf16 v[108:111], v[128:131], v[182:185], v[108:111]
	v_mfma_f32_16x16x32_bf16 v[104:107], v[146:149], v[182:185], v[104:107]
	s_waitcnt lgkmcnt(3)
	v_mfma_f32_16x16x32_bf16 v[92:95], v[128:131], v[212:215], v[92:95]
	v_mfma_f32_16x16x32_bf16 v[88:91], v[146:149], v[212:215], v[88:91]
	s_waitcnt lgkmcnt(1)
	v_mfma_f32_16x16x32_bf16 v[76:79], v[128:131], v[232:235], v[76:79]
	v_mfma_f32_16x16x32_bf16 v[72:75], v[146:149], v[232:235], v[72:75]
	v_mfma_f32_16x16x32_bf16 v[124:127], v[142:145], v[178:181], v[124:127]
	v_mfma_f32_16x16x32_bf16 v[120:123], v[154:157], v[178:181], v[120:123]
	v_mfma_f32_16x16x32_bf16 v[108:111], v[142:145], v[208:211], v[108:111]
	v_mfma_f32_16x16x32_bf16 v[104:107], v[154:157], v[208:211], v[104:107]
	v_mfma_f32_16x16x32_bf16 v[92:95], v[142:145], v[228:231], v[92:95]
	v_mfma_f32_16x16x32_bf16 v[88:91], v[154:157], v[228:231], v[88:91]
	s_waitcnt lgkmcnt(0)
	v_mfma_f32_16x16x32_bf16 v[76:79], v[142:145], v[236:239], v[76:79]
	v_mfma_f32_16x16x32_bf16 v[72:75], v[154:157], v[236:239], v[72:75]
	s_setprio 0
	s_setprio 1
	v_mfma_f32_16x16x32_bf16 v[116:119], v[158:161], v[174:177], v[116:119]
	v_mfma_f32_16x16x32_bf16 v[112:115], v[166:169], v[174:177], v[112:115]
	v_mfma_f32_16x16x32_bf16 v[100:103], v[158:161], v[182:185], v[100:103]
	v_mfma_f32_16x16x32_bf16 v[96:99], v[166:169], v[182:185], v[96:99]
	v_mfma_f32_16x16x32_bf16 v[84:87], v[158:161], v[212:215], v[84:87]
	v_mfma_f32_16x16x32_bf16 v[80:83], v[166:169], v[212:215], v[80:83]
	v_mfma_f32_16x16x32_bf16 v[68:71], v[158:161], v[232:235], v[68:71]
	v_mfma_f32_16x16x32_bf16 v[64:67], v[166:169], v[232:235], v[64:67]
	v_mfma_f32_16x16x32_bf16 v[116:119], v[162:165], v[178:181], v[116:119]
	v_mfma_f32_16x16x32_bf16 v[112:115], v[170:173], v[178:181], v[112:115]
	v_mfma_f32_16x16x32_bf16 v[100:103], v[162:165], v[208:211], v[100:103]
	v_mfma_f32_16x16x32_bf16 v[96:99], v[170:173], v[208:211], v[96:99]
	v_mfma_f32_16x16x32_bf16 v[84:87], v[162:165], v[228:231], v[84:87]
	v_mfma_f32_16x16x32_bf16 v[80:83], v[170:173], v[228:231], v[80:83]
	v_mfma_f32_16x16x32_bf16 v[68:71], v[162:165], v[236:239], v[68:71]
	v_mfma_f32_16x16x32_bf16 v[64:67], v[170:173], v[236:239], v[64:67]
	s_setprio 0
	s_barrier
	s_add_i32 s10, s10, s11
	v_lshl_add_u64 v[186:187], v[186:187], 0, s[48:49]
	s_mov_b32 m0, s10
	ds_read_b128 v[174:177], v153 offset:49152
	ds_read_b128 v[178:181], v153 offset:50176
	ds_read_b128 v[182:185], v153 offset:51200
	ds_read_b128 v[208:211], v153 offset:52224
	ds_read_b128 v[212:215], v153 offset:53248
	ds_read_b128 v[228:231], v153 offset:54272
	ds_read_b128 v[232:235], v153 offset:55296
	ds_read_b128 v[236:239], v153 offset:56320
	global_load_lds_dwordx4 v[186:187], off
	s_add_i32 m0, s10, 0x2000
	s_add_u32 s64, s90, 0x20080
	v_lshl_add_u64 v[186:187], v[240:241], 0, s[48:49]
	s_addc_u32 s65, s91, 0
	s_add_i32 s10, s33, s11
	global_load_lds_dwordx4 v[186:187], off
	v_lshl_add_u64 v[186:187], s[64:65], 0, v[194:195]
	s_mov_b32 m0, s10
	s_nop 0
	global_load_lds_dwordx4 v[186:187], off
	v_lshl_add_u64 v[186:187], s[64:65], 0, v[132:133]
	s_add_i32 m0, s10, 0x2000
	s_nop 0
	global_load_lds_dwordx4 v[186:187], off
	v_lshl_add_u64 v[186:187], v[242:243], 0, s[48:49]
	s_mov_b32 m0, s92
	s_nop 0
	global_load_lds_dwordx4 v[186:187], off
	v_lshl_add_u64 v[186:187], v[244:245], 0, s[48:49]
	s_mov_b32 m0, s94
	s_nop 0
	global_load_lds_dwordx4 v[186:187], off
	s_waitcnt vmcnt(8)
	s_barrier
	s_setprio 1
	s_waitcnt lgkmcnt(7)
	v_mfma_f32_16x16x32_bf16 v[60:63], v[128:131], v[174:177], v[60:63]
	v_mfma_f32_16x16x32_bf16 v[56:59], v[146:149], v[174:177], v[56:59]
	s_waitcnt lgkmcnt(5)
	v_mfma_f32_16x16x32_bf16 v[44:47], v[128:131], v[182:185], v[44:47]
	v_mfma_f32_16x16x32_bf16 v[40:43], v[146:149], v[182:185], v[40:43]
	s_waitcnt lgkmcnt(3)
	v_mfma_f32_16x16x32_bf16 v[28:31], v[128:131], v[212:215], v[28:31]
	v_mfma_f32_16x16x32_bf16 v[24:27], v[146:149], v[212:215], v[24:27]
	s_waitcnt lgkmcnt(1)
	v_mfma_f32_16x16x32_bf16 v[12:15], v[128:131], v[232:235], v[12:15]
	v_mfma_f32_16x16x32_bf16 v[8:11], v[146:149], v[232:235], v[8:11]
	v_mfma_f32_16x16x32_bf16 v[60:63], v[142:145], v[178:181], v[60:63]
	v_mfma_f32_16x16x32_bf16 v[56:59], v[154:157], v[178:181], v[56:59]
	v_mfma_f32_16x16x32_bf16 v[44:47], v[142:145], v[208:211], v[44:47]
	v_mfma_f32_16x16x32_bf16 v[40:43], v[154:157], v[208:211], v[40:43]
	v_mfma_f32_16x16x32_bf16 v[28:31], v[142:145], v[228:231], v[28:31]
	v_mfma_f32_16x16x32_bf16 v[24:27], v[154:157], v[228:231], v[24:27]
	s_waitcnt lgkmcnt(0)
	v_mfma_f32_16x16x32_bf16 v[12:15], v[142:145], v[236:239], v[12:15]
	v_mfma_f32_16x16x32_bf16 v[8:11], v[154:157], v[236:239], v[8:11]
	s_setprio 0
	s_setprio 1
	v_mfma_f32_16x16x32_bf16 v[52:55], v[158:161], v[174:177], v[52:55]
	v_mfma_f32_16x16x32_bf16 v[48:51], v[166:169], v[174:177], v[48:51]
	v_mfma_f32_16x16x32_bf16 v[36:39], v[158:161], v[182:185], v[36:39]
	v_mfma_f32_16x16x32_bf16 v[32:35], v[166:169], v[182:185], v[32:35]
	v_mfma_f32_16x16x32_bf16 v[20:23], v[158:161], v[212:215], v[20:23]
	v_mfma_f32_16x16x32_bf16 v[16:19], v[166:169], v[212:215], v[16:19]
	v_mfma_f32_16x16x32_bf16 v[4:7], v[158:161], v[232:235], v[4:7]
	v_mfma_f32_16x16x32_bf16 v[0:3], v[166:169], v[232:235], v[0:3]
	v_mfma_f32_16x16x32_bf16 v[52:55], v[162:165], v[178:181], v[52:55]
	v_mfma_f32_16x16x32_bf16 v[48:51], v[170:173], v[178:181], v[48:51]
	v_mfma_f32_16x16x32_bf16 v[36:39], v[162:165], v[208:211], v[36:39]
	v_mfma_f32_16x16x32_bf16 v[32:35], v[170:173], v[208:211], v[32:35]
	v_mfma_f32_16x16x32_bf16 v[20:23], v[162:165], v[228:231], v[20:23]
	v_mfma_f32_16x16x32_bf16 v[16:19], v[170:173], v[228:231], v[16:19]
	v_mfma_f32_16x16x32_bf16 v[4:7], v[162:165], v[236:239], v[4:7]
	v_mfma_f32_16x16x32_bf16 v[0:3], v[170:173], v[236:239], v[0:3]
	s_setprio 0
	s_barrier
	s_add_i32 s45, s45, 2
	s_add_u32 s35, s35, 0x100
	s_addc_u32 s41, s41, 0
	s_cmp_gt_u32 s45, 5
	s_mov_b64 s[64:65], s[0:1]
	s_cbranch_scc0 .LBB0_913

.Lgemm3_peel:
	s_add_u32 s0, s90, 0x100
	s_addc_u32 s1, s91, 0
	s_add_i32 s10, 0, 0x10000
	s_cmp_eq_u32 s78, 28
	s_cselect_b32 vcc_hi, s75, s1
	s_cselect_b32 vcc_lo, s74, s0
	s_cselect_b32 s47, s9, s73
	s_cselect_b32 s46, s34, s35
	s_add_i32 s33, 0, 0x14000
	v_add_u32_e32 v154, s10, v144
	v_add_u32_e32 v170, s33, v144
	ds_read_b128 v[140:143], v154
	ds_read_b128 v[146:149], v154 offset:1024
	ds_read_b128 v[150:153], v154 offset:2048
	ds_read_b128 v[154:157], v154 offset:3072
	ds_read_b128 v[158:161], v170
	ds_read_b128 v[162:165], v170 offset:1024
	ds_read_b128 v[166:169], v170 offset:2048
	ds_read_b128 v[170:173], v170 offset:3072
	v_lshl_add_u64 v[186:187], s[90:91], 0, v[136:137]
	s_add_i32 m0, s11, 0xc000
	ds_read_b128 v[174:177], v145
	ds_read_b128 v[178:181], v145 offset:1024
	ds_read_b128 v[182:185], v145 offset:2048
	ds_read_b128 v[208:211], v145 offset:3072
	ds_read_b128 v[212:215], v145 offset:4096
	ds_read_b128 v[228:231], v145 offset:5120
	ds_read_b128 v[232:235], v145 offset:6144
	ds_read_b128 v[236:239], v145 offset:7168
	global_load_lds_dwordx4 v[186:187], off
	v_lshl_add_u64 v[186:187], s[90:91], 0, v[138:139]
	s_add_i32 m0, s11, 0xe000
	s_nop 0
	global_load_lds_dwordx4 v[186:187], off
	s_waitcnt vmcnt(8)
	s_barrier
	s_setprio 1
	s_waitcnt lgkmcnt(7)
	v_mfma_f32_16x16x32_bf16 v[124:127], v[140:143], v[174:177], 0
	v_mfma_f32_16x16x32_bf16 v[120:123], v[150:153], v[174:177], 0
	s_waitcnt lgkmcnt(5)
	v_mfma_f32_16x16x32_bf16 v[108:111], v[140:143], v[182:185], 0
	v_mfma_f32_16x16x32_bf16 v[104:107], v[150:153], v[182:185], 0
	s_waitcnt lgkmcnt(3)
	v_mfma_f32_16x16x32_bf16 v[92:95], v[140:143], v[212:215], 0
	v_mfma_f32_16x16x32_bf16 v[88:91], v[150:153], v[212:215], 0
	s_waitcnt lgkmcnt(1)
	v_mfma_f32_16x16x32_bf16 v[76:79], v[140:143], v[232:235], 0
	v_mfma_f32_16x16x32_bf16 v[72:75], v[150:153], v[232:235], 0
	v_mfma_f32_16x16x32_bf16 v[124:127], v[146:149], v[178:181], v[124:127]
	v_mfma_f32_16x16x32_bf16 v[120:123], v[154:157], v[178:181], v[120:123]
	v_mfma_f32_16x16x32_bf16 v[108:111], v[146:149], v[208:211], v[108:111]
	v_mfma_f32_16x16x32_bf16 v[104:107], v[154:157], v[208:211], v[104:107]
	v_mfma_f32_16x16x32_bf16 v[92:95], v[146:149], v[228:231], v[92:95]
	v_mfma_f32_16x16x32_bf16 v[88:91], v[154:157], v[228:231], v[88:91]
	s_waitcnt lgkmcnt(0)
	v_mfma_f32_16x16x32_bf16 v[76:79], v[146:149], v[236:239], v[76:79]
	v_mfma_f32_16x16x32_bf16 v[72:75], v[154:157], v[236:239], v[72:75]
	s_setprio 0
	s_setprio 1
	v_mfma_f32_16x16x32_bf16 v[116:119], v[158:161], v[174:177], 0
	v_mfma_f32_16x16x32_bf16 v[112:115], v[166:169], v[174:177], 0
	v_mfma_f32_16x16x32_bf16 v[100:103], v[158:161], v[182:185], 0
	v_mfma_f32_16x16x32_bf16 v[96:99], v[166:169], v[182:185], 0
	v_mfma_f32_16x16x32_bf16 v[84:87], v[158:161], v[212:215], 0
	v_mfma_f32_16x16x32_bf16 v[80:83], v[166:169], v[212:215], 0
	v_mfma_f32_16x16x32_bf16 v[68:71], v[158:161], v[232:235], 0
	v_mfma_f32_16x16x32_bf16 v[64:67], v[166:169], v[232:235], 0
	v_mfma_f32_16x16x32_bf16 v[116:119], v[162:165], v[178:181], v[116:119]
	v_mfma_f32_16x16x32_bf16 v[112:115], v[170:173], v[178:181], v[112:115]
	v_mfma_f32_16x16x32_bf16 v[100:103], v[162:165], v[208:211], v[100:103]
	v_mfma_f32_16x16x32_bf16 v[96:99], v[170:173], v[208:211], v[96:99]
	v_mfma_f32_16x16x32_bf16 v[84:87], v[162:165], v[228:231], v[84:87]
	v_mfma_f32_16x16x32_bf16 v[80:83], v[170:173], v[228:231], v[80:83]
	v_mfma_f32_16x16x32_bf16 v[68:71], v[162:165], v[236:239], v[68:71]
	v_mfma_f32_16x16x32_bf16 v[64:67], v[170:173], v[236:239], v[64:67]
	s_setprio 0
	s_barrier
	s_add_i32 s10, s10, s3
	v_lshl_add_u64 v[186:187], s[46:47], 0, v[194:195]
	s_mov_b32 m0, s10
	ds_read_b128 v[174:177], v145 offset:16384
	ds_read_b128 v[178:181], v145 offset:17408
	ds_read_b128 v[182:185], v145 offset:18432
	ds_read_b128 v[208:211], v145 offset:19456
	ds_read_b128 v[212:215], v145 offset:20480
	ds_read_b128 v[228:231], v145 offset:21504
	ds_read_b128 v[232:235], v145 offset:22528
	ds_read_b128 v[236:239], v145 offset:23552
	global_load_lds_dwordx4 v[186:187], off
	s_add_i32 m0, s10, 0x2000
	s_add_u32 s90, s46, 0x80000
	v_lshl_add_u64 v[240:241], s[46:47], 0, v[128:129]
	s_addc_u32 s91, s47, 0
	s_add_i32 s10, s33, s3
	global_load_lds_dwordx4 v[240:241], off
	v_lshl_add_u64 v[242:243], s[90:91], 0, v[194:195]
	s_mov_b32 m0, s10
	v_lshl_add_u64 v[244:245], vcc, 0, v[130:131]
	global_load_lds_dwordx4 v[242:243], off
	v_lshl_add_u64 v[242:243], s[90:91], 0, v[128:129]
	s_add_i32 m0, s10, 0x2000
	s_nop 0
	global_load_lds_dwordx4 v[242:243], off
	v_lshl_add_u64 v[242:243], vcc, 0, v[132:133]
	s_mov_b32 m0, s11
	s_nop 0
	global_load_lds_dwordx4 v[242:243], off
	s_mov_b32 m0, s12
	s_nop 0
	global_load_lds_dwordx4 v[244:245], off
	s_waitcnt vmcnt(8)
	s_barrier
	s_setprio 1
	s_waitcnt lgkmcnt(7)
	v_mfma_f32_16x16x32_bf16 v[60:63], v[140:143], v[174:177], 0
	v_mfma_f32_16x16x32_bf16 v[56:59], v[150:153], v[174:177], 0
	s_waitcnt lgkmcnt(5)
	v_mfma_f32_16x16x32_bf16 v[44:47], v[140:143], v[182:185], 0
	v_mfma_f32_16x16x32_bf16 v[40:43], v[150:153], v[182:185], 0
	s_waitcnt lgkmcnt(3)
	v_mfma_f32_16x16x32_bf16 v[28:31], v[140:143], v[212:215], 0
	v_mfma_f32_16x16x32_bf16 v[24:27], v[150:153], v[212:215], 0
	s_waitcnt lgkmcnt(1)
	v_mfma_f32_16x16x32_bf16 v[12:15], v[140:143], v[232:235], 0
	v_mfma_f32_16x16x32_bf16 v[8:11], v[150:153], v[232:235], 0
	v_mfma_f32_16x16x32_bf16 v[60:63], v[146:149], v[178:181], v[60:63]
	v_mfma_f32_16x16x32_bf16 v[56:59], v[154:157], v[178:181], v[56:59]
	v_mfma_f32_16x16x32_bf16 v[44:47], v[146:149], v[208:211], v[44:47]
	v_mfma_f32_16x16x32_bf16 v[40:43], v[154:157], v[208:211], v[40:43]
	v_mfma_f32_16x16x32_bf16 v[28:31], v[146:149], v[228:231], v[28:31]
	v_mfma_f32_16x16x32_bf16 v[24:27], v[154:157], v[228:231], v[24:27]
	s_waitcnt lgkmcnt(0)
	v_mfma_f32_16x16x32_bf16 v[12:15], v[146:149], v[236:239], v[12:15]
	v_mfma_f32_16x16x32_bf16 v[8:11], v[154:157], v[236:239], v[8:11]
	s_setprio 0
	s_setprio 1
	v_mfma_f32_16x16x32_bf16 v[52:55], v[158:161], v[174:177], 0
	v_mfma_f32_16x16x32_bf16 v[48:51], v[166:169], v[174:177], 0
	v_mfma_f32_16x16x32_bf16 v[36:39], v[158:161], v[182:185], 0
	v_mfma_f32_16x16x32_bf16 v[32:35], v[166:169], v[182:185], 0
	v_mfma_f32_16x16x32_bf16 v[20:23], v[158:161], v[212:215], 0
	v_mfma_f32_16x16x32_bf16 v[16:19], v[166:169], v[212:215], 0
	v_mfma_f32_16x16x32_bf16 v[4:7], v[158:161], v[232:235], 0
	v_mfma_f32_16x16x32_bf16 v[0:3], v[166:169], v[232:235], 0
	v_mfma_f32_16x16x32_bf16 v[52:55], v[162:165], v[178:181], v[52:55]
	v_mfma_f32_16x16x32_bf16 v[48:51], v[170:173], v[178:181], v[48:51]
	v_mfma_f32_16x16x32_bf16 v[36:39], v[162:165], v[208:211], v[36:39]
	v_mfma_f32_16x16x32_bf16 v[32:35], v[170:173], v[208:211], v[32:35]
	v_mfma_f32_16x16x32_bf16 v[20:23], v[162:165], v[228:231], v[20:23]
	v_mfma_f32_16x16x32_bf16 v[16:19], v[170:173], v[228:231], v[16:19]
	v_mfma_f32_16x16x32_bf16 v[4:7], v[162:165], v[236:239], v[4:7]
	v_mfma_f32_16x16x32_bf16 v[0:3], v[170:173], v[236:239], v[0:3]
	s_setprio 0
	s_barrier
	s_add_i32 s10, 0, 0x18000
	s_add_i32 s33, 0, 0x1c000
	v_add_u32_e32 v154, s10, v144
	v_add_u32_e32 v170, s33, v144
	ds_read_b128 v[140:143], v154
	ds_read_b128 v[146:149], v154 offset:1024
	ds_read_b128 v[150:153], v154 offset:2048
	ds_read_b128 v[154:157], v154 offset:3072
	ds_read_b128 v[158:161], v170
	ds_read_b128 v[162:165], v170 offset:1024
	ds_read_b128 v[166:169], v170 offset:2048
	ds_read_b128 v[170:173], v170 offset:3072
	s_add_u32 s90, vcc_lo, 0x160000
	s_addc_u32 s91, vcc_hi, 0
	s_mov_b32 m0, s16
	v_lshl_add_u64 v[246:247], s[90:91], 0, v[132:133]
	ds_read_b128 v[174:177], v145 offset:32768
	ds_read_b128 v[178:181], v145 offset:33792
	ds_read_b128 v[182:185], v145 offset:34816
	ds_read_b128 v[208:211], v145 offset:35840
	ds_read_b128 v[212:215], v145 offset:36864
	ds_read_b128 v[228:231], v145 offset:37888
	ds_read_b128 v[232:235], v145 offset:38912
	ds_read_b128 v[236:239], v145 offset:39936
	global_load_lds_dwordx4 v[246:247], off
	v_lshl_add_u64 v[246:247], s[90:91], 0, v[130:131]
	s_mov_b32 m0, s17
	s_nop 0
	global_load_lds_dwordx4 v[246:247], off
	s_waitcnt vmcnt(8)
	s_barrier
	s_setprio 1
	s_waitcnt lgkmcnt(7)
	v_mfma_f32_16x16x32_bf16 v[124:127], v[140:143], v[174:177], v[124:127]
	v_mfma_f32_16x16x32_bf16 v[120:123], v[150:153], v[174:177], v[120:123]
	s_waitcnt lgkmcnt(5)
	v_mfma_f32_16x16x32_bf16 v[108:111], v[140:143], v[182:185], v[108:111]
	v_mfma_f32_16x16x32_bf16 v[104:107], v[150:153], v[182:185], v[104:107]
	s_waitcnt lgkmcnt(3)
	v_mfma_f32_16x16x32_bf16 v[92:95], v[140:143], v[212:215], v[92:95]
	v_mfma_f32_16x16x32_bf16 v[88:91], v[150:153], v[212:215], v[88:91]
	s_waitcnt lgkmcnt(1)
	v_mfma_f32_16x16x32_bf16 v[76:79], v[140:143], v[232:235], v[76:79]
	v_mfma_f32_16x16x32_bf16 v[72:75], v[150:153], v[232:235], v[72:75]
	v_mfma_f32_16x16x32_bf16 v[124:127], v[146:149], v[178:181], v[124:127]
	v_mfma_f32_16x16x32_bf16 v[120:123], v[154:157], v[178:181], v[120:123]
	v_mfma_f32_16x16x32_bf16 v[108:111], v[146:149], v[208:211], v[108:111]
	v_mfma_f32_16x16x32_bf16 v[104:107], v[154:157], v[208:211], v[104:107]
	v_mfma_f32_16x16x32_bf16 v[92:95], v[146:149], v[228:231], v[92:95]
	v_mfma_f32_16x16x32_bf16 v[88:91], v[154:157], v[228:231], v[88:91]
	s_waitcnt lgkmcnt(0)
	v_mfma_f32_16x16x32_bf16 v[76:79], v[146:149], v[236:239], v[76:79]
	v_mfma_f32_16x16x32_bf16 v[72:75], v[154:157], v[236:239], v[72:75]
	s_setprio 0
	s_setprio 1
	v_mfma_f32_16x16x32_bf16 v[116:119], v[158:161], v[174:177], v[116:119]
	v_mfma_f32_16x16x32_bf16 v[112:115], v[166:169], v[174:177], v[112:115]
	v_mfma_f32_16x16x32_bf16 v[100:103], v[158:161], v[182:185], v[100:103]
	v_mfma_f32_16x16x32_bf16 v[96:99], v[166:169], v[182:185], v[96:99]
	v_mfma_f32_16x16x32_bf16 v[84:87], v[158:161], v[212:215], v[84:87]
	v_mfma_f32_16x16x32_bf16 v[80:83], v[166:169], v[212:215], v[80:83]
	v_mfma_f32_16x16x32_bf16 v[68:71], v[158:161], v[232:235], v[68:71]
	v_mfma_f32_16x16x32_bf16 v[64:67], v[166:169], v[232:235], v[64:67]
	v_mfma_f32_16x16x32_bf16 v[116:119], v[162:165], v[178:181], v[116:119]
	v_mfma_f32_16x16x32_bf16 v[112:115], v[170:173], v[178:181], v[112:115]
	v_mfma_f32_16x16x32_bf16 v[100:103], v[162:165], v[208:211], v[100:103]
	v_mfma_f32_16x16x32_bf16 v[96:99], v[170:173], v[208:211], v[96:99]
	v_mfma_f32_16x16x32_bf16 v[84:87], v[162:165], v[228:231], v[84:87]
	v_mfma_f32_16x16x32_bf16 v[80:83], v[170:173], v[228:231], v[80:83]
	v_mfma_f32_16x16x32_bf16 v[68:71], v[162:165], v[236:239], v[68:71]
	v_mfma_f32_16x16x32_bf16 v[64:67], v[170:173], v[236:239], v[64:67]
	s_setprio 0
	s_barrier
	s_add_i32 s10, s10, s3
	v_lshl_add_u64 v[186:187], v[186:187], 0, s[48:49]
	s_mov_b32 m0, s10
	ds_read_b128 v[174:177], v145 offset:49152
	ds_read_b128 v[178:181], v145 offset:50176
	ds_read_b128 v[182:185], v145 offset:51200
	ds_read_b128 v[208:211], v145 offset:52224
	ds_read_b128 v[212:215], v145 offset:53248
	ds_read_b128 v[228:231], v145 offset:54272
	ds_read_b128 v[232:235], v145 offset:55296
	ds_read_b128 v[236:239], v145 offset:56320
	global_load_lds_dwordx4 v[186:187], off
	s_add_i32 m0, s10, 0x2000
	s_add_u32 s46, s46, 0x80080
	v_lshl_add_u64 v[186:187], v[240:241], 0, s[48:49]
	s_addc_u32 s47, s47, 0
	s_add_i32 s10, s33, s3
	global_load_lds_dwordx4 v[186:187], off
	v_lshl_add_u64 v[186:187], s[46:47], 0, v[194:195]
	s_mov_b32 m0, s10
	s_nop 0
	global_load_lds_dwordx4 v[186:187], off
	v_lshl_add_u64 v[186:187], s[46:47], 0, v[128:129]
	s_add_i32 m0, s10, 0x2000
	s_nop 0
	global_load_lds_dwordx4 v[186:187], off
	v_lshl_add_u64 v[186:187], v[242:243], 0, s[48:49]
	s_mov_b32 m0, s45
	s_nop 0
	global_load_lds_dwordx4 v[186:187], off
	v_lshl_add_u64 v[186:187], v[244:245], 0, s[48:49]
	s_mov_b32 m0, s60
	s_nop 0
	global_load_lds_dwordx4 v[186:187], off
	s_waitcnt vmcnt(8)
	s_barrier
	s_setprio 1
	s_waitcnt lgkmcnt(7)
	v_mfma_f32_16x16x32_bf16 v[60:63], v[140:143], v[174:177], v[60:63]
	v_mfma_f32_16x16x32_bf16 v[56:59], v[150:153], v[174:177], v[56:59]
	s_waitcnt lgkmcnt(5)
	v_mfma_f32_16x16x32_bf16 v[44:47], v[140:143], v[182:185], v[44:47]
	v_mfma_f32_16x16x32_bf16 v[40:43], v[150:153], v[182:185], v[40:43]
	s_waitcnt lgkmcnt(3)
	v_mfma_f32_16x16x32_bf16 v[28:31], v[140:143], v[212:215], v[28:31]
	v_mfma_f32_16x16x32_bf16 v[24:27], v[150:153], v[212:215], v[24:27]
	s_waitcnt lgkmcnt(1)
	v_mfma_f32_16x16x32_bf16 v[12:15], v[140:143], v[232:235], v[12:15]
	v_mfma_f32_16x16x32_bf16 v[8:11], v[150:153], v[232:235], v[8:11]
	v_mfma_f32_16x16x32_bf16 v[60:63], v[146:149], v[178:181], v[60:63]
	v_mfma_f32_16x16x32_bf16 v[56:59], v[154:157], v[178:181], v[56:59]
	v_mfma_f32_16x16x32_bf16 v[44:47], v[146:149], v[208:211], v[44:47]
	v_mfma_f32_16x16x32_bf16 v[40:43], v[154:157], v[208:211], v[40:43]
	v_mfma_f32_16x16x32_bf16 v[28:31], v[146:149], v[228:231], v[28:31]
	v_mfma_f32_16x16x32_bf16 v[24:27], v[154:157], v[228:231], v[24:27]
	s_waitcnt lgkmcnt(0)
	v_mfma_f32_16x16x32_bf16 v[12:15], v[146:149], v[236:239], v[12:15]
	v_mfma_f32_16x16x32_bf16 v[8:11], v[154:157], v[236:239], v[8:11]
	s_setprio 0
	s_setprio 1
	v_mfma_f32_16x16x32_bf16 v[52:55], v[158:161], v[174:177], v[52:55]
	v_mfma_f32_16x16x32_bf16 v[48:51], v[166:169], v[174:177], v[48:51]
	v_mfma_f32_16x16x32_bf16 v[36:39], v[158:161], v[182:185], v[36:39]
	v_mfma_f32_16x16x32_bf16 v[32:35], v[166:169], v[182:185], v[32:35]
	v_mfma_f32_16x16x32_bf16 v[20:23], v[158:161], v[212:215], v[20:23]
	v_mfma_f32_16x16x32_bf16 v[16:19], v[166:169], v[212:215], v[16:19]
	v_mfma_f32_16x16x32_bf16 v[4:7], v[158:161], v[232:235], v[4:7]
	v_mfma_f32_16x16x32_bf16 v[0:3], v[166:169], v[232:235], v[0:3]
	v_mfma_f32_16x16x32_bf16 v[52:55], v[162:165], v[178:181], v[52:55]
	v_mfma_f32_16x16x32_bf16 v[48:51], v[170:173], v[178:181], v[48:51]
	v_mfma_f32_16x16x32_bf16 v[36:39], v[162:165], v[208:211], v[36:39]
	v_mfma_f32_16x16x32_bf16 v[32:35], v[170:173], v[208:211], v[32:35]
	v_mfma_f32_16x16x32_bf16 v[20:23], v[162:165], v[228:231], v[20:23]
	v_mfma_f32_16x16x32_bf16 v[16:19], v[170:173], v[228:231], v[16:19]
	v_mfma_f32_16x16x32_bf16 v[4:7], v[162:165], v[236:239], v[4:7]
	v_mfma_f32_16x16x32_bf16 v[0:3], v[170:173], v[236:239], v[0:3]
	s_setprio 0
	s_barrier
	s_add_i32 s78, s78, 2
	s_add_u32 s35, s35, 0x100
	s_addc_u32 s73, s73, 0
	s_cmp_gt_u32 s78, 29
	s_mov_b64 s[90:91], s[0:1]
	s_cbranch_scc0 .LBB0_1020
	s_branch .Lgemm3_exit
.LBB0_1020:
	s_add_u32 s0, s90, 0x100
	s_addc_u32 s1, s91, 0
	s_add_i32 s10, 0, 0x10000
	s_cmp_eq_u32 s78, 28
	s_cselect_b32 vcc_hi, s75, s1
	s_cselect_b32 vcc_lo, s74, s0
	s_cselect_b32 s47, s9, s73
	s_cselect_b32 s46, s34, s35
	s_add_i32 s33, 0, 0x14000
	v_add_u32_e32 v154, s10, v144
	v_add_u32_e32 v170, s33, v144
	ds_read_b128 v[140:143], v154
	ds_read_b128 v[146:149], v154 offset:1024
	ds_read_b128 v[150:153], v154 offset:2048
	ds_read_b128 v[154:157], v154 offset:3072
	ds_read_b128 v[158:161], v170
	ds_read_b128 v[162:165], v170 offset:1024
	ds_read_b128 v[166:169], v170 offset:2048
	ds_read_b128 v[170:173], v170 offset:3072
	v_lshl_add_u64 v[186:187], s[90:91], 0, v[136:137]
	s_add_i32 m0, s11, 0xc000
	ds_read_b128 v[174:177], v145
	ds_read_b128 v[178:181], v145 offset:1024
	ds_read_b128 v[182:185], v145 offset:2048
	ds_read_b128 v[208:211], v145 offset:3072
	ds_read_b128 v[212:215], v145 offset:4096
	ds_read_b128 v[228:231], v145 offset:5120
	ds_read_b128 v[232:235], v145 offset:6144
	ds_read_b128 v[236:239], v145 offset:7168
	global_load_lds_dwordx4 v[186:187], off
	v_lshl_add_u64 v[186:187], s[90:91], 0, v[138:139]
	s_add_i32 m0, s11, 0xe000
	s_nop 0
	global_load_lds_dwordx4 v[186:187], off
	s_waitcnt vmcnt(8)
	s_barrier
	s_setprio 1
	s_waitcnt lgkmcnt(7)
	v_mfma_f32_16x16x32_bf16 v[124:127], v[140:143], v[174:177], v[124:127]
	v_mfma_f32_16x16x32_bf16 v[120:123], v[150:153], v[174:177], v[120:123]
	s_waitcnt lgkmcnt(5)
	v_mfma_f32_16x16x32_bf16 v[108:111], v[140:143], v[182:185], v[108:111]
	v_mfma_f32_16x16x32_bf16 v[104:107], v[150:153], v[182:185], v[104:107]
	s_waitcnt lgkmcnt(3)
	v_mfma_f32_16x16x32_bf16 v[92:95], v[140:143], v[212:215], v[92:95]
	v_mfma_f32_16x16x32_bf16 v[88:91], v[150:153], v[212:215], v[88:91]
	s_waitcnt lgkmcnt(1)
	v_mfma_f32_16x16x32_bf16 v[76:79], v[140:143], v[232:235], v[76:79]
	v_mfma_f32_16x16x32_bf16 v[72:75], v[150:153], v[232:235], v[72:75]
	v_mfma_f32_16x16x32_bf16 v[124:127], v[146:149], v[178:181], v[124:127]
	v_mfma_f32_16x16x32_bf16 v[120:123], v[154:157], v[178:181], v[120:123]
	v_mfma_f32_16x16x32_bf16 v[108:111], v[146:149], v[208:211], v[108:111]
	v_mfma_f32_16x16x32_bf16 v[104:107], v[154:157], v[208:211], v[104:107]
	v_mfma_f32_16x16x32_bf16 v[92:95], v[146:149], v[228:231], v[92:95]
	v_mfma_f32_16x16x32_bf16 v[88:91], v[154:157], v[228:231], v[88:91]
	s_waitcnt lgkmcnt(0)
	v_mfma_f32_16x16x32_bf16 v[76:79], v[146:149], v[236:239], v[76:79]
	v_mfma_f32_16x16x32_bf16 v[72:75], v[154:157], v[236:239], v[72:75]
	s_setprio 0
	s_setprio 1
	v_mfma_f32_16x16x32_bf16 v[116:119], v[158:161], v[174:177], v[116:119]
	v_mfma_f32_16x16x32_bf16 v[112:115], v[166:169], v[174:177], v[112:115]
	v_mfma_f32_16x16x32_bf16 v[100:103], v[158:161], v[182:185], v[100:103]
	v_mfma_f32_16x16x32_bf16 v[96:99], v[166:169], v[182:185], v[96:99]
	v_mfma_f32_16x16x32_bf16 v[84:87], v[158:161], v[212:215], v[84:87]
	v_mfma_f32_16x16x32_bf16 v[80:83], v[166:169], v[212:215], v[80:83]
	v_mfma_f32_16x16x32_bf16 v[68:71], v[158:161], v[232:235], v[68:71]
	v_mfma_f32_16x16x32_bf16 v[64:67], v[166:169], v[232:235], v[64:67]
	v_mfma_f32_16x16x32_bf16 v[116:119], v[162:165], v[178:181], v[116:119]
	v_mfma_f32_16x16x32_bf16 v[112:115], v[170:173], v[178:181], v[112:115]
	v_mfma_f32_16x16x32_bf16 v[100:103], v[162:165], v[208:211], v[100:103]
	v_mfma_f32_16x16x32_bf16 v[96:99], v[170:173], v[208:211], v[96:99]
	v_mfma_f32_16x16x32_bf16 v[84:87], v[162:165], v[228:231], v[84:87]
	v_mfma_f32_16x16x32_bf16 v[80:83], v[170:173], v[228:231], v[80:83]
	v_mfma_f32_16x16x32_bf16 v[68:71], v[162:165], v[236:239], v[68:71]
	v_mfma_f32_16x16x32_bf16 v[64:67], v[170:173], v[236:239], v[64:67]
	s_setprio 0
	s_barrier
	s_add_i32 s10, s10, s3
	v_lshl_add_u64 v[186:187], s[46:47], 0, v[194:195]
	s_mov_b32 m0, s10
	ds_read_b128 v[174:177], v145 offset:16384
	ds_read_b128 v[178:181], v145 offset:17408
	ds_read_b128 v[182:185], v145 offset:18432
	ds_read_b128 v[208:211], v145 offset:19456
	ds_read_b128 v[212:215], v145 offset:20480
	ds_read_b128 v[228:231], v145 offset:21504
	ds_read_b128 v[232:235], v145 offset:22528
	ds_read_b128 v[236:239], v145 offset:23552
	global_load_lds_dwordx4 v[186:187], off
	s_add_i32 m0, s10, 0x2000
	s_add_u32 s90, s46, 0x80000
	v_lshl_add_u64 v[240:241], s[46:47], 0, v[128:129]
	s_addc_u32 s91, s47, 0
	s_add_i32 s10, s33, s3
	global_load_lds_dwordx4 v[240:241], off
	v_lshl_add_u64 v[242:243], s[90:91], 0, v[194:195]
	s_mov_b32 m0, s10
	v_lshl_add_u64 v[244:245], vcc, 0, v[130:131]
	global_load_lds_dwordx4 v[242:243], off
	v_lshl_add_u64 v[242:243], s[90:91], 0, v[128:129]
	s_add_i32 m0, s10, 0x2000
	s_nop 0
	global_load_lds_dwordx4 v[242:243], off
	v_lshl_add_u64 v[242:243], vcc, 0, v[132:133]
	s_mov_b32 m0, s11
	s_nop 0
	global_load_lds_dwordx4 v[242:243], off
	s_mov_b32 m0, s12
	s_nop 0
	global_load_lds_dwordx4 v[244:245], off
	s_waitcnt vmcnt(8)
	s_barrier
	s_setprio 1
	s_waitcnt lgkmcnt(7)
	v_mfma_f32_16x16x32_bf16 v[60:63], v[140:143], v[174:177], v[60:63]
	v_mfma_f32_16x16x32_bf16 v[56:59], v[150:153], v[174:177], v[56:59]
	s_waitcnt lgkmcnt(5)
	v_mfma_f32_16x16x32_bf16 v[44:47], v[140:143], v[182:185], v[44:47]
	v_mfma_f32_16x16x32_bf16 v[40:43], v[150:153], v[182:185], v[40:43]
	s_waitcnt lgkmcnt(3)
	v_mfma_f32_16x16x32_bf16 v[28:31], v[140:143], v[212:215], v[28:31]
	v_mfma_f32_16x16x32_bf16 v[24:27], v[150:153], v[212:215], v[24:27]
	s_waitcnt lgkmcnt(1)
	v_mfma_f32_16x16x32_bf16 v[12:15], v[140:143], v[232:235], v[12:15]
	v_mfma_f32_16x16x32_bf16 v[8:11], v[150:153], v[232:235], v[8:11]
	v_mfma_f32_16x16x32_bf16 v[60:63], v[146:149], v[178:181], v[60:63]
	v_mfma_f32_16x16x32_bf16 v[56:59], v[154:157], v[178:181], v[56:59]
	v_mfma_f32_16x16x32_bf16 v[44:47], v[146:149], v[208:211], v[44:47]
	v_mfma_f32_16x16x32_bf16 v[40:43], v[154:157], v[208:211], v[40:43]
	v_mfma_f32_16x16x32_bf16 v[28:31], v[146:149], v[228:231], v[28:31]
	v_mfma_f32_16x16x32_bf16 v[24:27], v[154:157], v[228:231], v[24:27]
	s_waitcnt lgkmcnt(0)
	v_mfma_f32_16x16x32_bf16 v[12:15], v[146:149], v[236:239], v[12:15]
	v_mfma_f32_16x16x32_bf16 v[8:11], v[154:157], v[236:239], v[8:11]
	s_setprio 0
	s_setprio 1
	v_mfma_f32_16x16x32_bf16 v[52:55], v[158:161], v[174:177], v[52:55]
	v_mfma_f32_16x16x32_bf16 v[48:51], v[166:169], v[174:177], v[48:51]
	v_mfma_f32_16x16x32_bf16 v[36:39], v[158:161], v[182:185], v[36:39]
	v_mfma_f32_16x16x32_bf16 v[32:35], v[166:169], v[182:185], v[32:35]
	v_mfma_f32_16x16x32_bf16 v[20:23], v[158:161], v[212:215], v[20:23]
	v_mfma_f32_16x16x32_bf16 v[16:19], v[166:169], v[212:215], v[16:19]
	v_mfma_f32_16x16x32_bf16 v[4:7], v[158:161], v[232:235], v[4:7]
	v_mfma_f32_16x16x32_bf16 v[0:3], v[166:169], v[232:235], v[0:3]
	v_mfma_f32_16x16x32_bf16 v[52:55], v[162:165], v[178:181], v[52:55]
	v_mfma_f32_16x16x32_bf16 v[48:51], v[170:173], v[178:181], v[48:51]
	v_mfma_f32_16x16x32_bf16 v[36:39], v[162:165], v[208:211], v[36:39]
	v_mfma_f32_16x16x32_bf16 v[32:35], v[170:173], v[208:211], v[32:35]
	v_mfma_f32_16x16x32_bf16 v[20:23], v[162:165], v[228:231], v[20:23]
	v_mfma_f32_16x16x32_bf16 v[16:19], v[170:173], v[228:231], v[16:19]
	v_mfma_f32_16x16x32_bf16 v[4:7], v[162:165], v[236:239], v[4:7]
	v_mfma_f32_16x16x32_bf16 v[0:3], v[170:173], v[236:239], v[0:3]
	s_setprio 0
	s_barrier
	s_add_i32 s10, 0, 0x18000
	s_add_i32 s33, 0, 0x1c000
	v_add_u32_e32 v154, s10, v144
	v_add_u32_e32 v170, s33, v144
	ds_read_b128 v[140:143], v154
	ds_read_b128 v[146:149], v154 offset:1024
	ds_read_b128 v[150:153], v154 offset:2048
	ds_read_b128 v[154:157], v154 offset:3072
	ds_read_b128 v[158:161], v170
	ds_read_b128 v[162:165], v170 offset:1024
	ds_read_b128 v[166:169], v170 offset:2048
	ds_read_b128 v[170:173], v170 offset:3072
	s_add_u32 s90, vcc_lo, 0x160000
	s_addc_u32 s91, vcc_hi, 0
	s_mov_b32 m0, s16
	v_lshl_add_u64 v[246:247], s[90:91], 0, v[132:133]
	ds_read_b128 v[174:177], v145 offset:32768
	ds_read_b128 v[178:181], v145 offset:33792
	ds_read_b128 v[182:185], v145 offset:34816
	ds_read_b128 v[208:211], v145 offset:35840
	ds_read_b128 v[212:215], v145 offset:36864
	ds_read_b128 v[228:231], v145 offset:37888
	ds_read_b128 v[232:235], v145 offset:38912
	ds_read_b128 v[236:239], v145 offset:39936
	global_load_lds_dwordx4 v[246:247], off
	v_lshl_add_u64 v[246:247], s[90:91], 0, v[130:131]
	s_mov_b32 m0, s17
	s_nop 0
	global_load_lds_dwordx4 v[246:247], off
	s_waitcnt vmcnt(8)
	s_barrier
	s_setprio 1
	s_waitcnt lgkmcnt(7)
	v_mfma_f32_16x16x32_bf16 v[124:127], v[140:143], v[174:177], v[124:127]
	v_mfma_f32_16x16x32_bf16 v[120:123], v[150:153], v[174:177], v[120:123]
	s_waitcnt lgkmcnt(5)
	v_mfma_f32_16x16x32_bf16 v[108:111], v[140:143], v[182:185], v[108:111]
	v_mfma_f32_16x16x32_bf16 v[104:107], v[150:153], v[182:185], v[104:107]
	s_waitcnt lgkmcnt(3)
	v_mfma_f32_16x16x32_bf16 v[92:95], v[140:143], v[212:215], v[92:95]
	v_mfma_f32_16x16x32_bf16 v[88:91], v[150:153], v[212:215], v[88:91]
	s_waitcnt lgkmcnt(1)
	v_mfma_f32_16x16x32_bf16 v[76:79], v[140:143], v[232:235], v[76:79]
	v_mfma_f32_16x16x32_bf16 v[72:75], v[150:153], v[232:235], v[72:75]
	v_mfma_f32_16x16x32_bf16 v[124:127], v[146:149], v[178:181], v[124:127]
	v_mfma_f32_16x16x32_bf16 v[120:123], v[154:157], v[178:181], v[120:123]
	v_mfma_f32_16x16x32_bf16 v[108:111], v[146:149], v[208:211], v[108:111]
	v_mfma_f32_16x16x32_bf16 v[104:107], v[154:157], v[208:211], v[104:107]
	v_mfma_f32_16x16x32_bf16 v[92:95], v[146:149], v[228:231], v[92:95]
	v_mfma_f32_16x16x32_bf16 v[88:91], v[154:157], v[228:231], v[88:91]
	s_waitcnt lgkmcnt(0)
	v_mfma_f32_16x16x32_bf16 v[76:79], v[146:149], v[236:239], v[76:79]
	v_mfma_f32_16x16x32_bf16 v[72:75], v[154:157], v[236:239], v[72:75]
	s_setprio 0
	s_setprio 1
	v_mfma_f32_16x16x32_bf16 v[116:119], v[158:161], v[174:177], v[116:119]
	v_mfma_f32_16x16x32_bf16 v[112:115], v[166:169], v[174:177], v[112:115]
	v_mfma_f32_16x16x32_bf16 v[100:103], v[158:161], v[182:185], v[100:103]
	v_mfma_f32_16x16x32_bf16 v[96:99], v[166:169], v[182:185], v[96:99]
	v_mfma_f32_16x16x32_bf16 v[84:87], v[158:161], v[212:215], v[84:87]
	v_mfma_f32_16x16x32_bf16 v[80:83], v[166:169], v[212:215], v[80:83]
	v_mfma_f32_16x16x32_bf16 v[68:71], v[158:161], v[232:235], v[68:71]
	v_mfma_f32_16x16x32_bf16 v[64:67], v[166:169], v[232:235], v[64:67]
	v_mfma_f32_16x16x32_bf16 v[116:119], v[162:165], v[178:181], v[116:119]
	v_mfma_f32_16x16x32_bf16 v[112:115], v[170:173], v[178:181], v[112:115]
	v_mfma_f32_16x16x32_bf16 v[100:103], v[162:165], v[208:211], v[100:103]
	v_mfma_f32_16x16x32_bf16 v[96:99], v[170:173], v[208:211], v[96:99]
	v_mfma_f32_16x16x32_bf16 v[84:87], v[162:165], v[228:231], v[84:87]
	v_mfma_f32_16x16x32_bf16 v[80:83], v[170:173], v[228:231], v[80:83]
	v_mfma_f32_16x16x32_bf16 v[68:71], v[162:165], v[236:239], v[68:71]
	v_mfma_f32_16x16x32_bf16 v[64:67], v[170:173], v[236:239], v[64:67]
	s_setprio 0
	s_barrier
	s_add_i32 s10, s10, s3
	v_lshl_add_u64 v[186:187], v[186:187], 0, s[48:49]
	s_mov_b32 m0, s10
	ds_read_b128 v[174:177], v145 offset:49152
	ds_read_b128 v[178:181], v145 offset:50176
	ds_read_b128 v[182:185], v145 offset:51200
	ds_read_b128 v[208:211], v145 offset:52224
	ds_read_b128 v[212:215], v145 offset:53248
	ds_read_b128 v[228:231], v145 offset:54272
	ds_read_b128 v[232:235], v145 offset:55296
	ds_read_b128 v[236:239], v145 offset:56320
	global_load_lds_dwordx4 v[186:187], off
	s_add_i32 m0, s10, 0x2000
	s_add_u32 s46, s46, 0x80080
	v_lshl_add_u64 v[186:187], v[240:241], 0, s[48:49]
	s_addc_u32 s47, s47, 0
	s_add_i32 s10, s33, s3
	global_load_lds_dwordx4 v[186:187], off
	v_lshl_add_u64 v[186:187], s[46:47], 0, v[194:195]
	s_mov_b32 m0, s10
	s_nop 0
	global_load_lds_dwordx4 v[186:187], off
	v_lshl_add_u64 v[186:187], s[46:47], 0, v[128:129]
	s_add_i32 m0, s10, 0x2000
	s_nop 0
	global_load_lds_dwordx4 v[186:187], off
	v_lshl_add_u64 v[186:187], v[242:243], 0, s[48:49]
	s_mov_b32 m0, s45
	s_nop 0
	global_load_lds_dwordx4 v[186:187], off
	v_lshl_add_u64 v[186:187], v[244:245], 0, s[48:49]
	s_mov_b32 m0, s60
	s_nop 0
	global_load_lds_dwordx4 v[186:187], off
	s_waitcnt vmcnt(8)
	s_barrier
	s_setprio 1
	s_waitcnt lgkmcnt(7)
	v_mfma_f32_16x16x32_bf16 v[60:63], v[140:143], v[174:177], v[60:63]
	v_mfma_f32_16x16x32_bf16 v[56:59], v[150:153], v[174:177], v[56:59]
	s_waitcnt lgkmcnt(5)
	v_mfma_f32_16x16x32_bf16 v[44:47], v[140:143], v[182:185], v[44:47]
	v_mfma_f32_16x16x32_bf16 v[40:43], v[150:153], v[182:185], v[40:43]
	s_waitcnt lgkmcnt(3)
	v_mfma_f32_16x16x32_bf16 v[28:31], v[140:143], v[212:215], v[28:31]
	v_mfma_f32_16x16x32_bf16 v[24:27], v[150:153], v[212:215], v[24:27]
	s_waitcnt lgkmcnt(1)
	v_mfma_f32_16x16x32_bf16 v[12:15], v[140:143], v[232:235], v[12:15]
	v_mfma_f32_16x16x32_bf16 v[8:11], v[150:153], v[232:235], v[8:11]
	v_mfma_f32_16x16x32_bf16 v[60:63], v[146:149], v[178:181], v[60:63]
	v_mfma_f32_16x16x32_bf16 v[56:59], v[154:157], v[178:181], v[56:59]
	v_mfma_f32_16x16x32_bf16 v[44:47], v[146:149], v[208:211], v[44:47]
	v_mfma_f32_16x16x32_bf16 v[40:43], v[154:157], v[208:211], v[40:43]
	v_mfma_f32_16x16x32_bf16 v[28:31], v[146:149], v[228:231], v[28:31]
	v_mfma_f32_16x16x32_bf16 v[24:27], v[154:157], v[228:231], v[24:27]
	s_waitcnt lgkmcnt(0)
	v_mfma_f32_16x16x32_bf16 v[12:15], v[146:149], v[236:239], v[12:15]
	v_mfma_f32_16x16x32_bf16 v[8:11], v[154:157], v[236:239], v[8:11]
	s_setprio 0
	s_setprio 1
	v_mfma_f32_16x16x32_bf16 v[52:55], v[158:161], v[174:177], v[52:55]
	v_mfma_f32_16x16x32_bf16 v[48:51], v[166:169], v[174:177], v[48:51]
	v_mfma_f32_16x16x32_bf16 v[36:39], v[158:161], v[182:185], v[36:39]
	v_mfma_f32_16x16x32_bf16 v[32:35], v[166:169], v[182:185], v[32:35]
	v_mfma_f32_16x16x32_bf16 v[20:23], v[158:161], v[212:215], v[20:23]
	v_mfma_f32_16x16x32_bf16 v[16:19], v[166:169], v[212:215], v[16:19]
	v_mfma_f32_16x16x32_bf16 v[4:7], v[158:161], v[232:235], v[4:7]
	v_mfma_f32_16x16x32_bf16 v[0:3], v[166:169], v[232:235], v[0:3]
	v_mfma_f32_16x16x32_bf16 v[52:55], v[162:165], v[178:181], v[52:55]
	v_mfma_f32_16x16x32_bf16 v[48:51], v[170:173], v[178:181], v[48:51]
	v_mfma_f32_16x16x32_bf16 v[36:39], v[162:165], v[208:211], v[36:39]
	v_mfma_f32_16x16x32_bf16 v[32:35], v[170:173], v[208:211], v[32:35]
	v_mfma_f32_16x16x32_bf16 v[20:23], v[162:165], v[228:231], v[20:23]
	v_mfma_f32_16x16x32_bf16 v[16:19], v[170:173], v[228:231], v[16:19]
	v_mfma_f32_16x16x32_bf16 v[4:7], v[162:165], v[236:239], v[4:7]
	v_mfma_f32_16x16x32_bf16 v[0:3], v[170:173], v[236:239], v[0:3]
	s_setprio 0
	s_barrier
	s_add_i32 s78, s78, 2
	s_add_u32 s35, s35, 0x100
	s_addc_u32 s73, s73, 0
	s_cmp_gt_u32 s78, 29
	s_mov_b64 s[90:91], s[0:1]
	s_cbranch_scc0 .LBB0_1020

.Lgemm4_peel:
	s_add_u32 s0, s90, 0x100
	s_addc_u32 s1, s91, 0
	s_add_i32 s10, 0, 0x10000
	s_cmp_eq_u32 s78, 28
	s_cselect_b32 vcc_hi, s75, s1
	s_cselect_b32 vcc_lo, s74, s0
	v_add_u32_e32 v144, s10, v146
	s_cselect_b32 s47, s9, s73
	s_cselect_b32 s46, s34, s35
	s_add_i32 s33, 0, 0x14000
	ds_read_b128 v[140:143], v144
	ds_read_b128 v[148:151], v144 offset:1024
	ds_read_b128 v[152:155], v144 offset:2048
	ds_read_b128 v[156:159], v144 offset:3072
	v_add_u32_e32 v144, s33, v146
	ds_read_b128 v[160:163], v144
	ds_read_b128 v[164:167], v144 offset:1024
	ds_read_b128 v[168:171], v144 offset:2048
	ds_read_b128 v[172:175], v144 offset:3072
	v_lshl_add_u64 v[144:145], s[90:91], 0, v[136:137]
	s_add_i32 m0, s11, 0xc000
	ds_read_b128 v[176:179], v147
	ds_read_b128 v[180:183], v147 offset:1024
	ds_read_b128 v[184:187], v147 offset:2048
	ds_read_b128 v[208:211], v147 offset:3072
	ds_read_b128 v[212:215], v147 offset:4096
	ds_read_b128 v[228:231], v147 offset:5120
	ds_read_b128 v[232:235], v147 offset:6144
	ds_read_b128 v[236:239], v147 offset:7168
	global_load_lds_dwordx4 v[144:145], off
	v_lshl_add_u64 v[144:145], s[90:91], 0, v[138:139]
	s_add_i32 m0, s11, 0xe000
	s_nop 0
	global_load_lds_dwordx4 v[144:145], off
	s_waitcnt vmcnt(8)
	s_barrier
	s_setprio 1
	s_waitcnt lgkmcnt(7)
	v_mfma_f32_16x16x32_bf16 v[124:127], v[140:143], v[176:179], 0
	v_mfma_f32_16x16x32_bf16 v[120:123], v[152:155], v[176:179], 0
	s_waitcnt lgkmcnt(5)
	v_mfma_f32_16x16x32_bf16 v[108:111], v[140:143], v[184:187], 0
	v_mfma_f32_16x16x32_bf16 v[104:107], v[152:155], v[184:187], 0
	s_waitcnt lgkmcnt(3)
	v_mfma_f32_16x16x32_bf16 v[92:95], v[140:143], v[212:215], 0
	v_mfma_f32_16x16x32_bf16 v[88:91], v[152:155], v[212:215], 0
	s_waitcnt lgkmcnt(1)
	v_mfma_f32_16x16x32_bf16 v[76:79], v[140:143], v[232:235], 0
	v_mfma_f32_16x16x32_bf16 v[72:75], v[152:155], v[232:235], 0
	v_mfma_f32_16x16x32_bf16 v[124:127], v[148:151], v[180:183], v[124:127]
	v_mfma_f32_16x16x32_bf16 v[120:123], v[156:159], v[180:183], v[120:123]
	v_mfma_f32_16x16x32_bf16 v[108:111], v[148:151], v[208:211], v[108:111]
	v_mfma_f32_16x16x32_bf16 v[104:107], v[156:159], v[208:211], v[104:107]
	v_mfma_f32_16x16x32_bf16 v[92:95], v[148:151], v[228:231], v[92:95]
	v_mfma_f32_16x16x32_bf16 v[88:91], v[156:159], v[228:231], v[88:91]
	s_waitcnt lgkmcnt(0)
	v_mfma_f32_16x16x32_bf16 v[76:79], v[148:151], v[236:239], v[76:79]
	v_mfma_f32_16x16x32_bf16 v[72:75], v[156:159], v[236:239], v[72:75]
	s_setprio 0
	s_setprio 1
	v_mfma_f32_16x16x32_bf16 v[116:119], v[160:163], v[176:179], 0
	v_mfma_f32_16x16x32_bf16 v[112:115], v[168:171], v[176:179], 0
	v_mfma_f32_16x16x32_bf16 v[100:103], v[160:163], v[184:187], 0
	v_mfma_f32_16x16x32_bf16 v[96:99], v[168:171], v[184:187], 0
	v_mfma_f32_16x16x32_bf16 v[84:87], v[160:163], v[212:215], 0
	v_mfma_f32_16x16x32_bf16 v[80:83], v[168:171], v[212:215], 0
	v_mfma_f32_16x16x32_bf16 v[68:71], v[160:163], v[232:235], 0
	v_mfma_f32_16x16x32_bf16 v[64:67], v[168:171], v[232:235], 0
	v_mfma_f32_16x16x32_bf16 v[116:119], v[164:167], v[180:183], v[116:119]
	v_mfma_f32_16x16x32_bf16 v[112:115], v[172:175], v[180:183], v[112:115]
	v_mfma_f32_16x16x32_bf16 v[100:103], v[164:167], v[208:211], v[100:103]
	v_mfma_f32_16x16x32_bf16 v[96:99], v[172:175], v[208:211], v[96:99]
	v_mfma_f32_16x16x32_bf16 v[84:87], v[164:167], v[228:231], v[84:87]
	v_mfma_f32_16x16x32_bf16 v[80:83], v[172:175], v[228:231], v[80:83]
	v_mfma_f32_16x16x32_bf16 v[68:71], v[164:167], v[236:239], v[68:71]
	v_mfma_f32_16x16x32_bf16 v[64:67], v[172:175], v[236:239], v[64:67]
	s_setprio 0
	s_barrier
	s_add_i32 s10, s10, s3
	v_lshl_add_u64 v[144:145], s[46:47], 0, v[194:195]
	s_mov_b32 m0, s10
	ds_read_b128 v[176:179], v147 offset:16384
	ds_read_b128 v[180:183], v147 offset:17408
	ds_read_b128 v[184:187], v147 offset:18432
	ds_read_b128 v[208:211], v147 offset:19456
	ds_read_b128 v[212:215], v147 offset:20480
	ds_read_b128 v[228:231], v147 offset:21504
	ds_read_b128 v[232:235], v147 offset:22528
	ds_read_b128 v[236:239], v147 offset:23552
	global_load_lds_dwordx4 v[144:145], off
	s_add_i32 m0, s10, 0x2000
	s_add_u32 s90, s46, 0x80000
	v_lshl_add_u64 v[240:241], s[46:47], 0, v[128:129]
	s_addc_u32 s91, s47, 0
	s_add_i32 s10, s33, s3
	global_load_lds_dwordx4 v[240:241], off
	v_lshl_add_u64 v[242:243], s[90:91], 0, v[194:195]
	s_mov_b32 m0, s10
	v_lshl_add_u64 v[244:245], vcc, 0, v[130:131]
	global_load_lds_dwordx4 v[242:243], off
	v_lshl_add_u64 v[242:243], s[90:91], 0, v[128:129]
	s_add_i32 m0, s10, 0x2000
	s_nop 0
	global_load_lds_dwordx4 v[242:243], off
	v_lshl_add_u64 v[242:243], vcc, 0, v[132:133]
	s_mov_b32 m0, s11
	s_nop 0
	global_load_lds_dwordx4 v[242:243], off
	s_mov_b32 m0, s12
	s_nop 0
	global_load_lds_dwordx4 v[244:245], off
	s_waitcnt vmcnt(8)
	s_barrier
	s_setprio 1
	s_waitcnt lgkmcnt(7)
	v_mfma_f32_16x16x32_bf16 v[60:63], v[140:143], v[176:179], 0
	v_mfma_f32_16x16x32_bf16 v[56:59], v[152:155], v[176:179], 0
	s_waitcnt lgkmcnt(5)
	v_mfma_f32_16x16x32_bf16 v[44:47], v[140:143], v[184:187], 0
	v_mfma_f32_16x16x32_bf16 v[40:43], v[152:155], v[184:187], 0
	s_waitcnt lgkmcnt(3)
	v_mfma_f32_16x16x32_bf16 v[28:31], v[140:143], v[212:215], 0
	v_mfma_f32_16x16x32_bf16 v[24:27], v[152:155], v[212:215], 0
	s_waitcnt lgkmcnt(1)
	v_mfma_f32_16x16x32_bf16 v[12:15], v[140:143], v[232:235], 0
	v_mfma_f32_16x16x32_bf16 v[8:11], v[152:155], v[232:235], 0
	v_mfma_f32_16x16x32_bf16 v[60:63], v[148:151], v[180:183], v[60:63]
	v_mfma_f32_16x16x32_bf16 v[56:59], v[156:159], v[180:183], v[56:59]
	v_mfma_f32_16x16x32_bf16 v[44:47], v[148:151], v[208:211], v[44:47]
	v_mfma_f32_16x16x32_bf16 v[40:43], v[156:159], v[208:211], v[40:43]
	v_mfma_f32_16x16x32_bf16 v[28:31], v[148:151], v[228:231], v[28:31]
	v_mfma_f32_16x16x32_bf16 v[24:27], v[156:159], v[228:231], v[24:27]
	s_waitcnt lgkmcnt(0)
	v_mfma_f32_16x16x32_bf16 v[12:15], v[148:151], v[236:239], v[12:15]
	v_mfma_f32_16x16x32_bf16 v[8:11], v[156:159], v[236:239], v[8:11]
	s_setprio 0
	s_setprio 1
	v_mfma_f32_16x16x32_bf16 v[52:55], v[160:163], v[176:179], 0
	v_mfma_f32_16x16x32_bf16 v[48:51], v[168:171], v[176:179], 0
	v_mfma_f32_16x16x32_bf16 v[36:39], v[160:163], v[184:187], 0
	v_mfma_f32_16x16x32_bf16 v[32:35], v[168:171], v[184:187], 0
	v_mfma_f32_16x16x32_bf16 v[20:23], v[160:163], v[212:215], 0
	v_mfma_f32_16x16x32_bf16 v[16:19], v[168:171], v[212:215], 0
	v_mfma_f32_16x16x32_bf16 v[4:7], v[160:163], v[232:235], 0
	v_mfma_f32_16x16x32_bf16 v[0:3], v[168:171], v[232:235], 0
	v_mfma_f32_16x16x32_bf16 v[52:55], v[164:167], v[180:183], v[52:55]
	v_mfma_f32_16x16x32_bf16 v[48:51], v[172:175], v[180:183], v[48:51]
	v_mfma_f32_16x16x32_bf16 v[36:39], v[164:167], v[208:211], v[36:39]
	v_mfma_f32_16x16x32_bf16 v[32:35], v[172:175], v[208:211], v[32:35]
	v_mfma_f32_16x16x32_bf16 v[20:23], v[164:167], v[228:231], v[20:23]
	v_mfma_f32_16x16x32_bf16 v[16:19], v[172:175], v[228:231], v[16:19]
	v_mfma_f32_16x16x32_bf16 v[4:7], v[164:167], v[236:239], v[4:7]
	v_mfma_f32_16x16x32_bf16 v[0:3], v[172:175], v[236:239], v[0:3]
	s_setprio 0
	s_barrier
	s_add_i32 s10, 0, 0x18000
	s_add_i32 s33, 0, 0x1c000
	v_add_u32_e32 v156, s10, v146
	v_add_u32_e32 v172, s33, v146
	ds_read_b128 v[140:143], v156
	ds_read_b128 v[148:151], v156 offset:1024
	ds_read_b128 v[152:155], v156 offset:2048
	ds_read_b128 v[156:159], v156 offset:3072
	ds_read_b128 v[160:163], v172
	ds_read_b128 v[164:167], v172 offset:1024
	ds_read_b128 v[168:171], v172 offset:2048
	ds_read_b128 v[172:175], v172 offset:3072
	s_add_u32 s90, vcc_lo, 0x160000
	s_addc_u32 s91, vcc_hi, 0
	s_mov_b32 m0, s16
	v_lshl_add_u64 v[246:247], s[90:91], 0, v[132:133]
	ds_read_b128 v[176:179], v147 offset:32768
	ds_read_b128 v[180:183], v147 offset:33792
	ds_read_b128 v[184:187], v147 offset:34816
	ds_read_b128 v[208:211], v147 offset:35840
	ds_read_b128 v[212:215], v147 offset:36864
	ds_read_b128 v[228:231], v147 offset:37888
	ds_read_b128 v[232:235], v147 offset:38912
	ds_read_b128 v[236:239], v147 offset:39936
	global_load_lds_dwordx4 v[246:247], off
	v_lshl_add_u64 v[246:247], s[90:91], 0, v[130:131]
	s_mov_b32 m0, s17
	s_nop 0
	global_load_lds_dwordx4 v[246:247], off
	s_waitcnt vmcnt(8)
	s_barrier
	s_setprio 1
	s_waitcnt lgkmcnt(7)
	v_mfma_f32_16x16x32_bf16 v[124:127], v[140:143], v[176:179], v[124:127]
	v_mfma_f32_16x16x32_bf16 v[120:123], v[152:155], v[176:179], v[120:123]
	s_waitcnt lgkmcnt(5)
	v_mfma_f32_16x16x32_bf16 v[108:111], v[140:143], v[184:187], v[108:111]
	v_mfma_f32_16x16x32_bf16 v[104:107], v[152:155], v[184:187], v[104:107]
	s_waitcnt lgkmcnt(3)
	v_mfma_f32_16x16x32_bf16 v[92:95], v[140:143], v[212:215], v[92:95]
	v_mfma_f32_16x16x32_bf16 v[88:91], v[152:155], v[212:215], v[88:91]
	s_waitcnt lgkmcnt(1)
	v_mfma_f32_16x16x32_bf16 v[76:79], v[140:143], v[232:235], v[76:79]
	v_mfma_f32_16x16x32_bf16 v[72:75], v[152:155], v[232:235], v[72:75]
	v_mfma_f32_16x16x32_bf16 v[124:127], v[148:151], v[180:183], v[124:127]
	v_mfma_f32_16x16x32_bf16 v[120:123], v[156:159], v[180:183], v[120:123]
	v_mfma_f32_16x16x32_bf16 v[108:111], v[148:151], v[208:211], v[108:111]
	v_mfma_f32_16x16x32_bf16 v[104:107], v[156:159], v[208:211], v[104:107]
	v_mfma_f32_16x16x32_bf16 v[92:95], v[148:151], v[228:231], v[92:95]
	v_mfma_f32_16x16x32_bf16 v[88:91], v[156:159], v[228:231], v[88:91]
	s_waitcnt lgkmcnt(0)
	v_mfma_f32_16x16x32_bf16 v[76:79], v[148:151], v[236:239], v[76:79]
	v_mfma_f32_16x16x32_bf16 v[72:75], v[156:159], v[236:239], v[72:75]
	s_setprio 0
	s_setprio 1
	v_mfma_f32_16x16x32_bf16 v[116:119], v[160:163], v[176:179], v[116:119]
	v_mfma_f32_16x16x32_bf16 v[112:115], v[168:171], v[176:179], v[112:115]
	v_mfma_f32_16x16x32_bf16 v[100:103], v[160:163], v[184:187], v[100:103]
	v_mfma_f32_16x16x32_bf16 v[96:99], v[168:171], v[184:187], v[96:99]
	v_mfma_f32_16x16x32_bf16 v[84:87], v[160:163], v[212:215], v[84:87]
	v_mfma_f32_16x16x32_bf16 v[80:83], v[168:171], v[212:215], v[80:83]
	v_mfma_f32_16x16x32_bf16 v[68:71], v[160:163], v[232:235], v[68:71]
	v_mfma_f32_16x16x32_bf16 v[64:67], v[168:171], v[232:235], v[64:67]
	v_mfma_f32_16x16x32_bf16 v[116:119], v[164:167], v[180:183], v[116:119]
	v_mfma_f32_16x16x32_bf16 v[112:115], v[172:175], v[180:183], v[112:115]
	v_mfma_f32_16x16x32_bf16 v[100:103], v[164:167], v[208:211], v[100:103]
	v_mfma_f32_16x16x32_bf16 v[96:99], v[172:175], v[208:211], v[96:99]
	v_mfma_f32_16x16x32_bf16 v[84:87], v[164:167], v[228:231], v[84:87]
	v_mfma_f32_16x16x32_bf16 v[80:83], v[172:175], v[228:231], v[80:83]
	v_mfma_f32_16x16x32_bf16 v[68:71], v[164:167], v[236:239], v[68:71]
	v_mfma_f32_16x16x32_bf16 v[64:67], v[172:175], v[236:239], v[64:67]
	s_setprio 0
	s_barrier
	s_add_i32 s10, s10, s3
	v_lshl_add_u64 v[144:145], v[144:145], 0, s[48:49]
	s_mov_b32 m0, s10
	ds_read_b128 v[176:179], v147 offset:49152
	ds_read_b128 v[180:183], v147 offset:50176
	ds_read_b128 v[184:187], v147 offset:51200
	ds_read_b128 v[208:211], v147 offset:52224
	ds_read_b128 v[212:215], v147 offset:53248
	ds_read_b128 v[228:231], v147 offset:54272
	ds_read_b128 v[232:235], v147 offset:55296
	ds_read_b128 v[236:239], v147 offset:56320
	global_load_lds_dwordx4 v[144:145], off
	s_add_i32 m0, s10, 0x2000
	s_add_u32 s46, s46, 0x80080
	v_lshl_add_u64 v[144:145], v[240:241], 0, s[48:49]
	s_addc_u32 s47, s47, 0
	s_add_i32 s10, s33, s3
	global_load_lds_dwordx4 v[144:145], off
	v_lshl_add_u64 v[144:145], s[46:47], 0, v[194:195]
	s_mov_b32 m0, s10
	s_nop 0
	global_load_lds_dwordx4 v[144:145], off
	v_lshl_add_u64 v[144:145], s[46:47], 0, v[128:129]
	s_add_i32 m0, s10, 0x2000
	s_nop 0
	global_load_lds_dwordx4 v[144:145], off
	v_lshl_add_u64 v[144:145], v[242:243], 0, s[48:49]
	s_mov_b32 m0, s45
	s_nop 0
	global_load_lds_dwordx4 v[144:145], off
	v_lshl_add_u64 v[144:145], v[244:245], 0, s[48:49]
	s_mov_b32 m0, s60
	s_nop 0
	global_load_lds_dwordx4 v[144:145], off
	s_waitcnt vmcnt(8)
	s_barrier
	s_setprio 1
	s_waitcnt lgkmcnt(7)
	v_mfma_f32_16x16x32_bf16 v[60:63], v[140:143], v[176:179], v[60:63]
	v_mfma_f32_16x16x32_bf16 v[56:59], v[152:155], v[176:179], v[56:59]
	s_waitcnt lgkmcnt(5)
	v_mfma_f32_16x16x32_bf16 v[44:47], v[140:143], v[184:187], v[44:47]
	v_mfma_f32_16x16x32_bf16 v[40:43], v[152:155], v[184:187], v[40:43]
	s_waitcnt lgkmcnt(3)
	v_mfma_f32_16x16x32_bf16 v[28:31], v[140:143], v[212:215], v[28:31]
	v_mfma_f32_16x16x32_bf16 v[24:27], v[152:155], v[212:215], v[24:27]
	s_waitcnt lgkmcnt(1)
	v_mfma_f32_16x16x32_bf16 v[12:15], v[140:143], v[232:235], v[12:15]
	v_mfma_f32_16x16x32_bf16 v[8:11], v[152:155], v[232:235], v[8:11]
	v_mfma_f32_16x16x32_bf16 v[60:63], v[148:151], v[180:183], v[60:63]
	v_mfma_f32_16x16x32_bf16 v[56:59], v[156:159], v[180:183], v[56:59]
	v_mfma_f32_16x16x32_bf16 v[44:47], v[148:151], v[208:211], v[44:47]
	v_mfma_f32_16x16x32_bf16 v[40:43], v[156:159], v[208:211], v[40:43]
	v_mfma_f32_16x16x32_bf16 v[28:31], v[148:151], v[228:231], v[28:31]
	v_mfma_f32_16x16x32_bf16 v[24:27], v[156:159], v[228:231], v[24:27]
	s_waitcnt lgkmcnt(0)
	v_mfma_f32_16x16x32_bf16 v[12:15], v[148:151], v[236:239], v[12:15]
	v_mfma_f32_16x16x32_bf16 v[8:11], v[156:159], v[236:239], v[8:11]
	s_setprio 0
	s_setprio 1
	v_mfma_f32_16x16x32_bf16 v[52:55], v[160:163], v[176:179], v[52:55]
	v_mfma_f32_16x16x32_bf16 v[48:51], v[168:171], v[176:179], v[48:51]
	v_mfma_f32_16x16x32_bf16 v[36:39], v[160:163], v[184:187], v[36:39]
	v_mfma_f32_16x16x32_bf16 v[32:35], v[168:171], v[184:187], v[32:35]
	v_mfma_f32_16x16x32_bf16 v[20:23], v[160:163], v[212:215], v[20:23]
	v_mfma_f32_16x16x32_bf16 v[16:19], v[168:171], v[212:215], v[16:19]
	v_mfma_f32_16x16x32_bf16 v[4:7], v[160:163], v[232:235], v[4:7]
	v_mfma_f32_16x16x32_bf16 v[0:3], v[168:171], v[232:235], v[0:3]
	v_mfma_f32_16x16x32_bf16 v[52:55], v[164:167], v[180:183], v[52:55]
	v_mfma_f32_16x16x32_bf16 v[48:51], v[172:175], v[180:183], v[48:51]
	v_mfma_f32_16x16x32_bf16 v[36:39], v[164:167], v[208:211], v[36:39]
	v_mfma_f32_16x16x32_bf16 v[32:35], v[172:175], v[208:211], v[32:35]
	v_mfma_f32_16x16x32_bf16 v[20:23], v[164:167], v[228:231], v[20:23]
	v_mfma_f32_16x16x32_bf16 v[16:19], v[172:175], v[228:231], v[16:19]
	v_mfma_f32_16x16x32_bf16 v[4:7], v[164:167], v[236:239], v[4:7]
	v_mfma_f32_16x16x32_bf16 v[0:3], v[172:175], v[236:239], v[0:3]
	s_setprio 0
	s_barrier
	s_add_i32 s78, s78, 2
	s_add_u32 s35, s35, 0x100
	s_addc_u32 s73, s73, 0
	s_cmp_gt_u32 s78, 29
	s_mov_b64 s[90:91], s[0:1]
	s_cbranch_scc0 .LBB0_1060
	s_branch .Lgemm4_exit
.LBB0_1060:
	s_add_u32 s0, s90, 0x100
	s_addc_u32 s1, s91, 0
	s_add_i32 s10, 0, 0x10000
	s_cmp_eq_u32 s78, 28
	s_cselect_b32 vcc_hi, s75, s1
	s_cselect_b32 vcc_lo, s74, s0
	v_add_u32_e32 v144, s10, v146
	s_cselect_b32 s47, s9, s73
	s_cselect_b32 s46, s34, s35
	s_add_i32 s33, 0, 0x14000
	ds_read_b128 v[140:143], v144
	ds_read_b128 v[148:151], v144 offset:1024
	ds_read_b128 v[152:155], v144 offset:2048
	ds_read_b128 v[156:159], v144 offset:3072
	v_add_u32_e32 v144, s33, v146
	ds_read_b128 v[160:163], v144
	ds_read_b128 v[164:167], v144 offset:1024
	ds_read_b128 v[168:171], v144 offset:2048
	ds_read_b128 v[172:175], v144 offset:3072
	v_lshl_add_u64 v[144:145], s[90:91], 0, v[136:137]
	s_add_i32 m0, s11, 0xc000
	ds_read_b128 v[176:179], v147
	ds_read_b128 v[180:183], v147 offset:1024
	ds_read_b128 v[184:187], v147 offset:2048
	ds_read_b128 v[208:211], v147 offset:3072
	ds_read_b128 v[212:215], v147 offset:4096
	ds_read_b128 v[228:231], v147 offset:5120
	ds_read_b128 v[232:235], v147 offset:6144
	ds_read_b128 v[236:239], v147 offset:7168
	global_load_lds_dwordx4 v[144:145], off
	v_lshl_add_u64 v[144:145], s[90:91], 0, v[138:139]
	s_add_i32 m0, s11, 0xe000
	s_nop 0
	global_load_lds_dwordx4 v[144:145], off
	s_waitcnt vmcnt(8)
	s_barrier
	s_setprio 1
	s_waitcnt lgkmcnt(7)
	v_mfma_f32_16x16x32_bf16 v[124:127], v[140:143], v[176:179], v[124:127]
	v_mfma_f32_16x16x32_bf16 v[120:123], v[152:155], v[176:179], v[120:123]
	s_waitcnt lgkmcnt(5)
	v_mfma_f32_16x16x32_bf16 v[108:111], v[140:143], v[184:187], v[108:111]
	v_mfma_f32_16x16x32_bf16 v[104:107], v[152:155], v[184:187], v[104:107]
	s_waitcnt lgkmcnt(3)
	v_mfma_f32_16x16x32_bf16 v[92:95], v[140:143], v[212:215], v[92:95]
	v_mfma_f32_16x16x32_bf16 v[88:91], v[152:155], v[212:215], v[88:91]
	s_waitcnt lgkmcnt(1)
	v_mfma_f32_16x16x32_bf16 v[76:79], v[140:143], v[232:235], v[76:79]
	v_mfma_f32_16x16x32_bf16 v[72:75], v[152:155], v[232:235], v[72:75]
	v_mfma_f32_16x16x32_bf16 v[124:127], v[148:151], v[180:183], v[124:127]
	v_mfma_f32_16x16x32_bf16 v[120:123], v[156:159], v[180:183], v[120:123]
	v_mfma_f32_16x16x32_bf16 v[108:111], v[148:151], v[208:211], v[108:111]
	v_mfma_f32_16x16x32_bf16 v[104:107], v[156:159], v[208:211], v[104:107]
	v_mfma_f32_16x16x32_bf16 v[92:95], v[148:151], v[228:231], v[92:95]
	v_mfma_f32_16x16x32_bf16 v[88:91], v[156:159], v[228:231], v[88:91]
	s_waitcnt lgkmcnt(0)
	v_mfma_f32_16x16x32_bf16 v[76:79], v[148:151], v[236:239], v[76:79]
	v_mfma_f32_16x16x32_bf16 v[72:75], v[156:159], v[236:239], v[72:75]
	s_setprio 0
	s_setprio 1
	v_mfma_f32_16x16x32_bf16 v[116:119], v[160:163], v[176:179], v[116:119]
	v_mfma_f32_16x16x32_bf16 v[112:115], v[168:171], v[176:179], v[112:115]
	v_mfma_f32_16x16x32_bf16 v[100:103], v[160:163], v[184:187], v[100:103]
	v_mfma_f32_16x16x32_bf16 v[96:99], v[168:171], v[184:187], v[96:99]
	v_mfma_f32_16x16x32_bf16 v[84:87], v[160:163], v[212:215], v[84:87]
	v_mfma_f32_16x16x32_bf16 v[80:83], v[168:171], v[212:215], v[80:83]
	v_mfma_f32_16x16x32_bf16 v[68:71], v[160:163], v[232:235], v[68:71]
	v_mfma_f32_16x16x32_bf16 v[64:67], v[168:171], v[232:235], v[64:67]
	v_mfma_f32_16x16x32_bf16 v[116:119], v[164:167], v[180:183], v[116:119]
	v_mfma_f32_16x16x32_bf16 v[112:115], v[172:175], v[180:183], v[112:115]
	v_mfma_f32_16x16x32_bf16 v[100:103], v[164:167], v[208:211], v[100:103]
	v_mfma_f32_16x16x32_bf16 v[96:99], v[172:175], v[208:211], v[96:99]
	v_mfma_f32_16x16x32_bf16 v[84:87], v[164:167], v[228:231], v[84:87]
	v_mfma_f32_16x16x32_bf16 v[80:83], v[172:175], v[228:231], v[80:83]
	v_mfma_f32_16x16x32_bf16 v[68:71], v[164:167], v[236:239], v[68:71]
	v_mfma_f32_16x16x32_bf16 v[64:67], v[172:175], v[236:239], v[64:67]
	s_setprio 0
	s_barrier
	s_add_i32 s10, s10, s3
	v_lshl_add_u64 v[144:145], s[46:47], 0, v[194:195]
	s_mov_b32 m0, s10
	ds_read_b128 v[176:179], v147 offset:16384
	ds_read_b128 v[180:183], v147 offset:17408
	ds_read_b128 v[184:187], v147 offset:18432
	ds_read_b128 v[208:211], v147 offset:19456
	ds_read_b128 v[212:215], v147 offset:20480
	ds_read_b128 v[228:231], v147 offset:21504
	ds_read_b128 v[232:235], v147 offset:22528
	ds_read_b128 v[236:239], v147 offset:23552
	global_load_lds_dwordx4 v[144:145], off
	s_add_i32 m0, s10, 0x2000
	s_add_u32 s90, s46, 0x80000
	v_lshl_add_u64 v[240:241], s[46:47], 0, v[128:129]
	s_addc_u32 s91, s47, 0
	s_add_i32 s10, s33, s3
	global_load_lds_dwordx4 v[240:241], off
	v_lshl_add_u64 v[242:243], s[90:91], 0, v[194:195]
	s_mov_b32 m0, s10
	v_lshl_add_u64 v[244:245], vcc, 0, v[130:131]
	global_load_lds_dwordx4 v[242:243], off
	v_lshl_add_u64 v[242:243], s[90:91], 0, v[128:129]
	s_add_i32 m0, s10, 0x2000
	s_nop 0
	global_load_lds_dwordx4 v[242:243], off
	v_lshl_add_u64 v[242:243], vcc, 0, v[132:133]
	s_mov_b32 m0, s11
	s_nop 0
	global_load_lds_dwordx4 v[242:243], off
	s_mov_b32 m0, s12
	s_nop 0
	global_load_lds_dwordx4 v[244:245], off
	s_waitcnt vmcnt(8)
	s_barrier
	s_setprio 1
	s_waitcnt lgkmcnt(7)
	v_mfma_f32_16x16x32_bf16 v[60:63], v[140:143], v[176:179], v[60:63]
	v_mfma_f32_16x16x32_bf16 v[56:59], v[152:155], v[176:179], v[56:59]
	s_waitcnt lgkmcnt(5)
	v_mfma_f32_16x16x32_bf16 v[44:47], v[140:143], v[184:187], v[44:47]
	v_mfma_f32_16x16x32_bf16 v[40:43], v[152:155], v[184:187], v[40:43]
	s_waitcnt lgkmcnt(3)
	v_mfma_f32_16x16x32_bf16 v[28:31], v[140:143], v[212:215], v[28:31]
	v_mfma_f32_16x16x32_bf16 v[24:27], v[152:155], v[212:215], v[24:27]
	s_waitcnt lgkmcnt(1)
	v_mfma_f32_16x16x32_bf16 v[12:15], v[140:143], v[232:235], v[12:15]
	v_mfma_f32_16x16x32_bf16 v[8:11], v[152:155], v[232:235], v[8:11]
	v_mfma_f32_16x16x32_bf16 v[60:63], v[148:151], v[180:183], v[60:63]
	v_mfma_f32_16x16x32_bf16 v[56:59], v[156:159], v[180:183], v[56:59]
	v_mfma_f32_16x16x32_bf16 v[44:47], v[148:151], v[208:211], v[44:47]
	v_mfma_f32_16x16x32_bf16 v[40:43], v[156:159], v[208:211], v[40:43]
	v_mfma_f32_16x16x32_bf16 v[28:31], v[148:151], v[228:231], v[28:31]
	v_mfma_f32_16x16x32_bf16 v[24:27], v[156:159], v[228:231], v[24:27]
	s_waitcnt lgkmcnt(0)
	v_mfma_f32_16x16x32_bf16 v[12:15], v[148:151], v[236:239], v[12:15]
	v_mfma_f32_16x16x32_bf16 v[8:11], v[156:159], v[236:239], v[8:11]
	s_setprio 0
	s_setprio 1
	v_mfma_f32_16x16x32_bf16 v[52:55], v[160:163], v[176:179], v[52:55]
	v_mfma_f32_16x16x32_bf16 v[48:51], v[168:171], v[176:179], v[48:51]
	v_mfma_f32_16x16x32_bf16 v[36:39], v[160:163], v[184:187], v[36:39]
	v_mfma_f32_16x16x32_bf16 v[32:35], v[168:171], v[184:187], v[32:35]
	v_mfma_f32_16x16x32_bf16 v[20:23], v[160:163], v[212:215], v[20:23]
	v_mfma_f32_16x16x32_bf16 v[16:19], v[168:171], v[212:215], v[16:19]
	v_mfma_f32_16x16x32_bf16 v[4:7], v[160:163], v[232:235], v[4:7]
	v_mfma_f32_16x16x32_bf16 v[0:3], v[168:171], v[232:235], v[0:3]
	v_mfma_f32_16x16x32_bf16 v[52:55], v[164:167], v[180:183], v[52:55]
	v_mfma_f32_16x16x32_bf16 v[48:51], v[172:175], v[180:183], v[48:51]
	v_mfma_f32_16x16x32_bf16 v[36:39], v[164:167], v[208:211], v[36:39]
	v_mfma_f32_16x16x32_bf16 v[32:35], v[172:175], v[208:211], v[32:35]
	v_mfma_f32_16x16x32_bf16 v[20:23], v[164:167], v[228:231], v[20:23]
	v_mfma_f32_16x16x32_bf16 v[16:19], v[172:175], v[228:231], v[16:19]
	v_mfma_f32_16x16x32_bf16 v[4:7], v[164:167], v[236:239], v[4:7]
	v_mfma_f32_16x16x32_bf16 v[0:3], v[172:175], v[236:239], v[0:3]
	s_setprio 0
	s_barrier
	s_add_i32 s10, 0, 0x18000
	s_add_i32 s33, 0, 0x1c000
	v_add_u32_e32 v156, s10, v146
	v_add_u32_e32 v172, s33, v146
	ds_read_b128 v[140:143], v156
	ds_read_b128 v[148:151], v156 offset:1024
	ds_read_b128 v[152:155], v156 offset:2048
	ds_read_b128 v[156:159], v156 offset:3072
	ds_read_b128 v[160:163], v172
	ds_read_b128 v[164:167], v172 offset:1024
	ds_read_b128 v[168:171], v172 offset:2048
	ds_read_b128 v[172:175], v172 offset:3072
	s_add_u32 s90, vcc_lo, 0x160000
	s_addc_u32 s91, vcc_hi, 0
	s_mov_b32 m0, s16
	v_lshl_add_u64 v[246:247], s[90:91], 0, v[132:133]
	ds_read_b128 v[176:179], v147 offset:32768
	ds_read_b128 v[180:183], v147 offset:33792
	ds_read_b128 v[184:187], v147 offset:34816
	ds_read_b128 v[208:211], v147 offset:35840
	ds_read_b128 v[212:215], v147 offset:36864
	ds_read_b128 v[228:231], v147 offset:37888
	ds_read_b128 v[232:235], v147 offset:38912
	ds_read_b128 v[236:239], v147 offset:39936
	global_load_lds_dwordx4 v[246:247], off
	v_lshl_add_u64 v[246:247], s[90:91], 0, v[130:131]
	s_mov_b32 m0, s17
	s_nop 0
	global_load_lds_dwordx4 v[246:247], off
	s_waitcnt vmcnt(8)
	s_barrier
	s_setprio 1
	s_waitcnt lgkmcnt(7)
	v_mfma_f32_16x16x32_bf16 v[124:127], v[140:143], v[176:179], v[124:127]
	v_mfma_f32_16x16x32_bf16 v[120:123], v[152:155], v[176:179], v[120:123]
	s_waitcnt lgkmcnt(5)
	v_mfma_f32_16x16x32_bf16 v[108:111], v[140:143], v[184:187], v[108:111]
	v_mfma_f32_16x16x32_bf16 v[104:107], v[152:155], v[184:187], v[104:107]
	s_waitcnt lgkmcnt(3)
	v_mfma_f32_16x16x32_bf16 v[92:95], v[140:143], v[212:215], v[92:95]
	v_mfma_f32_16x16x32_bf16 v[88:91], v[152:155], v[212:215], v[88:91]
	s_waitcnt lgkmcnt(1)
	v_mfma_f32_16x16x32_bf16 v[76:79], v[140:143], v[232:235], v[76:79]
	v_mfma_f32_16x16x32_bf16 v[72:75], v[152:155], v[232:235], v[72:75]
	v_mfma_f32_16x16x32_bf16 v[124:127], v[148:151], v[180:183], v[124:127]
	v_mfma_f32_16x16x32_bf16 v[120:123], v[156:159], v[180:183], v[120:123]
	v_mfma_f32_16x16x32_bf16 v[108:111], v[148:151], v[208:211], v[108:111]
	v_mfma_f32_16x16x32_bf16 v[104:107], v[156:159], v[208:211], v[104:107]
	v_mfma_f32_16x16x32_bf16 v[92:95], v[148:151], v[228:231], v[92:95]
	v_mfma_f32_16x16x32_bf16 v[88:91], v[156:159], v[228:231], v[88:91]
	s_waitcnt lgkmcnt(0)
	v_mfma_f32_16x16x32_bf16 v[76:79], v[148:151], v[236:239], v[76:79]
	v_mfma_f32_16x16x32_bf16 v[72:75], v[156:159], v[236:239], v[72:75]
	s_setprio 0
	s_setprio 1
	v_mfma_f32_16x16x32_bf16 v[116:119], v[160:163], v[176:179], v[116:119]
	v_mfma_f32_16x16x32_bf16 v[112:115], v[168:171], v[176:179], v[112:115]
	v_mfma_f32_16x16x32_bf16 v[100:103], v[160:163], v[184:187], v[100:103]
	v_mfma_f32_16x16x32_bf16 v[96:99], v[168:171], v[184:187], v[96:99]
	v_mfma_f32_16x16x32_bf16 v[84:87], v[160:163], v[212:215], v[84:87]
	v_mfma_f32_16x16x32_bf16 v[80:83], v[168:171], v[212:215], v[80:83]
	v_mfma_f32_16x16x32_bf16 v[68:71], v[160:163], v[232:235], v[68:71]
	v_mfma_f32_16x16x32_bf16 v[64:67], v[168:171], v[232:235], v[64:67]
	v_mfma_f32_16x16x32_bf16 v[116:119], v[164:167], v[180:183], v[116:119]
	v_mfma_f32_16x16x32_bf16 v[112:115], v[172:175], v[180:183], v[112:115]
	v_mfma_f32_16x16x32_bf16 v[100:103], v[164:167], v[208:211], v[100:103]
	v_mfma_f32_16x16x32_bf16 v[96:99], v[172:175], v[208:211], v[96:99]
	v_mfma_f32_16x16x32_bf16 v[84:87], v[164:167], v[228:231], v[84:87]
	v_mfma_f32_16x16x32_bf16 v[80:83], v[172:175], v[228:231], v[80:83]
	v_mfma_f32_16x16x32_bf16 v[68:71], v[164:167], v[236:239], v[68:71]
	v_mfma_f32_16x16x32_bf16 v[64:67], v[172:175], v[236:239], v[64:67]
	s_setprio 0
	s_barrier
	s_add_i32 s10, s10, s3
	v_lshl_add_u64 v[144:145], v[144:145], 0, s[48:49]
	s_mov_b32 m0, s10
	ds_read_b128 v[176:179], v147 offset:49152
	ds_read_b128 v[180:183], v147 offset:50176
	ds_read_b128 v[184:187], v147 offset:51200
	ds_read_b128 v[208:211], v147 offset:52224
	ds_read_b128 v[212:215], v147 offset:53248
	ds_read_b128 v[228:231], v147 offset:54272
	ds_read_b128 v[232:235], v147 offset:55296
	ds_read_b128 v[236:239], v147 offset:56320
	global_load_lds_dwordx4 v[144:145], off
	s_add_i32 m0, s10, 0x2000
	s_add_u32 s46, s46, 0x80080
	v_lshl_add_u64 v[144:145], v[240:241], 0, s[48:49]
	s_addc_u32 s47, s47, 0
	s_add_i32 s10, s33, s3
	global_load_lds_dwordx4 v[144:145], off
	v_lshl_add_u64 v[144:145], s[46:47], 0, v[194:195]
	s_mov_b32 m0, s10
	s_nop 0
	global_load_lds_dwordx4 v[144:145], off
	v_lshl_add_u64 v[144:145], s[46:47], 0, v[128:129]
	s_add_i32 m0, s10, 0x2000
	s_nop 0
	global_load_lds_dwordx4 v[144:145], off
	v_lshl_add_u64 v[144:145], v[242:243], 0, s[48:49]
	s_mov_b32 m0, s45
	s_nop 0
	global_load_lds_dwordx4 v[144:145], off
	v_lshl_add_u64 v[144:145], v[244:245], 0, s[48:49]
	s_mov_b32 m0, s60
	s_nop 0
	global_load_lds_dwordx4 v[144:145], off
	s_waitcnt vmcnt(8)
	s_barrier
	s_setprio 1
	s_waitcnt lgkmcnt(7)
	v_mfma_f32_16x16x32_bf16 v[60:63], v[140:143], v[176:179], v[60:63]
	v_mfma_f32_16x16x32_bf16 v[56:59], v[152:155], v[176:179], v[56:59]
	s_waitcnt lgkmcnt(5)
	v_mfma_f32_16x16x32_bf16 v[44:47], v[140:143], v[184:187], v[44:47]
	v_mfma_f32_16x16x32_bf16 v[40:43], v[152:155], v[184:187], v[40:43]
	s_waitcnt lgkmcnt(3)
	v_mfma_f32_16x16x32_bf16 v[28:31], v[140:143], v[212:215], v[28:31]
	v_mfma_f32_16x16x32_bf16 v[24:27], v[152:155], v[212:215], v[24:27]
	s_waitcnt lgkmcnt(1)
	v_mfma_f32_16x16x32_bf16 v[12:15], v[140:143], v[232:235], v[12:15]
	v_mfma_f32_16x16x32_bf16 v[8:11], v[152:155], v[232:235], v[8:11]
	v_mfma_f32_16x16x32_bf16 v[60:63], v[148:151], v[180:183], v[60:63]
	v_mfma_f32_16x16x32_bf16 v[56:59], v[156:159], v[180:183], v[56:59]
	v_mfma_f32_16x16x32_bf16 v[44:47], v[148:151], v[208:211], v[44:47]
	v_mfma_f32_16x16x32_bf16 v[40:43], v[156:159], v[208:211], v[40:43]
	v_mfma_f32_16x16x32_bf16 v[28:31], v[148:151], v[228:231], v[28:31]
	v_mfma_f32_16x16x32_bf16 v[24:27], v[156:159], v[228:231], v[24:27]
	s_waitcnt lgkmcnt(0)
	v_mfma_f32_16x16x32_bf16 v[12:15], v[148:151], v[236:239], v[12:15]
	v_mfma_f32_16x16x32_bf16 v[8:11], v[156:159], v[236:239], v[8:11]
	s_setprio 0
	s_setprio 1
	v_mfma_f32_16x16x32_bf16 v[52:55], v[160:163], v[176:179], v[52:55]
	v_mfma_f32_16x16x32_bf16 v[48:51], v[168:171], v[176:179], v[48:51]
	v_mfma_f32_16x16x32_bf16 v[36:39], v[160:163], v[184:187], v[36:39]
	v_mfma_f32_16x16x32_bf16 v[32:35], v[168:171], v[184:187], v[32:35]
	v_mfma_f32_16x16x32_bf16 v[20:23], v[160:163], v[212:215], v[20:23]
	v_mfma_f32_16x16x32_bf16 v[16:19], v[168:171], v[212:215], v[16:19]
	v_mfma_f32_16x16x32_bf16 v[4:7], v[160:163], v[232:235], v[4:7]
	v_mfma_f32_16x16x32_bf16 v[0:3], v[168:171], v[232:235], v[0:3]
	v_mfma_f32_16x16x32_bf16 v[52:55], v[164:167], v[180:183], v[52:55]
	v_mfma_f32_16x16x32_bf16 v[48:51], v[172:175], v[180:183], v[48:51]
	v_mfma_f32_16x16x32_bf16 v[36:39], v[164:167], v[208:211], v[36:39]
	v_mfma_f32_16x16x32_bf16 v[32:35], v[172:175], v[208:211], v[32:35]
	v_mfma_f32_16x16x32_bf16 v[20:23], v[164:167], v[228:231], v[20:23]
	v_mfma_f32_16x16x32_bf16 v[16:19], v[172:175], v[228:231], v[16:19]
	v_mfma_f32_16x16x32_bf16 v[4:7], v[164:167], v[236:239], v[4:7]
	v_mfma_f32_16x16x32_bf16 v[0:3], v[172:175], v[236:239], v[0:3]
	s_setprio 0
	s_barrier
	s_add_i32 s78, s78, 2
	s_add_u32 s35, s35, 0x100
	s_addc_u32 s73, s73, 0
	s_cmp_gt_u32 s78, 29
	s_mov_b64 s[90:91], s[0:1]
	s_cbranch_scc0 .LBB0_1060
